# chainzz2 + sc1 on the in-loop LDS-DMA tile loads (bypass per-CU L1, lines are used once per CU)
# baseline (speedup 1.0000x reference)
; #define PG8_STAGE(bufoff, gbase, voff) do { _Pragma("unroll") for (int _i = 0; _i < 2; ++_i) \
;         __builtin_amdgcn_global_load_lds((const unsigned*)((const char*)(gbase) + (voff)[_i]), (LAS unsigned*)(lds + (bufoff) + ldsw + _i * 8192), 16, 0, 0); } while (0)
; #define PG8_LDA(dst, b, h) do { _Pragma("unroll") for (int m = 0; m < 4; ++m) _Pragma("unroll") for (int k = 0; k < 2; ++k) dst[m][k] = *(const LAS bf16x8*)(lds + PG8_SA(b, h) + aoffk[k] + m * 2048); } while (0)
; #define PG8_LDB(dst, b, h) do { _Pragma("unroll") for (int n = 0; n < 2; ++n) _Pragma("unroll") for (int k = 0; k < 2; ++k) dst[n][k] = *(const LAS bf16x8*)(lds + PG8_SB(b, h) + boffk[k] + n * 2048); } while (0)
; #define PG8_WAIT_V(n) asm volatile("s_waitcnt vmcnt(" #n ")" ::: "memory")
; #define PG8_WAIT_L(n) asm volatile("s_waitcnt lgkmcnt(" #n ")" ::: "memory")
; #define PG8_BAR __builtin_amdgcn_s_barrier()
; #define PG8_SCHED __builtin_amdgcn_sched_barrier(0)
; template <class Epi, class Sched, class GemmT>
; __device__ __forceinline__ void gemm_phase(LAS unsigned char* lds, const GemmT& g, const Sched& S, const Epi& E, const int wid) {
;     ...
;             for (int t = 0; t < nt; t += 2) {
;                 const bool last = (t == nt - 2);
;                 const char* a1 = cA + (size_t)(t + 1) * kstep;
;                 const char* a2 = last ? ns.A : cA + (size_t)(t + 2) * kstep; const char* b2 = last ? ns.B : cB + (size_t)(t + 2) * kstep;
;                 const char* a3 = a2 + kstep; const char* b3 = b2 + kstep;
;                 unsigned vA2[2], vB2[2];
; #pragma unroll
;                 for (int i = 0; i < 2; ++i) { vA2[i] = last ? nvA[i] : voffA[i]; vB2[i] = last ? nvB[i] : voffB[i]; }
;                 const size_t hA2 = last ? nhA : hstepA, hB2 = last ? nhB : hstepB;
;                 PG8_LDB(B0, 0, 0); PG8_LDB(B1, 0, 1); PG8_SCHED; PG8_LDA(At, 0, 0); PG8_STAGE(PG8_SA(1, 1), a1 + hstepA, voffA);
;                 PG8_WAIT_V(8); PG8_WAIT_L(0); PG8_BAR; PG8_MMA(0, 0, At, B0); PG8_MMA(0, 1, At, B1); PG8_BAR; PG8_SCHED;
;                 PG8_LDA(At, 0, 1); PG8_STAGE(PG8_SB(0, 0), b2, vB2); PG8_STAGE(PG8_SB(0, 1), b2 + hB2, vB2); PG8_STAGE(PG8_SA(0, 0), a2, vA2);
;                 PG8_WAIT_V(8); PG8_WAIT_L(0); PG8_BAR; PG8_MMA(1, 0, At, B0); PG8_MMA(1, 1, At, B1); PG8_BAR; PG8_SCHED;
.LBB0_361:
	ds_read_b128 v[24:27], v186
	ds_read_b128 v[28:31], v187
	ds_read_b128 v[16:19], v188
	ds_read_b128 v[20:23], v189
	ds_read_b128 v[8:11], v190
	ds_read_b128 v[12:15], v191
	ds_read_b128 v[0:3], v192
	ds_read_b128 v[4:7], v193
	s_add_u32 s41, s56, 0xfff80080
	s_addc_u32 s48, s57, -1
	s_cmp_eq_u32 s40, 28
	s_cselect_b32 s83, s43, s48
	s_cselect_b32 s82, s42, s41
	s_cselect_b32 s59, s37, s39
	s_cselect_b32 s58, s36, s38
	v_lshl_add_u64 v[230:231], s[56:57], 0, v[160:161]
	s_add_i32 m0, s12, 0xc000
	ds_read_b128 v[174:177], v194
	ds_read_b128 v[204:207], v194 offset:2048
	ds_read_b128 v[178:181], v195
	ds_read_b128 v[208:211], v195 offset:2048
	ds_read_b128 v[212:215], v194 offset:4096
	ds_read_b128 v[220:223], v194 offset:6144
	ds_read_b128 v[216:219], v195 offset:4096
	ds_read_b128 v[224:227], v195 offset:6144
	global_load_lds_dwordx4 v[230:231], off sc1
	v_lshl_add_u64 v[230:231], s[56:57], 0, v[164:165]
	s_add_i32 m0, s12, 0xe000
	s_nop 0
	global_load_lds_dwordx4 v[230:231], off sc1
	s_waitcnt vmcnt(8)
	s_waitcnt lgkmcnt(0)
	s_barrier
	s_setprio 3
	s_waitcnt lgkmcnt(0)
	v_mfma_scale_f32_16x16x128_f8f6f4 v[156:159], v[24:31], v[174:181], v[156:159], v196, v196 op_sel_hi:[0,0,0]
	v_mfma_scale_f32_16x16x128_f8f6f4 v[152:155], v[16:23], v[174:181], v[152:155], v196, v196 op_sel_hi:[0,0,0]
	v_mfma_scale_f32_16x16x128_f8f6f4 v[136:139], v[16:23], v[204:211], v[136:139], v196, v196 op_sel_hi:[0,0,0]
	v_mfma_scale_f32_16x16x128_f8f6f4 v[140:143], v[24:31], v[204:211], v[140:143], v196, v196 op_sel_hi:[0,0,0]
	v_mfma_scale_f32_16x16x128_f8f6f4 v[124:127], v[24:31], v[212:219], v[124:127], v196, v196 op_sel_hi:[0,0,0]
	v_mfma_scale_f32_16x16x128_f8f6f4 v[120:123], v[16:23], v[212:219], v[120:123], v196, v196 op_sel_hi:[0,0,0]
	v_mfma_scale_f32_16x16x128_f8f6f4 v[104:107], v[16:23], v[220:227], v[104:107], v196, v196 op_sel_hi:[0,0,0]
	v_mfma_scale_f32_16x16x128_f8f6f4 v[108:111], v[24:31], v[220:227], v[108:111], v196, v196 op_sel_hi:[0,0,0]
	s_setprio 0
	s_setprio 3
	v_mfma_scale_f32_16x16x128_f8f6f4 v[148:151], v[8:15], v[174:181], v[148:151], v196, v196 op_sel_hi:[0,0,0]
	v_mfma_scale_f32_16x16x128_f8f6f4 v[144:147], v[0:7], v[174:181], v[144:147], v196, v196 op_sel_hi:[0,0,0]
	v_mfma_scale_f32_16x16x128_f8f6f4 v[128:131], v[0:7], v[204:211], v[128:131], v196, v196 op_sel_hi:[0,0,0]
	v_mfma_scale_f32_16x16x128_f8f6f4 v[132:135], v[8:15], v[204:211], v[132:135], v196, v196 op_sel_hi:[0,0,0]
	v_mfma_scale_f32_16x16x128_f8f6f4 v[116:119], v[8:15], v[212:219], v[116:119], v196, v196 op_sel_hi:[0,0,0]
	v_mfma_scale_f32_16x16x128_f8f6f4 v[112:115], v[0:7], v[212:219], v[112:115], v196, v196 op_sel_hi:[0,0,0]
	v_mfma_scale_f32_16x16x128_f8f6f4 v[96:99], v[0:7], v[220:227], v[96:99], v196, v196 op_sel_hi:[0,0,0]
	v_mfma_scale_f32_16x16x128_f8f6f4 v[100:103], v[8:15], v[220:227], v[100:103], v196, v196 op_sel_hi:[0,0,0]
	s_setprio 0
	s_barrier
	s_add_i32 s41, s64, s68
	v_lshl_add_u64 v[174:175], s[58:59], 0, v[162:163]
	s_mov_b32 m0, s41
	ds_read_b128 v[204:207], v194 offset:16384
	ds_read_b128 v[212:215], v194 offset:18432
	ds_read_b128 v[208:211], v195 offset:16384
	ds_read_b128 v[216:219], v195 offset:18432
	ds_read_b128 v[220:223], v194 offset:20480
	ds_read_b128 v[230:233], v194 offset:22528
	ds_read_b128 v[224:227], v195 offset:20480
	ds_read_b128 v[234:237], v195 offset:22528
	global_load_lds_dwordx4 v[174:175], off sc1
	s_add_i32 m0, s41, 0x2000
	s_add_u32 s50, s58, 0x80000
	v_lshl_add_u64 v[176:177], s[58:59], 0, v[166:167]
	s_addc_u32 s51, s59, 0
	s_add_i32 s41, s65, s68
	global_load_lds_dwordx4 v[176:177], off sc1
	v_lshl_add_u64 v[178:179], s[50:51], 0, v[162:163]
	s_mov_b32 m0, s41
	v_lshl_add_u64 v[180:181], s[82:83], 0, v[164:165]
	global_load_lds_dwordx4 v[178:179], off sc1
	v_lshl_add_u64 v[178:179], s[50:51], 0, v[166:167]
	s_add_i32 m0, s41, 0x2000
	s_nop 0
	global_load_lds_dwordx4 v[178:179], off sc1
	v_lshl_add_u64 v[178:179], s[82:83], 0, v[160:161]
	s_mov_b32 m0, s12
	s_nop 0
	global_load_lds_dwordx4 v[178:179], off sc1
	s_mov_b32 m0, s13
	s_nop 0
	global_load_lds_dwordx4 v[180:181], off sc1
	s_waitcnt vmcnt(8)
	s_waitcnt lgkmcnt(0)
	s_barrier
	s_setprio 3
	s_waitcnt lgkmcnt(0)
	v_mfma_scale_f32_16x16x128_f8f6f4 v[84:87], v[24:31], v[204:211], v[84:87], v196, v196 op_sel_hi:[0,0,0]
	v_mfma_scale_f32_16x16x128_f8f6f4 v[80:83], v[16:23], v[204:211], v[80:83], v196, v196 op_sel_hi:[0,0,0]
	v_mfma_scale_f32_16x16x128_f8f6f4 v[64:67], v[16:23], v[212:219], v[64:67], v196, v196 op_sel_hi:[0,0,0]
	v_mfma_scale_f32_16x16x128_f8f6f4 v[68:71], v[24:31], v[212:219], v[68:71], v196, v196 op_sel_hi:[0,0,0]
	v_mfma_scale_f32_16x16x128_f8f6f4 v[52:55], v[24:31], v[220:227], v[52:55], v196, v196 op_sel_hi:[0,0,0]
	v_mfma_scale_f32_16x16x128_f8f6f4 v[48:51], v[16:23], v[220:227], v[48:51], v196, v196 op_sel_hi:[0,0,0]
	v_mfma_scale_f32_16x16x128_f8f6f4 v[32:35], v[16:23], v[230:237], v[32:35], v196, v196 op_sel_hi:[0,0,0]
	v_mfma_scale_f32_16x16x128_f8f6f4 v[36:39], v[24:31], v[230:237], v[36:39], v196, v196 op_sel_hi:[0,0,0]
	s_setprio 0
	s_setprio 3
	v_mfma_scale_f32_16x16x128_f8f6f4 v[92:95], v[8:15], v[204:211], v[92:95], v196, v196 op_sel_hi:[0,0,0]
	v_mfma_scale_f32_16x16x128_f8f6f4 v[88:91], v[0:7], v[204:211], v[88:91], v196, v196 op_sel_hi:[0,0,0]
	v_mfma_scale_f32_16x16x128_f8f6f4 v[72:75], v[0:7], v[212:219], v[72:75], v196, v196 op_sel_hi:[0,0,0]
	v_mfma_scale_f32_16x16x128_f8f6f4 v[76:79], v[8:15], v[212:219], v[76:79], v196, v196 op_sel_hi:[0,0,0]
	v_mfma_scale_f32_16x16x128_f8f6f4 v[60:63], v[8:15], v[220:227], v[60:63], v196, v196 op_sel_hi:[0,0,0]
	v_mfma_scale_f32_16x16x128_f8f6f4 v[56:59], v[0:7], v[220:227], v[56:59], v196, v196 op_sel_hi:[0,0,0]
	v_mfma_scale_f32_16x16x128_f8f6f4 v[40:43], v[0:7], v[230:237], v[40:43], v196, v196 op_sel_hi:[0,0,0]
	v_mfma_scale_f32_16x16x128_f8f6f4 v[44:47], v[8:15], v[230:237], v[44:47], v196, v196 op_sel_hi:[0,0,0]
	s_setprio 0
	s_barrier
; #define PG8_STAGE(bufoff, gbase, voff) do { _Pragma("unroll") for (int _i = 0; _i < 2; ++_i) \
;         __builtin_amdgcn_global_load_lds((const unsigned*)((const char*)(gbase) + (voff)[_i]), (LAS unsigned*)(lds + (bufoff) + ldsw + _i * 8192), 16, 0, 0); } while (0)
; #define PG8_LDA(dst, b, h) do { _Pragma("unroll") for (int m = 0; m < 4; ++m) _Pragma("unroll") for (int k = 0; k < 2; ++k) dst[m][k] = *(const LAS bf16x8*)(lds + PG8_SA(b, h) + aoffk[k] + m * 2048); } while (0)
; #define PG8_LDB(dst, b, h) do { _Pragma("unroll") for (int n = 0; n < 2; ++n) _Pragma("unroll") for (int k = 0; k < 2; ++k) dst[n][k] = *(const LAS bf16x8*)(lds + PG8_SB(b, h) + boffk[k] + n * 2048); } while (0)
; #define PG8_WAIT_V(n) asm volatile("s_waitcnt vmcnt(" #n ")" ::: "memory")
; #define PG8_BAR __builtin_amdgcn_s_barrier()
; template <class Epi, class Sched, class GemmT>
; __device__ __forceinline__ void gemm_phase(LAS unsigned char* lds, const GemmT& g, const Sched& S, const Epi& E, const int wid) {
;     ...
;                 PG8_LDB(B0, 0, 0); PG8_LDB(B1, 0, 1); PG8_SCHED; PG8_LDA(At, 0, 0); PG8_STAGE(PG8_SA(1, 1), a1 + hstepA, voffA);
;                 PG8_WAIT_V(8); PG8_WAIT_L(0); PG8_BAR; PG8_MMA(0, 0, At, B0); PG8_MMA(0, 1, At, B1); PG8_BAR; PG8_SCHED;
;                 PG8_LDA(At, 0, 1); PG8_STAGE(PG8_SB(0, 0), b2, vB2); PG8_STAGE(PG8_SB(0, 1), b2 + hB2, vB2); PG8_STAGE(PG8_SA(0, 0), a2, vA2);
;                 PG8_WAIT_V(8); PG8_WAIT_L(0); PG8_BAR; PG8_MMA(1, 0, At, B0); PG8_MMA(1, 1, At, B1); PG8_BAR; PG8_SCHED;
;                 PG8_LDB(B0, 1, 0); PG8_LDB(B1, 1, 1); PG8_SCHED; PG8_LDA(At, 1, 0); PG8_STAGE(PG8_SA(0, 1), a2 + hA2, vA2);
;                 PG8_WAIT_V(8); PG8_WAIT_L(0); PG8_BAR; PG8_MMA(0, 0, At, B0); PG8_MMA(0, 1, At, B1); PG8_BAR; PG8_SCHED;
;                 PG8_LDA(At, 1, 1); PG8_STAGE(PG8_SB(1, 0), b3, vB2); PG8_STAGE(PG8_SB(1, 1), b3 + hB2, vB2); PG8_STAGE(PG8_SA(1, 0), a3, vA2);
;                 PG8_WAIT_V(8); PG8_WAIT_L(0); PG8_BAR; PG8_MMA(1, 0, At, B0); PG8_MMA(1, 1, At, B1); PG8_BAR; PG8_SCHED;
;             }
;             if constexpr (NSEG > 1) { if (sgi + 1 < NSEG) E.mid(acc, cur, sgi, wr, wc, fr, fq); }
;             cs = ns; cA = ns.A; cB = ns.B; hstepA = nhA; hstepB = nhB;
; #pragma unroll
;             for (int i = 0; i < 2; ++i) { voffA[i] = nvA[i]; voffB[i] = nvB[i]; }
;         }
;         if (wr == 0) PG8_BAR;
	s_add_i32 s41, 0, 0x18000
	s_add_i32 s48, 0, 0x1c000
	v_add_u32_e32 v0, s41, v184
	v_add_u32_e32 v4, s41, v185
	v_add_u32_e32 v16, s48, v184
	v_add_u32_e32 v20, s48, v185
	ds_read_b128 v[0:3], v0
	ds_read_b128 v[4:7], v4
	ds_read_b128 v[8:11], v197
	ds_read_b128 v[12:15], v198
	ds_read_b128 v[16:19], v16
	ds_read_b128 v[20:23], v20
	ds_read_b128 v[24:27], v199
	ds_read_b128 v[28:31], v200
	s_add_u32 s50, s82, 0x80000
	s_addc_u32 s51, s83, 0
	s_mov_b32 m0, s15
	v_lshl_add_u64 v[238:239], s[50:51], 0, v[160:161]
	ds_read_b128 v[204:207], v194 offset:32768
	ds_read_b128 v[212:215], v194 offset:34816
	ds_read_b128 v[208:211], v195 offset:32768
	ds_read_b128 v[216:219], v195 offset:34816
	ds_read_b128 v[220:223], v194 offset:36864
	ds_read_b128 v[230:233], v194 offset:38912
	ds_read_b128 v[224:227], v195 offset:36864
	ds_read_b128 v[234:237], v195 offset:38912
	global_load_lds_dwordx4 v[238:239], off sc1
	v_lshl_add_u64 v[238:239], s[50:51], 0, v[164:165]
	s_mov_b32 m0, s21
	s_nop 0
	global_load_lds_dwordx4 v[238:239], off sc1
	s_waitcnt vmcnt(8)
	s_waitcnt lgkmcnt(0)
	s_barrier
	s_setprio 3
	s_waitcnt lgkmcnt(0)
	v_mfma_scale_f32_16x16x128_f8f6f4 v[156:159], v[0:7], v[204:211], v[156:159], v196, v196 op_sel_hi:[0,0,0]
	v_mfma_scale_f32_16x16x128_f8f6f4 v[152:155], v[8:15], v[204:211], v[152:155], v196, v196 op_sel_hi:[0,0,0]
	v_mfma_scale_f32_16x16x128_f8f6f4 v[136:139], v[8:15], v[212:219], v[136:139], v196, v196 op_sel_hi:[0,0,0]
	v_mfma_scale_f32_16x16x128_f8f6f4 v[140:143], v[0:7], v[212:219], v[140:143], v196, v196 op_sel_hi:[0,0,0]
	v_mfma_scale_f32_16x16x128_f8f6f4 v[124:127], v[0:7], v[220:227], v[124:127], v196, v196 op_sel_hi:[0,0,0]
	v_mfma_scale_f32_16x16x128_f8f6f4 v[120:123], v[8:15], v[220:227], v[120:123], v196, v196 op_sel_hi:[0,0,0]
	v_mfma_scale_f32_16x16x128_f8f6f4 v[104:107], v[8:15], v[230:237], v[104:107], v196, v196 op_sel_hi:[0,0,0]
	v_mfma_scale_f32_16x16x128_f8f6f4 v[108:111], v[0:7], v[230:237], v[108:111], v196, v196 op_sel_hi:[0,0,0]
	s_setprio 0
	s_setprio 3
	v_mfma_scale_f32_16x16x128_f8f6f4 v[148:151], v[16:23], v[204:211], v[148:151], v196, v196 op_sel_hi:[0,0,0]
	v_mfma_scale_f32_16x16x128_f8f6f4 v[144:147], v[24:31], v[204:211], v[144:147], v196, v196 op_sel_hi:[0,0,0]
	v_mfma_scale_f32_16x16x128_f8f6f4 v[128:131], v[24:31], v[212:219], v[128:131], v196, v196 op_sel_hi:[0,0,0]
	v_mfma_scale_f32_16x16x128_f8f6f4 v[132:135], v[16:23], v[212:219], v[132:135], v196, v196 op_sel_hi:[0,0,0]
	v_mfma_scale_f32_16x16x128_f8f6f4 v[116:119], v[16:23], v[220:227], v[116:119], v196, v196 op_sel_hi:[0,0,0]
	v_mfma_scale_f32_16x16x128_f8f6f4 v[112:115], v[24:31], v[220:227], v[112:115], v196, v196 op_sel_hi:[0,0,0]
	v_mfma_scale_f32_16x16x128_f8f6f4 v[96:99], v[24:31], v[230:237], v[96:99], v196, v196 op_sel_hi:[0,0,0]
	v_mfma_scale_f32_16x16x128_f8f6f4 v[100:103], v[16:23], v[230:237], v[100:103], v196, v196 op_sel_hi:[0,0,0]
	s_setprio 0
	s_barrier
	s_add_i32 s41, s41, s68
	v_lshl_add_u64 v[174:175], v[174:175], 0, s[10:11]
	s_mov_b32 m0, s41
	ds_read_b128 v[204:207], v194 offset:49152
	ds_read_b128 v[212:215], v194 offset:51200
	ds_read_b128 v[208:211], v195 offset:49152
	ds_read_b128 v[216:219], v195 offset:51200
	ds_read_b128 v[220:223], v194 offset:53248
	ds_read_b128 v[230:233], v194 offset:55296
	ds_read_b128 v[224:227], v195 offset:53248
	ds_read_b128 v[234:237], v195 offset:55296
	global_load_lds_dwordx4 v[174:175], off sc1
	s_add_i32 m0, s41, 0x2000
	s_add_u32 s50, s58, 0x80080
	v_lshl_add_u64 v[174:175], v[176:177], 0, s[10:11]
	s_addc_u32 s51, s59, 0
	s_add_i32 s41, s48, s68
	global_load_lds_dwordx4 v[174:175], off sc1
	v_lshl_add_u64 v[174:175], s[50:51], 0, v[162:163]
	s_mov_b32 m0, s41
	s_nop 0
	global_load_lds_dwordx4 v[174:175], off sc1
	v_lshl_add_u64 v[174:175], s[50:51], 0, v[166:167]
	s_add_i32 m0, s41, 0x2000
	s_nop 0
	global_load_lds_dwordx4 v[174:175], off sc1
	v_lshl_add_u64 v[174:175], v[178:179], 0, s[10:11]
	s_mov_b32 m0, s35
	s_nop 0
	global_load_lds_dwordx4 v[174:175], off sc1
	v_lshl_add_u64 v[174:175], v[180:181], 0, s[10:11]
	s_mov_b32 m0, s53
	s_nop 0
	global_load_lds_dwordx4 v[174:175], off sc1
	s_waitcnt vmcnt(8)
	s_waitcnt lgkmcnt(0)
	s_barrier
	s_setprio 3
	s_waitcnt lgkmcnt(0)
	v_mfma_scale_f32_16x16x128_f8f6f4 v[84:87], v[0:7], v[204:211], v[84:87], v196, v196 op_sel_hi:[0,0,0]
	v_mfma_scale_f32_16x16x128_f8f6f4 v[80:83], v[8:15], v[204:211], v[80:83], v196, v196 op_sel_hi:[0,0,0]
	v_mfma_scale_f32_16x16x128_f8f6f4 v[64:67], v[8:15], v[212:219], v[64:67], v196, v196 op_sel_hi:[0,0,0]
	v_mfma_scale_f32_16x16x128_f8f6f4 v[68:71], v[0:7], v[212:219], v[68:71], v196, v196 op_sel_hi:[0,0,0]
	v_mfma_scale_f32_16x16x128_f8f6f4 v[52:55], v[0:7], v[220:227], v[52:55], v196, v196 op_sel_hi:[0,0,0]
	v_mfma_scale_f32_16x16x128_f8f6f4 v[48:51], v[8:15], v[220:227], v[48:51], v196, v196 op_sel_hi:[0,0,0]
	v_mfma_scale_f32_16x16x128_f8f6f4 v[32:35], v[8:15], v[230:237], v[32:35], v196, v196 op_sel_hi:[0,0,0]
	v_mfma_scale_f32_16x16x128_f8f6f4 v[36:39], v[0:7], v[230:237], v[36:39], v196, v196 op_sel_hi:[0,0,0]
	s_setprio 0
	s_setprio 3
	v_mfma_scale_f32_16x16x128_f8f6f4 v[92:95], v[16:23], v[204:211], v[92:95], v196, v196 op_sel_hi:[0,0,0]
	v_mfma_scale_f32_16x16x128_f8f6f4 v[88:91], v[24:31], v[204:211], v[88:91], v196, v196 op_sel_hi:[0,0,0]
	v_mfma_scale_f32_16x16x128_f8f6f4 v[72:75], v[24:31], v[212:219], v[72:75], v196, v196 op_sel_hi:[0,0,0]
	v_mfma_scale_f32_16x16x128_f8f6f4 v[76:79], v[16:23], v[212:219], v[76:79], v196, v196 op_sel_hi:[0,0,0]
	v_mfma_scale_f32_16x16x128_f8f6f4 v[60:63], v[16:23], v[220:227], v[60:63], v196, v196 op_sel_hi:[0,0,0]
	v_mfma_scale_f32_16x16x128_f8f6f4 v[56:59], v[24:31], v[220:227], v[56:59], v196, v196 op_sel_hi:[0,0,0]
	v_mfma_scale_f32_16x16x128_f8f6f4 v[40:43], v[24:31], v[230:237], v[40:43], v196, v196 op_sel_hi:[0,0,0]
	v_mfma_scale_f32_16x16x128_f8f6f4 v[44:47], v[16:23], v[230:237], v[44:47], v196, v196 op_sel_hi:[0,0,0]
	s_setprio 0
	s_barrier
	s_add_i32 s40, s40, 2
	s_add_u32 s56, s56, 0x100
	s_addc_u32 s57, s57, 0
	s_add_u32 s38, s38, 0x100
	s_addc_u32 s39, s39, 0
	s_cmp_gt_u32 s40, 29
	s_cbranch_scc0 .LBB0_361
	s_and_b64 vcc, exec, s[16:17]
	s_cbranch_vccz .LBB0_364
	s_barrier

; #define PG8_STAGE(bufoff, gbase, voff) do { _Pragma("unroll") for (int _i = 0; _i < 2; ++_i) \
;         __builtin_amdgcn_global_load_lds((const unsigned*)((const char*)(gbase) + (voff)[_i]), (LAS unsigned*)(lds + (bufoff) + ldsw + _i * 8192), 16, 0, 0); } while (0)
; #define PG8_LDA(dst, b, h) do { _Pragma("unroll") for (int m = 0; m < 4; ++m) _Pragma("unroll") for (int k = 0; k < 2; ++k) dst[m][k] = *(const LAS bf16x8*)(lds + PG8_SA(b, h) + aoffk[k] + m * 2048); } while (0)
; #define PG8_LDB(dst, b, h) do { _Pragma("unroll") for (int n = 0; n < 2; ++n) _Pragma("unroll") for (int k = 0; k < 2; ++k) dst[n][k] = *(const LAS bf16x8*)(lds + PG8_SB(b, h) + boffk[k] + n * 2048); } while (0)
; #define PG8_WAIT_V(n) asm volatile("s_waitcnt vmcnt(" #n ")" ::: "memory")
; #define PG8_WAIT_L(n) asm volatile("s_waitcnt lgkmcnt(" #n ")" ::: "memory")
; #define PG8_BAR __builtin_amdgcn_s_barrier()
; #define PG8_SCHED __builtin_amdgcn_sched_barrier(0)
; template <class Epi, class Sched, class GemmT>
; __device__ __forceinline__ void gemm_phase(LAS unsigned char* lds, const GemmT& g, const Sched& S, const Epi& E, const int wid) {
;     ...
;                 const char* a1 = cA + (size_t)(t + 1) * kstep;
;                 const char* a2 = last ? ns.A : cA + (size_t)(t + 2) * kstep; const char* b2 = last ? ns.B : cB + (size_t)(t + 2) * kstep;
;                 const char* a3 = a2 + kstep; const char* b3 = b2 + kstep;
;                 unsigned vA2[2], vB2[2];
; #pragma unroll
;                 for (int i = 0; i < 2; ++i) { vA2[i] = last ? nvA[i] : voffA[i]; vB2[i] = last ? nvB[i] : voffB[i]; }
;                 const size_t hA2 = last ? nhA : hstepA, hB2 = last ? nhB : hstepB;
;                 PG8_LDB(B0, 0, 0); PG8_LDB(B1, 0, 1); PG8_SCHED; PG8_LDA(At, 0, 0); PG8_STAGE(PG8_SA(1, 1), a1 + hstepA, voffA);
;                 PG8_WAIT_V(8); PG8_WAIT_L(0); PG8_BAR; PG8_MMA(0, 0, At, B0); PG8_MMA(0, 1, At, B1); PG8_BAR; PG8_SCHED;
;                 PG8_LDA(At, 0, 1); PG8_STAGE(PG8_SB(0, 0), b2, vB2); PG8_STAGE(PG8_SB(0, 1), b2 + hB2, vB2); PG8_STAGE(PG8_SA(0, 0), a2, vA2);
.LBB0_417:
	ds_read_b128 v[140:143], v192
	ds_read_b128 v[144:147], v193
	ds_read_b128 v[148:151], v194
	ds_read_b128 v[152:155], v195
	ds_read_b128 v[156:159], v196
	ds_read_b128 v[160:163], v197
	ds_read_b128 v[164:167], v198
	ds_read_b128 v[168:171], v199
	s_add_u32 s39, s84, 0xfff00080
	s_addc_u32 s40, s85, -1
	s_cmp_eq_u32 s38, 60
	s_cselect_b32 s87, s57, s40
	s_cselect_b32 s86, s56, s39
	s_cselect_b32 s71, s16, s37
	s_cselect_b32 s70, s5, s36
	v_lshl_add_u64 v[176:177], s[84:85], 0, v[128:129]
	s_add_i32 m0, s9, 0xc000
	ds_read_b128 v[172:175], v200
	ds_read_b128 v[208:211], v200 offset:2048
	ds_read_b128 v[212:215], v201
	ds_read_b128 v[216:219], v201 offset:2048
	ds_read_b128 v[220:223], v200 offset:4096
	ds_read_b128 v[224:227], v200 offset:6144
	ds_read_b128 v[230:233], v201 offset:4096
	ds_read_b128 v[234:237], v201 offset:6144
	global_load_lds_dwordx4 v[176:177], off sc1
	v_lshl_add_u64 v[176:177], s[84:85], 0, v[132:133]
	s_add_i32 m0, s9, 0xe000
	s_nop 0
	global_load_lds_dwordx4 v[176:177], off sc1
	s_waitcnt vmcnt(8)
	s_waitcnt lgkmcnt(0)
	s_barrier
	s_setprio 3
	s_waitcnt lgkmcnt(0)
	v_mfma_f32_16x16x32_bf16 v[124:127], v[140:143], v[172:175], v[124:127]
	v_mfma_f32_16x16x32_bf16 v[124:127], v[144:147], v[212:215], v[124:127]
	v_mfma_f32_16x16x32_bf16 v[120:123], v[152:155], v[212:215], v[120:123]
	v_mfma_f32_16x16x32_bf16 v[120:123], v[148:151], v[172:175], v[120:123]
	v_mfma_f32_16x16x32_bf16 v[112:115], v[148:151], v[208:211], v[112:115]
	v_mfma_f32_16x16x32_bf16 v[112:115], v[152:155], v[216:219], v[112:115]
	v_mfma_f32_16x16x32_bf16 v[116:119], v[144:147], v[216:219], v[116:119]
	v_mfma_f32_16x16x32_bf16 v[116:119], v[140:143], v[208:211], v[116:119]
	v_mfma_f32_16x16x32_bf16 v[100:103], v[140:143], v[220:223], v[100:103]
	v_mfma_f32_16x16x32_bf16 v[100:103], v[144:147], v[230:233], v[100:103]
	v_mfma_f32_16x16x32_bf16 v[96:99], v[152:155], v[230:233], v[96:99]
	v_mfma_f32_16x16x32_bf16 v[96:99], v[148:151], v[220:223], v[96:99]
	v_mfma_f32_16x16x32_bf16 v[76:79], v[148:151], v[224:227], v[76:79]
	v_mfma_f32_16x16x32_bf16 v[76:79], v[152:155], v[234:237], v[76:79]
	v_mfma_f32_16x16x32_bf16 v[84:87], v[144:147], v[234:237], v[84:87]
	v_mfma_f32_16x16x32_bf16 v[84:87], v[140:143], v[224:227], v[84:87]
	s_setprio 0
	s_setprio 3
	v_mfma_f32_16x16x32_bf16 v[108:111], v[156:159], v[172:175], v[108:111]
	v_mfma_f32_16x16x32_bf16 v[108:111], v[160:163], v[212:215], v[108:111]
	v_mfma_f32_16x16x32_bf16 v[104:107], v[168:171], v[212:215], v[104:107]
	v_mfma_f32_16x16x32_bf16 v[104:107], v[164:167], v[172:175], v[104:107]
	v_mfma_f32_16x16x32_bf16 v[88:91], v[164:167], v[208:211], v[88:91]
	v_mfma_f32_16x16x32_bf16 v[88:91], v[168:171], v[216:219], v[88:91]
	v_mfma_f32_16x16x32_bf16 v[92:95], v[160:163], v[216:219], v[92:95]
	v_mfma_f32_16x16x32_bf16 v[92:95], v[156:159], v[208:211], v[92:95]
	v_mfma_f32_16x16x32_bf16 v[68:71], v[156:159], v[220:223], v[68:71]
	v_mfma_f32_16x16x32_bf16 v[68:71], v[160:163], v[230:233], v[68:71]
	v_mfma_f32_16x16x32_bf16 v[64:67], v[168:171], v[230:233], v[64:67]
	v_mfma_f32_16x16x32_bf16 v[64:67], v[164:167], v[220:223], v[64:67]
	v_mfma_f32_16x16x32_bf16 v[40:43], v[164:167], v[224:227], v[40:43]
	v_mfma_f32_16x16x32_bf16 v[40:43], v[168:171], v[234:237], v[40:43]
	v_mfma_f32_16x16x32_bf16 v[48:51], v[160:163], v[234:237], v[48:51]
	v_mfma_f32_16x16x32_bf16 v[48:51], v[156:159], v[224:227], v[48:51]
	s_setprio 0
	s_barrier
	s_add_i32 s39, s35, s68
	v_lshl_add_u64 v[176:177], s[70:71], 0, v[130:131]
	s_mov_b32 m0, s39
	ds_read_b128 v[172:175], v200 offset:16384
	ds_read_b128 v[208:211], v200 offset:18432
	ds_read_b128 v[212:215], v201 offset:16384
	ds_read_b128 v[216:219], v201 offset:18432
	ds_read_b128 v[220:223], v200 offset:20480
	ds_read_b128 v[224:227], v200 offset:22528
	ds_read_b128 v[230:233], v201 offset:20480
	ds_read_b128 v[234:237], v201 offset:22528
	global_load_lds_dwordx4 v[176:177], off sc1
	s_add_i32 m0, s39, 0x2000
	s_add_u32 s40, s70, 0x100000
	v_lshl_add_u64 v[180:181], s[70:71], 0, v[134:135]
	s_addc_u32 s41, s71, 0
	s_add_i32 s39, s69, s68
	global_load_lds_dwordx4 v[180:181], off sc1
	v_lshl_add_u64 v[184:185], s[40:41], 0, v[130:131]
	s_mov_b32 m0, s39
	v_lshl_add_u64 v[188:189], s[86:87], 0, v[132:133]
	global_load_lds_dwordx4 v[184:185], off sc1
	v_lshl_add_u64 v[184:185], s[40:41], 0, v[134:135]
	s_add_i32 m0, s39, 0x2000
	s_nop 0
	global_load_lds_dwordx4 v[184:185], off sc1
	v_lshl_add_u64 v[184:185], s[86:87], 0, v[128:129]
	s_mov_b32 m0, s9
	s_nop 0
	global_load_lds_dwordx4 v[184:185], off sc1
	s_mov_b32 m0, s29
	s_nop 0
	global_load_lds_dwordx4 v[188:189], off sc1
	s_waitcnt vmcnt(8)
	s_waitcnt lgkmcnt(0)
	s_barrier
; #define PG8_STAGE(bufoff, gbase, voff) do { _Pragma("unroll") for (int _i = 0; _i < 2; ++_i) \
;         __builtin_amdgcn_global_load_lds((const unsigned*)((const char*)(gbase) + (voff)[_i]), (LAS unsigned*)(lds + (bufoff) + ldsw + _i * 8192), 16, 0, 0); } while (0)
; #define PG8_LDA(dst, b, h) do { _Pragma("unroll") for (int m = 0; m < 4; ++m) _Pragma("unroll") for (int k = 0; k < 2; ++k) dst[m][k] = *(const LAS bf16x8*)(lds + PG8_SA(b, h) + aoffk[k] + m * 2048); } while (0)
; #define PG8_LDB(dst, b, h) do { _Pragma("unroll") for (int n = 0; n < 2; ++n) _Pragma("unroll") for (int k = 0; k < 2; ++k) dst[n][k] = *(const LAS bf16x8*)(lds + PG8_SB(b, h) + boffk[k] + n * 2048); } while (0)
; #define PG8_WAIT_V(n) asm volatile("s_waitcnt vmcnt(" #n ")" ::: "memory")
; #define PG8_WAIT_L(n) asm volatile("s_waitcnt lgkmcnt(" #n ")" ::: "memory")
; #define PG8_BAR __builtin_amdgcn_s_barrier()
; #define PG8_SCHED __builtin_amdgcn_sched_barrier(0)
; template <class Epi, class Sched, class GemmT>
; __device__ __forceinline__ void gemm_phase(LAS unsigned char* lds, const GemmT& g, const Sched& S, const Epi& E, const int wid) {
;     ...
;                 PG8_WAIT_V(8); PG8_WAIT_L(0); PG8_BAR; PG8_MMA(0, 0, At, B0); PG8_MMA(0, 1, At, B1); PG8_BAR; PG8_SCHED;
;                 PG8_LDA(At, 0, 1); PG8_STAGE(PG8_SB(0, 0), b2, vB2); PG8_STAGE(PG8_SB(0, 1), b2 + hB2, vB2); PG8_STAGE(PG8_SA(0, 0), a2, vA2);
;                 PG8_WAIT_V(8); PG8_WAIT_L(0); PG8_BAR; PG8_MMA(1, 0, At, B0); PG8_MMA(1, 1, At, B1); PG8_BAR; PG8_SCHED;
;                 PG8_LDB(B0, 1, 0); PG8_LDB(B1, 1, 1); PG8_SCHED; PG8_LDA(At, 1, 0); PG8_STAGE(PG8_SA(0, 1), a2 + hA2, vA2);
;                 PG8_WAIT_V(8); PG8_WAIT_L(0); PG8_BAR; PG8_MMA(0, 0, At, B0); PG8_MMA(0, 1, At, B1); PG8_BAR; PG8_SCHED;
	s_setprio 3
	s_waitcnt lgkmcnt(0)
	v_mfma_f32_16x16x32_bf16 v[28:31], v[140:143], v[172:175], v[28:31]
	v_mfma_f32_16x16x32_bf16 v[28:31], v[144:147], v[212:215], v[28:31]
	v_mfma_f32_16x16x32_bf16 v[24:27], v[152:155], v[212:215], v[24:27]
	v_mfma_f32_16x16x32_bf16 v[24:27], v[148:151], v[172:175], v[24:27]
	v_mfma_f32_16x16x32_bf16 v[16:19], v[148:151], v[208:211], v[16:19]
	v_mfma_f32_16x16x32_bf16 v[16:19], v[152:155], v[216:219], v[16:19]
	v_mfma_f32_16x16x32_bf16 v[20:23], v[144:147], v[216:219], v[20:23]
	v_mfma_f32_16x16x32_bf16 v[20:23], v[140:143], v[208:211], v[20:23]
	v_mfma_f32_16x16x32_bf16 v[12:15], v[140:143], v[220:223], v[12:15]
	v_mfma_f32_16x16x32_bf16 v[12:15], v[144:147], v[230:233], v[12:15]
	v_mfma_f32_16x16x32_bf16 v[8:11], v[152:155], v[230:233], v[8:11]
	v_mfma_f32_16x16x32_bf16 v[8:11], v[148:151], v[220:223], v[8:11]
	v_mfma_f32_16x16x32_bf16 v[0:3], v[148:151], v[224:227], v[0:3]
	v_mfma_f32_16x16x32_bf16 v[0:3], v[152:155], v[234:237], v[0:3]
	v_mfma_f32_16x16x32_bf16 v[4:7], v[144:147], v[234:237], v[4:7]
	v_mfma_f32_16x16x32_bf16 v[4:7], v[140:143], v[224:227], v[4:7]
	s_setprio 0
	s_setprio 3
	v_mfma_f32_16x16x32_bf16 v[80:83], v[156:159], v[172:175], v[80:83]
	v_mfma_f32_16x16x32_bf16 v[80:83], v[160:163], v[212:215], v[80:83]
	v_mfma_f32_16x16x32_bf16 v[72:75], v[168:171], v[212:215], v[72:75]
	v_mfma_f32_16x16x32_bf16 v[72:75], v[164:167], v[172:175], v[72:75]
	v_mfma_f32_16x16x32_bf16 v[56:59], v[164:167], v[208:211], v[56:59]
	v_mfma_f32_16x16x32_bf16 v[56:59], v[168:171], v[216:219], v[56:59]
	v_mfma_f32_16x16x32_bf16 v[60:63], v[160:163], v[216:219], v[60:63]
	v_mfma_f32_16x16x32_bf16 v[60:63], v[156:159], v[208:211], v[60:63]
	v_mfma_f32_16x16x32_bf16 v[52:55], v[156:159], v[220:223], v[52:55]
	v_mfma_f32_16x16x32_bf16 v[52:55], v[160:163], v[230:233], v[52:55]
	v_mfma_f32_16x16x32_bf16 v[44:47], v[168:171], v[230:233], v[44:47]
	v_mfma_f32_16x16x32_bf16 v[44:47], v[164:167], v[220:223], v[44:47]
	v_mfma_f32_16x16x32_bf16 v[32:35], v[164:167], v[224:227], v[32:35]
	v_mfma_f32_16x16x32_bf16 v[32:35], v[168:171], v[234:237], v[32:35]
	v_mfma_f32_16x16x32_bf16 v[36:39], v[160:163], v[234:237], v[36:39]
	v_mfma_f32_16x16x32_bf16 v[36:39], v[156:159], v[224:227], v[36:39]
	s_setprio 0
	s_barrier
	s_add_i32 s39, 0, 0x18000
	s_add_i32 s48, 0, 0x1c000
	v_add_u32_e32 v140, s39, v187
	v_add_u32_e32 v144, s39, v190
	v_add_u32_e32 v156, s48, v187
	v_add_u32_e32 v160, s48, v190
	ds_read_b128 v[140:143], v140
	ds_read_b128 v[144:147], v144
	ds_read_b128 v[148:151], v202
	ds_read_b128 v[152:155], v203
	ds_read_b128 v[156:159], v156
	ds_read_b128 v[160:163], v160
	ds_read_b128 v[164:167], v204
	ds_read_b128 v[168:171], v205
	s_add_u32 s40, s86, 0x100000
	s_addc_u32 s41, s87, 0
	s_mov_b32 m0, s93
	v_lshl_add_u64 v[238:239], s[40:41], 0, v[128:129]
	ds_read_b128 v[172:175], v200 offset:32768
	ds_read_b128 v[208:211], v200 offset:34816
	ds_read_b128 v[212:215], v201 offset:32768
	ds_read_b128 v[216:219], v201 offset:34816
	ds_read_b128 v[220:223], v200 offset:36864
	ds_read_b128 v[224:227], v200 offset:38912
	ds_read_b128 v[230:233], v201 offset:36864
	ds_read_b128 v[234:237], v201 offset:38912
	global_load_lds_dwordx4 v[238:239], off sc1
	v_lshl_add_u64 v[238:239], s[40:41], 0, v[132:133]
	s_mov_b32 m0, s6
	s_nop 0
	global_load_lds_dwordx4 v[238:239], off sc1
	s_waitcnt vmcnt(8)
	s_waitcnt lgkmcnt(0)
	s_barrier
	s_setprio 3
	s_waitcnt lgkmcnt(0)
	v_mfma_f32_16x16x32_bf16 v[124:127], v[140:143], v[172:175], v[124:127]
	v_mfma_f32_16x16x32_bf16 v[124:127], v[144:147], v[212:215], v[124:127]
	v_mfma_f32_16x16x32_bf16 v[120:123], v[152:155], v[212:215], v[120:123]
	v_mfma_f32_16x16x32_bf16 v[120:123], v[148:151], v[172:175], v[120:123]
	v_mfma_f32_16x16x32_bf16 v[112:115], v[148:151], v[208:211], v[112:115]
	v_mfma_f32_16x16x32_bf16 v[112:115], v[152:155], v[216:219], v[112:115]
	v_mfma_f32_16x16x32_bf16 v[116:119], v[144:147], v[216:219], v[116:119]
	v_mfma_f32_16x16x32_bf16 v[116:119], v[140:143], v[208:211], v[116:119]
	v_mfma_f32_16x16x32_bf16 v[100:103], v[140:143], v[220:223], v[100:103]
	v_mfma_f32_16x16x32_bf16 v[100:103], v[144:147], v[230:233], v[100:103]
	v_mfma_f32_16x16x32_bf16 v[96:99], v[152:155], v[230:233], v[96:99]
	v_mfma_f32_16x16x32_bf16 v[96:99], v[148:151], v[220:223], v[96:99]
	v_mfma_f32_16x16x32_bf16 v[76:79], v[148:151], v[224:227], v[76:79]
	v_mfma_f32_16x16x32_bf16 v[76:79], v[152:155], v[234:237], v[76:79]
	v_mfma_f32_16x16x32_bf16 v[84:87], v[144:147], v[234:237], v[84:87]
	v_mfma_f32_16x16x32_bf16 v[84:87], v[140:143], v[224:227], v[84:87]
	s_setprio 0
	s_setprio 3
	v_mfma_f32_16x16x32_bf16 v[108:111], v[156:159], v[172:175], v[108:111]
	v_mfma_f32_16x16x32_bf16 v[108:111], v[160:163], v[212:215], v[108:111]
	v_mfma_f32_16x16x32_bf16 v[104:107], v[168:171], v[212:215], v[104:107]
	v_mfma_f32_16x16x32_bf16 v[104:107], v[164:167], v[172:175], v[104:107]
	v_mfma_f32_16x16x32_bf16 v[88:91], v[164:167], v[208:211], v[88:91]
	v_mfma_f32_16x16x32_bf16 v[88:91], v[168:171], v[216:219], v[88:91]
	v_mfma_f32_16x16x32_bf16 v[92:95], v[160:163], v[216:219], v[92:95]
	v_mfma_f32_16x16x32_bf16 v[92:95], v[156:159], v[208:211], v[92:95]
	v_mfma_f32_16x16x32_bf16 v[68:71], v[156:159], v[220:223], v[68:71]
	v_mfma_f32_16x16x32_bf16 v[68:71], v[160:163], v[230:233], v[68:71]
	v_mfma_f32_16x16x32_bf16 v[64:67], v[168:171], v[230:233], v[64:67]
	v_mfma_f32_16x16x32_bf16 v[64:67], v[164:167], v[220:223], v[64:67]
	v_mfma_f32_16x16x32_bf16 v[40:43], v[164:167], v[224:227], v[40:43]
	v_mfma_f32_16x16x32_bf16 v[40:43], v[168:171], v[234:237], v[40:43]
	v_mfma_f32_16x16x32_bf16 v[48:51], v[160:163], v[234:237], v[48:51]
	v_mfma_f32_16x16x32_bf16 v[48:51], v[156:159], v[224:227], v[48:51]
	s_setprio 0
	s_barrier
; #define PG8_STAGE(bufoff, gbase, voff) do { _Pragma("unroll") for (int _i = 0; _i < 2; ++_i) \
;         __builtin_amdgcn_global_load_lds((const unsigned*)((const char*)(gbase) + (voff)[_i]), (LAS unsigned*)(lds + (bufoff) + ldsw + _i * 8192), 16, 0, 0); } while (0)
; #define PG8_LDA(dst, b, h) do { _Pragma("unroll") for (int m = 0; m < 4; ++m) _Pragma("unroll") for (int k = 0; k < 2; ++k) dst[m][k] = *(const LAS bf16x8*)(lds + PG8_SA(b, h) + aoffk[k] + m * 2048); } while (0)
; #define PG8_WAIT_V(n) asm volatile("s_waitcnt vmcnt(" #n ")" ::: "memory")
; #define PG8_WAIT_L(n) asm volatile("s_waitcnt lgkmcnt(" #n ")" ::: "memory")
; #define PG8_BAR __builtin_amdgcn_s_barrier()
; #define PG8_SCHED __builtin_amdgcn_sched_barrier(0)
; template <class Epi, class Sched, class GemmT>
; __device__ __forceinline__ void gemm_phase(LAS unsigned char* lds, const GemmT& g, const Sched& S, const Epi& E, const int wid) {
;     ...
;                 PG8_LDA(At, 1, 1); PG8_STAGE(PG8_SB(1, 0), b3, vB2); PG8_STAGE(PG8_SB(1, 1), b3 + hB2, vB2); PG8_STAGE(PG8_SA(1, 0), a3, vA2);
;                 PG8_WAIT_V(8); PG8_WAIT_L(0); PG8_BAR; PG8_MMA(1, 0, At, B0); PG8_MMA(1, 1, At, B1); PG8_BAR; PG8_SCHED;
;             }
;             if constexpr (NSEG > 1) { if (sgi + 1 < NSEG) E.mid(acc, cur, sgi, wr, wc, fr, fq); }
;             cs = ns; cA = ns.A; cB = ns.B; hstepA = nhA; hstepB = nhB;
; #pragma unroll
;             for (int i = 0; i < 2; ++i) { voffA[i] = nvA[i]; voffB[i] = nvB[i]; }
;         }
;         if (wr == 0) PG8_BAR;
	s_add_i32 s39, s39, s68
	v_lshl_add_u64 v[176:177], v[176:177], 0, s[66:67]
	s_mov_b32 m0, s39
	ds_read_b128 v[172:175], v200 offset:49152
	ds_read_b128 v[208:211], v200 offset:51200
	ds_read_b128 v[212:215], v201 offset:49152
	ds_read_b128 v[216:219], v201 offset:51200
	ds_read_b128 v[220:223], v200 offset:53248
	ds_read_b128 v[224:227], v200 offset:55296
	ds_read_b128 v[230:233], v201 offset:53248
	ds_read_b128 v[234:237], v201 offset:55296
	global_load_lds_dwordx4 v[176:177], off sc1
	s_add_i32 m0, s39, 0x2000
	s_add_u32 s40, s70, 0x100080
	v_lshl_add_u64 v[176:177], v[180:181], 0, s[66:67]
	s_addc_u32 s41, s71, 0
	s_add_i32 s39, s48, s68
	global_load_lds_dwordx4 v[176:177], off sc1
	v_lshl_add_u64 v[176:177], s[40:41], 0, v[130:131]
	s_mov_b32 m0, s39
	s_nop 0
	global_load_lds_dwordx4 v[176:177], off sc1
	v_lshl_add_u64 v[176:177], s[40:41], 0, v[134:135]
	s_add_i32 m0, s39, 0x2000
	s_nop 0
	global_load_lds_dwordx4 v[176:177], off sc1
	v_lshl_add_u64 v[176:177], v[184:185], 0, s[66:67]
	s_mov_b32 m0, s7
	s_nop 0
	global_load_lds_dwordx4 v[176:177], off sc1
	v_lshl_add_u64 v[176:177], v[188:189], 0, s[66:67]
	s_mov_b32 m0, s12
	s_nop 0
	global_load_lds_dwordx4 v[176:177], off sc1
	s_waitcnt vmcnt(8)
	s_waitcnt lgkmcnt(0)
	s_barrier
	s_setprio 3
	s_waitcnt lgkmcnt(0)
	v_mfma_f32_16x16x32_bf16 v[28:31], v[140:143], v[172:175], v[28:31]
	v_mfma_f32_16x16x32_bf16 v[28:31], v[144:147], v[212:215], v[28:31]
	v_mfma_f32_16x16x32_bf16 v[24:27], v[152:155], v[212:215], v[24:27]
	v_mfma_f32_16x16x32_bf16 v[24:27], v[148:151], v[172:175], v[24:27]
	v_mfma_f32_16x16x32_bf16 v[16:19], v[148:151], v[208:211], v[16:19]
	v_mfma_f32_16x16x32_bf16 v[16:19], v[152:155], v[216:219], v[16:19]
	v_mfma_f32_16x16x32_bf16 v[20:23], v[144:147], v[216:219], v[20:23]
	v_mfma_f32_16x16x32_bf16 v[20:23], v[140:143], v[208:211], v[20:23]
	v_mfma_f32_16x16x32_bf16 v[12:15], v[140:143], v[220:223], v[12:15]
	v_mfma_f32_16x16x32_bf16 v[12:15], v[144:147], v[230:233], v[12:15]
	v_mfma_f32_16x16x32_bf16 v[8:11], v[152:155], v[230:233], v[8:11]
	v_mfma_f32_16x16x32_bf16 v[8:11], v[148:151], v[220:223], v[8:11]
	v_mfma_f32_16x16x32_bf16 v[0:3], v[148:151], v[224:227], v[0:3]
	v_mfma_f32_16x16x32_bf16 v[0:3], v[152:155], v[234:237], v[0:3]
	v_mfma_f32_16x16x32_bf16 v[4:7], v[144:147], v[234:237], v[4:7]
	v_mfma_f32_16x16x32_bf16 v[4:7], v[140:143], v[224:227], v[4:7]
	s_setprio 0
	s_setprio 3
	v_mfma_f32_16x16x32_bf16 v[80:83], v[156:159], v[172:175], v[80:83]
	v_mfma_f32_16x16x32_bf16 v[80:83], v[160:163], v[212:215], v[80:83]
	v_mfma_f32_16x16x32_bf16 v[72:75], v[168:171], v[212:215], v[72:75]
	v_mfma_f32_16x16x32_bf16 v[72:75], v[164:167], v[172:175], v[72:75]
	v_mfma_f32_16x16x32_bf16 v[56:59], v[164:167], v[208:211], v[56:59]
	v_mfma_f32_16x16x32_bf16 v[56:59], v[168:171], v[216:219], v[56:59]
	v_mfma_f32_16x16x32_bf16 v[60:63], v[160:163], v[216:219], v[60:63]
	v_mfma_f32_16x16x32_bf16 v[60:63], v[156:159], v[208:211], v[60:63]
	v_mfma_f32_16x16x32_bf16 v[52:55], v[156:159], v[220:223], v[52:55]
	v_mfma_f32_16x16x32_bf16 v[52:55], v[160:163], v[230:233], v[52:55]
	v_mfma_f32_16x16x32_bf16 v[44:47], v[168:171], v[230:233], v[44:47]
	v_mfma_f32_16x16x32_bf16 v[44:47], v[164:167], v[220:223], v[44:47]
	v_mfma_f32_16x16x32_bf16 v[32:35], v[164:167], v[224:227], v[32:35]
	v_mfma_f32_16x16x32_bf16 v[32:35], v[168:171], v[234:237], v[32:35]
	v_mfma_f32_16x16x32_bf16 v[36:39], v[160:163], v[234:237], v[36:39]
	v_mfma_f32_16x16x32_bf16 v[36:39], v[156:159], v[224:227], v[36:39]
	s_setprio 0
	s_barrier
	s_add_i32 s38, s38, 2
	s_add_u32 s84, s84, 0x100
	s_addc_u32 s85, s85, 0
	s_add_u32 s36, s36, 0x100
	s_addc_u32 s37, s37, 0
	s_cmp_gt_u32 s38, 61
	s_cbranch_scc0 .LBB0_417
	s_and_b64 vcc, exec, s[20:21]
	s_cbranch_vccz .LBB0_420
	s_barrier

; #define PG8_STAGE(bufoff, gbase, voff) do { _Pragma("unroll") for (int _i = 0; _i < 2; ++_i) \
;         __builtin_amdgcn_global_load_lds((const unsigned*)((const char*)(gbase) + (voff)[_i]), (LAS unsigned*)(lds + (bufoff) + ldsw + _i * 8192), 16, 0, 0); } while (0)
; #define PG8_LDA(dst, b, h) do { _Pragma("unroll") for (int m = 0; m < 4; ++m) _Pragma("unroll") for (int k = 0; k < 2; ++k) dst[m][k] = *(const LAS bf16x8*)(lds + PG8_SA(b, h) + aoffk[k] + m * 2048); } while (0)
; #define PG8_LDB(dst, b, h) do { _Pragma("unroll") for (int n = 0; n < 2; ++n) _Pragma("unroll") for (int k = 0; k < 2; ++k) dst[n][k] = *(const LAS bf16x8*)(lds + PG8_SB(b, h) + boffk[k] + n * 2048); } while (0)
; #define PG8_WAIT_V(n) asm volatile("s_waitcnt vmcnt(" #n ")" ::: "memory")
; #define PG8_WAIT_L(n) asm volatile("s_waitcnt lgkmcnt(" #n ")" ::: "memory")
; #define PG8_BAR __builtin_amdgcn_s_barrier()
; #define PG8_SCHED __builtin_amdgcn_sched_barrier(0)
; template <class Epi, class Sched, class GemmT>
; __device__ __forceinline__ void gemm_phase(LAS unsigned char* lds, const GemmT& g, const Sched& S, const Epi& E, const int wid) {
;     ...
;             for (int t = 0; t < nt; t += 2) {
;                 const bool last = (t == nt - 2);
;                 const char* a1 = cA + (size_t)(t + 1) * kstep;
;                 const char* a2 = last ? ns.A : cA + (size_t)(t + 2) * kstep; const char* b2 = last ? ns.B : cB + (size_t)(t + 2) * kstep;
;                 const char* a3 = a2 + kstep; const char* b3 = b2 + kstep;
;                 unsigned vA2[2], vB2[2];
; #pragma unroll
;                 for (int i = 0; i < 2; ++i) { vA2[i] = last ? nvA[i] : voffA[i]; vB2[i] = last ? nvB[i] : voffB[i]; }
;                 const size_t hA2 = last ? nhA : hstepA, hB2 = last ? nhB : hstepB;
;                 PG8_LDB(B0, 0, 0); PG8_LDB(B1, 0, 1); PG8_SCHED; PG8_LDA(At, 0, 0); PG8_STAGE(PG8_SA(1, 1), a1 + hstepA, voffA);
;                 PG8_WAIT_V(8); PG8_WAIT_L(0); PG8_BAR; PG8_MMA(0, 0, At, B0); PG8_MMA(0, 1, At, B1); PG8_BAR; PG8_SCHED;
;                 PG8_LDA(At, 0, 1); PG8_STAGE(PG8_SB(0, 0), b2, vB2); PG8_STAGE(PG8_SB(0, 1), b2 + hB2, vB2); PG8_STAGE(PG8_SA(0, 0), a2, vA2);
.LBB0_764:
	s_cmp_eq_u32 s43, s56
	s_cselect_b64 vcc, -1, 0
	s_add_i32 s90, s90, 2
	v_add_u32_e32 v131, s62, v208
	s_add_u32 s48, s50, s56
	v_add_u32_e32 v133, s62, v209
	ds_read_b128 v[144:147], v131
	ds_read_b128 v[148:151], v133
	v_add_u32_e32 v131, s63, v208
	s_addc_u32 s49, s51, s57
	v_add_u32_e32 v133, s63, v209
	ds_read_b128 v[152:155], v131
	ds_read_b128 v[156:159], v133
	v_add_u32_e32 v131, s64, v208
	s_add_u32 s58, s48, 0x100
	v_add_u32_e32 v133, s64, v209
	ds_read_b128 v[160:163], v131
	ds_read_b128 v[164:167], v133
	v_add_u32_e32 v131, s65, v208
	s_addc_u32 s59, s49, 0
	v_add_u32_e32 v133, s65, v209
	ds_read_b128 v[168:171], v131
	ds_read_b128 v[172:175], v133
	s_and_b64 s[48:49], vcc, exec
	s_cselect_b32 s59, s19, s59
	s_cselect_b32 s58, s18, s58
	s_add_u32 s60, s85, s56
	s_addc_u32 s61, s89, s57
	s_and_b64 s[48:49], vcc, exec
	v_cndmask_b32_e32 v138, v132, v190, vcc
	v_cndmask_b32_e32 v0, v143, v214, vcc
	v_cndmask_b32_e32 v140, v130, v194, vcc
	v_cndmask_b32_e32 v188, v142, v192, vcc
	s_cselect_b32 s61, s13, s61
	s_cselect_b32 s60, s12, s60
	s_cselect_b32 s91, 0, s45
	s_cselect_b32 s92, s6, s44
	v_lshl_add_u64 v[202:203], v[134:135], 0, s[56:57]
	s_add_i32 m0, s14, 0xc000
	ds_read_b128 v[176:179], v212
	ds_read_b128 v[180:183], v212 offset:2048
	ds_read_b128 v[184:187], v213
	ds_read_b128 v[216:219], v213 offset:2048
	ds_read_b128 v[220:223], v212 offset:4096
	ds_read_b128 v[224:227], v212 offset:6144
	ds_read_b128 v[230:233], v213 offset:4096
	ds_read_b128 v[234:237], v213 offset:6144
	global_load_lds_dwordx4 v[202:203], off sc1
	v_lshl_add_u64 v[202:203], v[136:137], 0, s[56:57]
	s_add_i32 m0, s14, 0xe000
	s_nop 0
	global_load_lds_dwordx4 v[202:203], off sc1
	s_waitcnt vmcnt(8)
	s_waitcnt lgkmcnt(0)
	s_barrier
	s_setprio 3
	s_waitcnt lgkmcnt(0)
	v_mfma_f32_16x16x32_bf16 v[126:129], v[144:147], v[176:179], v[126:129]
	v_mfma_f32_16x16x32_bf16 v[126:129], v[148:151], v[184:187], v[126:129]
	v_mfma_f32_16x16x32_bf16 v[122:125], v[156:159], v[184:187], v[122:125]
	v_mfma_f32_16x16x32_bf16 v[122:125], v[152:155], v[176:179], v[122:125]
	v_mfma_f32_16x16x32_bf16 v[106:109], v[152:155], v[180:183], v[106:109]
	v_mfma_f32_16x16x32_bf16 v[106:109], v[156:159], v[216:219], v[106:109]
	v_mfma_f32_16x16x32_bf16 v[110:113], v[148:151], v[216:219], v[110:113]
	v_mfma_f32_16x16x32_bf16 v[110:113], v[144:147], v[180:183], v[110:113]
	v_mfma_f32_16x16x32_bf16 v[94:97], v[144:147], v[220:223], v[94:97]
	v_mfma_f32_16x16x32_bf16 v[94:97], v[148:151], v[230:233], v[94:97]
	v_mfma_f32_16x16x32_bf16 v[90:93], v[156:159], v[230:233], v[90:93]
	v_mfma_f32_16x16x32_bf16 v[90:93], v[152:155], v[220:223], v[90:93]
	v_mfma_f32_16x16x32_bf16 v[74:77], v[152:155], v[224:227], v[74:77]
	v_mfma_f32_16x16x32_bf16 v[74:77], v[156:159], v[234:237], v[74:77]
	v_mfma_f32_16x16x32_bf16 v[78:81], v[148:151], v[234:237], v[78:81]
	v_mfma_f32_16x16x32_bf16 v[78:81], v[144:147], v[224:227], v[78:81]
	s_setprio 0
	s_setprio 3
	v_mfma_f32_16x16x32_bf16 v[118:121], v[160:163], v[176:179], v[118:121]
	v_mfma_f32_16x16x32_bf16 v[118:121], v[164:167], v[184:187], v[118:121]
	v_mfma_f32_16x16x32_bf16 v[114:117], v[172:175], v[184:187], v[114:117]
	v_mfma_f32_16x16x32_bf16 v[114:117], v[168:171], v[176:179], v[114:117]
	v_mfma_f32_16x16x32_bf16 v[98:101], v[168:171], v[180:183], v[98:101]
	v_mfma_f32_16x16x32_bf16 v[98:101], v[172:175], v[216:219], v[98:101]
	v_mfma_f32_16x16x32_bf16 v[102:105], v[164:167], v[216:219], v[102:105]
	v_mfma_f32_16x16x32_bf16 v[102:105], v[160:163], v[180:183], v[102:105]
	v_mfma_f32_16x16x32_bf16 v[86:89], v[160:163], v[220:223], v[86:89]
	v_mfma_f32_16x16x32_bf16 v[86:89], v[164:167], v[230:233], v[86:89]
	v_mfma_f32_16x16x32_bf16 v[82:85], v[172:175], v[230:233], v[82:85]
	v_mfma_f32_16x16x32_bf16 v[82:85], v[168:171], v[220:223], v[82:85]
	v_mfma_f32_16x16x32_bf16 v[66:69], v[168:171], v[224:227], v[66:69]
	v_mfma_f32_16x16x32_bf16 v[66:69], v[172:175], v[234:237], v[66:69]
	v_mfma_f32_16x16x32_bf16 v[70:73], v[164:167], v[234:237], v[70:73]
	v_mfma_f32_16x16x32_bf16 v[70:73], v[160:163], v[224:227], v[70:73]
	s_setprio 0
	s_barrier
	s_add_i32 s48, s62, s68
	s_mov_b32 m0, s48
	ds_read_b128 v[176:179], v212 offset:16384
	ds_read_b128 v[180:183], v213 offset:16384
	ds_read_b128 v[184:187], v212 offset:18432
	ds_read_b128 v[216:219], v213 offset:18432
	ds_read_b128 v[220:223], v212 offset:20480
	ds_read_b128 v[224:227], v213 offset:20480
	ds_read_b128 v[230:233], v212 offset:22528
	ds_read_b128 v[234:237], v213 offset:22528
	global_load_lds_dwordx4 v0, s[60:61] sc1
	s_add_i32 m0, s48, 0x2000
	v_mov_b32_e32 v189, v1
	s_add_u32 s48, s60, s92
	v_lshl_add_u64 v[202:203], s[60:61], 0, v[0:1]
	v_lshl_add_u64 v[238:239], s[60:61], 0, v[188:189]
	global_load_lds_dwordx4 v188, s[60:61] sc1
	s_addc_u32 s49, s61, s91
	s_add_i32 s60, s64, s68
	s_mov_b32 m0, s60
	v_mov_b32_e32 v139, v1
	global_load_lds_dwordx4 v0, s[48:49] sc1
	s_add_i32 m0, s60, 0x2000
	v_mov_b32_e32 v141, v1
	global_load_lds_dwordx4 v188, s[48:49] sc1
	s_mov_b32 m0, s14
	v_lshl_add_u64 v[240:241], s[48:49], 0, v[0:1]
	global_load_lds_dwordx4 v138, s[58:59] sc1
	s_mov_b32 m0, s15
	v_lshl_add_u64 v[242:243], s[48:49], 0, v[188:189]
	global_load_lds_dwordx4 v140, s[58:59] sc1
	s_waitcnt vmcnt(8)
	s_waitcnt lgkmcnt(0)
	v_lshl_add_u64 v[188:189], s[58:59], 0, v[138:139]
	v_lshl_add_u64 v[244:245], s[58:59], 0, v[140:141]
	s_barrier
; #define PG8_STAGE(bufoff, gbase, voff) do { _Pragma("unroll") for (int _i = 0; _i < 2; ++_i) \
;         __builtin_amdgcn_global_load_lds((const unsigned*)((const char*)(gbase) + (voff)[_i]), (LAS unsigned*)(lds + (bufoff) + ldsw + _i * 8192), 16, 0, 0); } while (0)
; #define PG8_LDA(dst, b, h) do { _Pragma("unroll") for (int m = 0; m < 4; ++m) _Pragma("unroll") for (int k = 0; k < 2; ++k) dst[m][k] = *(const LAS bf16x8*)(lds + PG8_SA(b, h) + aoffk[k] + m * 2048); } while (0)
; #define PG8_LDB(dst, b, h) do { _Pragma("unroll") for (int n = 0; n < 2; ++n) _Pragma("unroll") for (int k = 0; k < 2; ++k) dst[n][k] = *(const LAS bf16x8*)(lds + PG8_SB(b, h) + boffk[k] + n * 2048); } while (0)
; #define PG8_WAIT_V(n) asm volatile("s_waitcnt vmcnt(" #n ")" ::: "memory")
; #define PG8_WAIT_L(n) asm volatile("s_waitcnt lgkmcnt(" #n ")" ::: "memory")
; #define PG8_BAR __builtin_amdgcn_s_barrier()
; #define PG8_SCHED __builtin_amdgcn_sched_barrier(0)
; template <class Epi, class Sched, class GemmT>
; __device__ __forceinline__ void gemm_phase(LAS unsigned char* lds, const GemmT& g, const Sched& S, const Epi& E, const int wid) {
;     ...
;                 PG8_WAIT_V(8); PG8_WAIT_L(0); PG8_BAR; PG8_MMA(1, 0, At, B0); PG8_MMA(1, 1, At, B1); PG8_BAR; PG8_SCHED;
;                 PG8_LDB(B0, 1, 0); PG8_LDB(B1, 1, 1); PG8_SCHED; PG8_LDA(At, 1, 0); PG8_STAGE(PG8_SA(0, 1), a2 + hA2, vA2);
;                 PG8_WAIT_V(8); PG8_WAIT_L(0); PG8_BAR; PG8_MMA(0, 0, At, B0); PG8_MMA(0, 1, At, B1); PG8_BAR; PG8_SCHED;
	s_setprio 3
	s_waitcnt lgkmcnt(0)
	v_mfma_f32_16x16x32_bf16 v[62:65], v[144:147], v[176:179], v[62:65]
	v_mfma_f32_16x16x32_bf16 v[62:65], v[148:151], v[180:183], v[62:65]
	v_mfma_f32_16x16x32_bf16 v[58:61], v[156:159], v[180:183], v[58:61]
	v_mfma_f32_16x16x32_bf16 v[58:61], v[152:155], v[176:179], v[58:61]
	v_mfma_f32_16x16x32_bf16 v[42:45], v[152:155], v[184:187], v[42:45]
	v_mfma_f32_16x16x32_bf16 v[42:45], v[156:159], v[216:219], v[42:45]
	v_mfma_f32_16x16x32_bf16 v[46:49], v[148:151], v[216:219], v[46:49]
	v_mfma_f32_16x16x32_bf16 v[46:49], v[144:147], v[184:187], v[46:49]
	v_mfma_f32_16x16x32_bf16 v[30:33], v[144:147], v[220:223], v[30:33]
	v_mfma_f32_16x16x32_bf16 v[30:33], v[148:151], v[224:227], v[30:33]
	v_mfma_f32_16x16x32_bf16 v[22:25], v[156:159], v[224:227], v[22:25]
	v_mfma_f32_16x16x32_bf16 v[22:25], v[152:155], v[220:223], v[22:25]
	v_mfma_f32_16x16x32_bf16 v[6:9], v[152:155], v[230:233], v[6:9]
	v_mfma_f32_16x16x32_bf16 v[6:9], v[156:159], v[234:237], v[6:9]
	v_mfma_f32_16x16x32_bf16 v[14:17], v[148:151], v[234:237], v[14:17]
	v_mfma_f32_16x16x32_bf16 v[14:17], v[144:147], v[230:233], v[14:17]
	s_setprio 0
	s_setprio 3
	v_mfma_f32_16x16x32_bf16 v[54:57], v[160:163], v[176:179], v[54:57]
	v_mfma_f32_16x16x32_bf16 v[54:57], v[164:167], v[180:183], v[54:57]
	v_mfma_f32_16x16x32_bf16 v[50:53], v[172:175], v[180:183], v[50:53]
	v_mfma_f32_16x16x32_bf16 v[50:53], v[168:171], v[176:179], v[50:53]
	v_mfma_f32_16x16x32_bf16 v[34:37], v[168:171], v[184:187], v[34:37]
	v_mfma_f32_16x16x32_bf16 v[34:37], v[172:175], v[216:219], v[34:37]
	v_mfma_f32_16x16x32_bf16 v[38:41], v[164:167], v[216:219], v[38:41]
	v_mfma_f32_16x16x32_bf16 v[38:41], v[160:163], v[184:187], v[38:41]
	v_mfma_f32_16x16x32_bf16 v[26:29], v[160:163], v[220:223], v[26:29]
	v_mfma_f32_16x16x32_bf16 v[26:29], v[164:167], v[224:227], v[26:29]
	v_mfma_f32_16x16x32_bf16 v[18:21], v[172:175], v[224:227], v[18:21]
	v_mfma_f32_16x16x32_bf16 v[18:21], v[168:171], v[220:223], v[18:21]
	v_mfma_f32_16x16x32_bf16 v[2:5], v[168:171], v[230:233], v[2:5]
	v_mfma_f32_16x16x32_bf16 v[2:5], v[172:175], v[234:237], v[2:5]
	v_mfma_f32_16x16x32_bf16 v[10:13], v[164:167], v[234:237], v[10:13]
	v_mfma_f32_16x16x32_bf16 v[10:13], v[160:163], v[230:233], v[10:13]
	s_setprio 0
	s_barrier
	s_add_i32 s60, 0, 0x18000
	v_add_u32_e32 v0, s60, v208
	v_add_u32_e32 v131, s60, v209
	ds_read_b128 v[144:147], v0
	ds_read_b128 v[148:151], v131
	v_add_u32_e32 v0, s66, v208
	s_add_i32 s61, 0, 0x1c000
	v_add_u32_e32 v131, s66, v209
	ds_read_b128 v[152:155], v0
	ds_read_b128 v[156:159], v131
	v_add_u32_e32 v0, s61, v208
	v_add_u32_e32 v131, s61, v209
	ds_read_b128 v[160:163], v0
	ds_read_b128 v[164:167], v131
	v_add_u32_e32 v0, s67, v208
	v_add_u32_e32 v131, s67, v209
	ds_read_b128 v[168:171], v0
	ds_read_b128 v[172:175], v131
	s_add_u32 s48, s58, s92
	s_addc_u32 s49, s59, s91
	s_mov_b32 m0, s34
	ds_read_b128 v[176:179], v212 offset:32768
	ds_read_b128 v[180:183], v212 offset:34816
	ds_read_b128 v[184:187], v213 offset:32768
	ds_read_b128 v[216:219], v213 offset:34816
	ds_read_b128 v[220:223], v212 offset:36864
	ds_read_b128 v[224:227], v212 offset:38912
	ds_read_b128 v[230:233], v213 offset:36864
	ds_read_b128 v[234:237], v213 offset:38912
	global_load_lds_dwordx4 v138, s[48:49] sc1
	s_mov_b32 m0, s35
	s_nop 0
	global_load_lds_dwordx4 v140, s[48:49] sc1
	s_waitcnt vmcnt(8)
	s_waitcnt lgkmcnt(0)
	s_barrier
	s_setprio 3
	s_waitcnt lgkmcnt(0)
	v_mfma_f32_16x16x32_bf16 v[126:129], v[144:147], v[176:179], v[126:129]
	v_mfma_f32_16x16x32_bf16 v[126:129], v[148:151], v[184:187], v[126:129]
	v_mfma_f32_16x16x32_bf16 v[122:125], v[156:159], v[184:187], v[122:125]
	v_mfma_f32_16x16x32_bf16 v[122:125], v[152:155], v[176:179], v[122:125]
	v_mfma_f32_16x16x32_bf16 v[106:109], v[152:155], v[180:183], v[106:109]
	v_mfma_f32_16x16x32_bf16 v[106:109], v[156:159], v[216:219], v[106:109]
	v_mfma_f32_16x16x32_bf16 v[110:113], v[148:151], v[216:219], v[110:113]
	v_mfma_f32_16x16x32_bf16 v[110:113], v[144:147], v[180:183], v[110:113]
	v_mfma_f32_16x16x32_bf16 v[94:97], v[144:147], v[220:223], v[94:97]
	v_mfma_f32_16x16x32_bf16 v[94:97], v[148:151], v[230:233], v[94:97]
	v_mfma_f32_16x16x32_bf16 v[90:93], v[156:159], v[230:233], v[90:93]
	v_mfma_f32_16x16x32_bf16 v[90:93], v[152:155], v[220:223], v[90:93]
	v_mfma_f32_16x16x32_bf16 v[74:77], v[152:155], v[224:227], v[74:77]
	v_mfma_f32_16x16x32_bf16 v[74:77], v[156:159], v[234:237], v[74:77]
	v_mfma_f32_16x16x32_bf16 v[78:81], v[148:151], v[234:237], v[78:81]
	v_mfma_f32_16x16x32_bf16 v[78:81], v[144:147], v[224:227], v[78:81]
	s_setprio 0
	s_setprio 3
	v_mfma_f32_16x16x32_bf16 v[118:121], v[160:163], v[176:179], v[118:121]
	v_mfma_f32_16x16x32_bf16 v[118:121], v[164:167], v[184:187], v[118:121]
	v_mfma_f32_16x16x32_bf16 v[114:117], v[172:175], v[184:187], v[114:117]
	v_mfma_f32_16x16x32_bf16 v[114:117], v[168:171], v[176:179], v[114:117]
	v_mfma_f32_16x16x32_bf16 v[98:101], v[168:171], v[180:183], v[98:101]
	v_mfma_f32_16x16x32_bf16 v[98:101], v[172:175], v[216:219], v[98:101]
	v_mfma_f32_16x16x32_bf16 v[102:105], v[164:167], v[216:219], v[102:105]
	v_mfma_f32_16x16x32_bf16 v[102:105], v[160:163], v[180:183], v[102:105]
	v_mfma_f32_16x16x32_bf16 v[86:89], v[160:163], v[220:223], v[86:89]
	v_mfma_f32_16x16x32_bf16 v[86:89], v[164:167], v[230:233], v[86:89]
	v_mfma_f32_16x16x32_bf16 v[82:85], v[172:175], v[230:233], v[82:85]
	v_mfma_f32_16x16x32_bf16 v[82:85], v[168:171], v[220:223], v[82:85]
	v_mfma_f32_16x16x32_bf16 v[66:69], v[168:171], v[224:227], v[66:69]
	v_mfma_f32_16x16x32_bf16 v[66:69], v[172:175], v[234:237], v[66:69]
	v_mfma_f32_16x16x32_bf16 v[70:73], v[164:167], v[234:237], v[70:73]
	v_mfma_f32_16x16x32_bf16 v[70:73], v[160:163], v[224:227], v[70:73]
	s_setprio 0
	s_barrier
; #define PG8_STAGE(bufoff, gbase, voff) do { _Pragma("unroll") for (int _i = 0; _i < 2; ++_i) \
;         __builtin_amdgcn_global_load_lds((const unsigned*)((const char*)(gbase) + (voff)[_i]), (LAS unsigned*)(lds + (bufoff) + ldsw + _i * 8192), 16, 0, 0); } while (0)
; #define PG8_LDA(dst, b, h) do { _Pragma("unroll") for (int m = 0; m < 4; ++m) _Pragma("unroll") for (int k = 0; k < 2; ++k) dst[m][k] = *(const LAS bf16x8*)(lds + PG8_SA(b, h) + aoffk[k] + m * 2048); } while (0)
; #define PG8_WAIT_V(n) asm volatile("s_waitcnt vmcnt(" #n ")" ::: "memory")
; #define PG8_WAIT_L(n) asm volatile("s_waitcnt lgkmcnt(" #n ")" ::: "memory")
; #define PG8_BAR __builtin_amdgcn_s_barrier()
; #define PG8_SCHED __builtin_amdgcn_sched_barrier(0)
;     __device__ __forceinline__ void mid(Acc& acc, const Unit& u, int s, int wr, int wc, int fr, int fq) const {
;         int lo = (wr * 4 + wc) * 8192 + (fq * 16 + fr) * 16; asm volatile("" : "+v"(lo));
;         const unsigned char* gp = gate + ((size_t)(u.pm * 48 + s * 16 + u.pn) << 16) + lo;
;         u32x4 G[8][2];
; #pragma unroll
;         for (int i = 0; i < 8; ++i) { G[i][0] = __builtin_nontemporal_load((const u32x4*)(gp + i * 1024)); G[i][1] = __builtin_nontemporal_load((const u32x4*)(gp + (1 << 20) + i * 1024)); }
; template <class Epi, class Sched, class GemmT>
; __device__ __forceinline__ void gemm_phase(LAS unsigned char* lds, const GemmT& g, const Sched& S, const Epi& E, const int wid) {
;     ...
;                 PG8_LDA(At, 1, 1); PG8_STAGE(PG8_SB(1, 0), b3, vB2); PG8_STAGE(PG8_SB(1, 1), b3 + hB2, vB2); PG8_STAGE(PG8_SA(1, 0), a3, vA2);
;                 PG8_WAIT_V(8); PG8_WAIT_L(0); PG8_BAR; PG8_MMA(1, 0, At, B0); PG8_MMA(1, 1, At, B1); PG8_BAR; PG8_SCHED;
;             }
;             if constexpr (NSEG > 1) { if (sgi + 1 < NSEG) E.mid(acc, cur, sgi, wr, wc, fr, fq); }
	s_add_i32 s48, s60, s68
	v_lshl_add_u64 v[202:203], v[202:203], 0, s[20:21]
	s_mov_b32 m0, s48
	ds_read_b128 v[138:141], v212 offset:49152
	ds_read_b128 v[176:179], v212 offset:51200
	ds_read_b128 v[180:183], v213 offset:49152
	ds_read_b128 v[184:187], v213 offset:51200
	ds_read_b128 v[216:219], v212 offset:53248
	ds_read_b128 v[220:223], v212 offset:55296
	ds_read_b128 v[224:227], v213 offset:53248
	ds_read_b128 v[230:233], v213 offset:55296
	global_load_lds_dwordx4 v[202:203], off sc1
	v_lshl_add_u64 v[202:203], v[238:239], 0, s[20:21]
	s_add_i32 m0, s48, 0x2000
	s_add_i32 s48, s61, s68
	global_load_lds_dwordx4 v[202:203], off sc1
	v_lshl_add_u64 v[202:203], v[240:241], 0, s[20:21]
	s_mov_b32 m0, s48
	v_lshl_add_u64 v[188:189], v[188:189], 0, s[20:21]
	global_load_lds_dwordx4 v[202:203], off sc1
	v_lshl_add_u64 v[202:203], v[242:243], 0, s[20:21]
	s_add_i32 m0, s48, 0x2000
	s_nop 0
	global_load_lds_dwordx4 v[202:203], off sc1
	s_mov_b32 m0, s54
	s_nop 0
	global_load_lds_dwordx4 v[188:189], off sc1
	v_lshl_add_u64 v[188:189], v[244:245], 0, s[20:21]
	s_mov_b32 m0, s55
	s_nop 0
	global_load_lds_dwordx4 v[188:189], off sc1
	s_waitcnt vmcnt(8)
	s_waitcnt lgkmcnt(0)
	s_barrier
	s_setprio 3
	s_waitcnt lgkmcnt(0)
	v_mfma_f32_16x16x32_bf16 v[62:65], v[144:147], v[138:141], v[62:65]
	v_mfma_f32_16x16x32_bf16 v[62:65], v[148:151], v[180:183], v[62:65]
	v_mfma_f32_16x16x32_bf16 v[58:61], v[156:159], v[180:183], v[58:61]
	v_mfma_f32_16x16x32_bf16 v[58:61], v[152:155], v[138:141], v[58:61]
	v_mfma_f32_16x16x32_bf16 v[42:45], v[152:155], v[176:179], v[42:45]
	v_mfma_f32_16x16x32_bf16 v[42:45], v[156:159], v[184:187], v[42:45]
	v_mfma_f32_16x16x32_bf16 v[46:49], v[148:151], v[184:187], v[46:49]
	v_mfma_f32_16x16x32_bf16 v[46:49], v[144:147], v[176:179], v[46:49]
	v_mfma_f32_16x16x32_bf16 v[30:33], v[144:147], v[216:219], v[30:33]
	v_mfma_f32_16x16x32_bf16 v[30:33], v[148:151], v[224:227], v[30:33]
	v_mfma_f32_16x16x32_bf16 v[22:25], v[156:159], v[224:227], v[22:25]
	v_mfma_f32_16x16x32_bf16 v[22:25], v[152:155], v[216:219], v[22:25]
	v_mfma_f32_16x16x32_bf16 v[6:9], v[152:155], v[220:223], v[6:9]
	v_mfma_f32_16x16x32_bf16 v[6:9], v[156:159], v[230:233], v[6:9]
	v_mfma_f32_16x16x32_bf16 v[14:17], v[148:151], v[230:233], v[14:17]
	v_mfma_f32_16x16x32_bf16 v[14:17], v[144:147], v[220:223], v[14:17]
	s_setprio 0
	s_setprio 3
	v_mfma_f32_16x16x32_bf16 v[54:57], v[160:163], v[138:141], v[54:57]
	v_mfma_f32_16x16x32_bf16 v[54:57], v[164:167], v[180:183], v[54:57]
	v_mfma_f32_16x16x32_bf16 v[50:53], v[172:175], v[180:183], v[50:53]
	v_mfma_f32_16x16x32_bf16 v[50:53], v[168:171], v[138:141], v[50:53]
	v_mfma_f32_16x16x32_bf16 v[34:37], v[168:171], v[176:179], v[34:37]
	v_mfma_f32_16x16x32_bf16 v[34:37], v[172:175], v[184:187], v[34:37]
	v_mfma_f32_16x16x32_bf16 v[38:41], v[164:167], v[184:187], v[38:41]
	v_mfma_f32_16x16x32_bf16 v[38:41], v[160:163], v[176:179], v[38:41]
	v_mfma_f32_16x16x32_bf16 v[26:29], v[160:163], v[216:219], v[26:29]
	v_mfma_f32_16x16x32_bf16 v[26:29], v[164:167], v[224:227], v[26:29]
	v_mfma_f32_16x16x32_bf16 v[18:21], v[172:175], v[224:227], v[18:21]
	v_mfma_f32_16x16x32_bf16 v[18:21], v[168:171], v[216:219], v[18:21]
	v_mfma_f32_16x16x32_bf16 v[2:5], v[168:171], v[220:223], v[2:5]
	v_mfma_f32_16x16x32_bf16 v[2:5], v[172:175], v[230:233], v[2:5]
	v_mfma_f32_16x16x32_bf16 v[10:13], v[164:167], v[230:233], v[10:13]
	v_mfma_f32_16x16x32_bf16 v[10:13], v[160:163], v[220:223], v[10:13]
	s_setprio 0
	s_barrier
	s_add_u32 s56, s56, 0x100
	s_addc_u32 s57, s57, 0
	s_cmp_ge_u32 s90, s42
	s_cbranch_scc0 .LBB0_764
	s_and_b64 vcc, exec, s[52:53]
	s_cbranch_vccz .LBB0_767
	s_lshl_b32 s42, s83, 4
	s_add_i32 s42, s82, s42
	s_ashr_i32 s43, s42, 31
	s_lshl_b64 s[42:43], s[42:43], 16
	v_mov_b32_e32 v130, v210
	s_add_u32 s42, s22, s42
	s_addc_u32 s43, s23, s43
	v_ashrrev_i32_e32 v131, 31, v130
	v_lshl_add_u64 v[130:131], s[42:43], 0, v[130:131]
	v_add_co_u32_e32 v132, vcc, s69, v130
	s_mov_b32 s42, 0x101000
	s_nop 0
	v_addc_co_u32_e32 v133, vcc, 0, v131, vcc
	global_load_dwordx4 v[186:189], v[130:131], off nt
	v_add_co_u32_e32 v134, vcc, s42, v130
	s_movk_i32 s42, 0x1000
	s_nop 0
	v_addc_co_u32_e32 v135, vcc, 0, v131, vcc
	global_load_dwordx4 v[216:219], v[134:135], off offset:-4096 nt
	global_load_dwordx4 v[178:181], v[130:131], off offset:1024 nt
	global_load_dwordx4 v[182:185], v[132:133], off offset:1024 nt
	global_load_dwordx4 v[170:173], v[130:131], off offset:2048 nt
	global_load_dwordx4 v[174:177], v[132:133], off offset:2048 nt
	global_load_dwordx4 v[162:165], v[130:131], off offset:3072 nt
	global_load_dwordx4 v[166:169], v[132:133], off offset:3072 nt
	v_add_co_u32_e32 v130, vcc, s42, v130
	s_waitcnt vmcnt(0)
;     __device__ __forceinline__ void mid(Acc& acc, const Unit& u, int s, int wr, int wc, int fr, int fq) const {
;         int lo = (wr * 4 + wc) * 8192 + (fq * 16 + fr) * 16; asm volatile("" : "+v"(lo));
;         const unsigned char* gp = gate + ((size_t)(u.pm * 48 + s * 16 + u.pn) << 16) + lo;
;         u32x4 G[8][2];
; #pragma unroll
;         for (int i = 0; i < 8; ++i) { G[i][0] = __builtin_nontemporal_load((const u32x4*)(gp + i * 1024)); G[i][1] = __builtin_nontemporal_load((const u32x4*)(gp + (1 << 20) + i * 1024)); }
; #pragma unroll
;         for (int i = 0; i < 8; ++i) { const int ai = i >> 2, m = i & 3;
; #pragma unroll
;             for (int bj = 0; bj < 2; ++bj) {
;                 const u32x4 ga = G[i][0], gb = G[i][1];
;                 const u32x2 wa = bj == 0 ? (u32x2){ga.x, ga.y} : (u32x2){ga.z, ga.w}, wb = bj == 0 ? (u32x2){gb.x, gb.y} : (u32x2){gb.z, gb.w};
;                 float fa[8], fb[8]; gate_unpack8(wa, fa); gate_unpack8(wb, fb);
; #pragma unroll
;                 for (int e = 0; e < 8; ++e) fa[e] = fa[e] * __builtin_amdgcn_rcpf(fb[e]);
;                 f32x4& v0 = acc[ai][bj][m][0]; f32x4& v1 = acc[ai][bj][m][1];
;                 v0[0] *= fa[0]; v0[1] *= fa[1]; v0[2] *= fa[2]; v0[3] *= fa[3]; v1[0] *= fa[4]; v1[1] *= fa[5]; v1[2] *= fa[6]; v1[3] *= fa[7]; }
	v_cvt_f32_ubyte0_e32 v0, v216
	v_addc_co_u32_e32 v131, vcc, 0, v131, vcc
	global_load_dwordx4 v[154:157], v[130:131], off nt
	global_load_dwordx4 v[158:161], v[134:135], off nt
	global_load_dwordx4 v[146:149], v[130:131], off offset:1024 nt
	global_load_dwordx4 v[150:153], v[134:135], off offset:1024 nt
	global_load_dwordx4 v[138:141], v[130:131], off offset:2048 nt
	global_load_dwordx4 v[142:145], v[134:135], off offset:2048 nt
	s_nop 0
	global_load_dwordx4 v[130:133], v[130:131], off offset:3072 nt
	s_nop 0
	global_load_dwordx4 v[134:137], v[134:135], off offset:3072 nt
	v_cvt_f32_ubyte1_e32 v203, v216
	v_cvt_f32_ubyte2_e32 v215, v216
	v_cvt_f32_ubyte3_e32 v220, v216
	v_cvt_f32_ubyte0_e32 v221, v217
	v_cvt_f32_ubyte1_e32 v222, v217
	v_cvt_f32_ubyte2_e32 v223, v217
	v_cvt_f32_ubyte3_e32 v224, v217
	v_rcp_iflag_f32_e32 v202, v0
	v_rcp_iflag_f32_e32 v203, v203
	v_rcp_iflag_f32_e32 v216, v215
	v_rcp_iflag_f32_e32 v217, v220
	v_rcp_iflag_f32_e32 v220, v221
	v_rcp_iflag_f32_e32 v221, v222
	v_rcp_iflag_f32_e32 v222, v223
	v_rcp_iflag_f32_e32 v223, v224
	v_cvt_f32_ubyte3_e32 v225, v186
	v_cvt_f32_ubyte2_e32 v224, v186
	v_cvt_f32_ubyte1_e32 v227, v186
	v_cvt_f32_ubyte0_e32 v226, v186
	v_pk_mul_f32 v[202:203], v[202:203], v[226:227]
	v_pk_mul_f32 v[216:217], v[216:217], v[224:225]
	v_pk_mul_f32 v[126:127], v[126:127], v[202:203]
	v_pk_mul_f32 v[128:129], v[128:129], v[216:217]
	v_cvt_f32_ubyte3_e32 v203, v187
	v_cvt_f32_ubyte2_e32 v202, v187
	v_cvt_f32_ubyte1_e32 v217, v187
	v_cvt_f32_ubyte0_e32 v216, v187
	v_pk_mul_f32 v[186:187], v[220:221], v[216:217]
	v_pk_mul_f32 v[202:203], v[222:223], v[202:203]
	v_pk_mul_f32 v[122:123], v[122:123], v[186:187]
	v_pk_mul_f32 v[124:125], v[124:125], v[202:203]
	v_cvt_f32_ubyte0_e32 v0, v218
	v_cvt_f32_ubyte1_e32 v186, v218
	v_cvt_f32_ubyte2_e32 v187, v218
	v_cvt_f32_ubyte3_e32 v202, v218
	v_cvt_f32_ubyte0_e32 v203, v219
	v_cvt_f32_ubyte1_e32 v215, v219
	v_cvt_f32_ubyte2_e32 v220, v219
	v_cvt_f32_ubyte3_e32 v221, v219
	v_rcp_iflag_f32_e32 v216, v0
	v_rcp_iflag_f32_e32 v217, v186
	v_rcp_iflag_f32_e32 v218, v187
	v_rcp_iflag_f32_e32 v219, v202
	v_rcp_iflag_f32_e32 v202, v203
	v_rcp_iflag_f32_e32 v203, v215
	v_rcp_iflag_f32_e32 v186, v220
	v_rcp_iflag_f32_e32 v187, v221
	v_cvt_f32_ubyte3_e32 v221, v188
	v_cvt_f32_ubyte2_e32 v220, v188
	v_cvt_f32_ubyte1_e32 v223, v188
	v_cvt_f32_ubyte0_e32 v222, v188
	v_pk_mul_f32 v[216:217], v[216:217], v[222:223]
	v_pk_mul_f32 v[218:219], v[218:219], v[220:221]
	v_pk_mul_f32 v[118:119], v[118:119], v[216:217]
	v_pk_mul_f32 v[120:121], v[120:121], v[218:219]
	v_cvt_f32_ubyte3_e32 v217, v189
	v_cvt_f32_ubyte2_e32 v216, v189
	v_cvt_f32_ubyte1_e32 v219, v189
	v_cvt_f32_ubyte0_e32 v218, v189
	v_pk_mul_f32 v[188:189], v[202:203], v[218:219]
	v_pk_mul_f32 v[186:187], v[186:187], v[216:217]
	v_pk_mul_f32 v[114:115], v[114:115], v[188:189]
	v_pk_mul_f32 v[116:117], v[116:117], v[186:187]
	v_cvt_f32_ubyte0_e32 v0, v182
	v_cvt_f32_ubyte1_e32 v186, v182
	v_cvt_f32_ubyte2_e32 v187, v182
	v_cvt_f32_ubyte3_e32 v188, v182
	v_cvt_f32_ubyte0_e32 v189, v183
	v_cvt_f32_ubyte1_e32 v202, v183
	v_cvt_f32_ubyte2_e32 v203, v183
	v_cvt_f32_ubyte3_e32 v215, v183
	v_rcp_iflag_f32_e32 v182, v0
	v_rcp_iflag_f32_e32 v183, v186
	v_rcp_iflag_f32_e32 v186, v187
	v_rcp_iflag_f32_e32 v187, v188
	v_rcp_iflag_f32_e32 v188, v189
	v_rcp_iflag_f32_e32 v189, v202
	v_rcp_iflag_f32_e32 v202, v203
	v_rcp_iflag_f32_e32 v203, v215
	v_cvt_f32_ubyte3_e32 v217, v178
	v_cvt_f32_ubyte2_e32 v216, v178
	v_cvt_f32_ubyte1_e32 v219, v178
	v_cvt_f32_ubyte0_e32 v218, v178
	v_pk_mul_f32 v[182:183], v[182:183], v[218:219]
	v_pk_mul_f32 v[186:187], v[186:187], v[216:217]
	v_pk_mul_f32 v[110:111], v[110:111], v[182:183]
	v_pk_mul_f32 v[112:113], v[112:113], v[186:187]
	v_cvt_f32_ubyte3_e32 v183, v179
	v_cvt_f32_ubyte2_e32 v182, v179
	v_cvt_f32_ubyte1_e32 v187, v179
	v_cvt_f32_ubyte0_e32 v186, v179
	v_pk_mul_f32 v[178:179], v[188:189], v[186:187]
	v_pk_mul_f32 v[182:183], v[202:203], v[182:183]
	v_pk_mul_f32 v[106:107], v[106:107], v[178:179]
	v_pk_mul_f32 v[108:109], v[108:109], v[182:183]
	v_cvt_f32_ubyte0_e32 v0, v184
	v_cvt_f32_ubyte1_e32 v179, v184
	v_cvt_f32_ubyte2_e32 v182, v184
	v_cvt_f32_ubyte3_e32 v183, v184
	v_rcp_iflag_f32_e32 v178, v0
	v_rcp_iflag_f32_e32 v179, v179
	v_rcp_iflag_f32_e32 v182, v182
	v_rcp_iflag_f32_e32 v183, v183
	v_cvt_f32_ubyte0_e32 v184, v185
	v_cvt_f32_ubyte1_e32 v186, v185
	v_cvt_f32_ubyte2_e32 v187, v185
	v_cvt_f32_ubyte3_e32 v188, v185
	v_rcp_iflag_f32_e32 v184, v184
	v_rcp_iflag_f32_e32 v185, v186
	v_rcp_iflag_f32_e32 v186, v187
	v_rcp_iflag_f32_e32 v187, v188
	v_cvt_f32_ubyte3_e32 v189, v180
	v_cvt_f32_ubyte2_e32 v188, v180
	v_cvt_f32_ubyte1_e32 v203, v180
	v_cvt_f32_ubyte0_e32 v202, v180
	v_pk_mul_f32 v[178:179], v[178:179], v[202:203]
	v_pk_mul_f32 v[182:183], v[182:183], v[188:189]
	v_pk_mul_f32 v[102:103], v[102:103], v[178:179]
	v_pk_mul_f32 v[104:105], v[104:105], v[182:183]
	v_cvt_f32_ubyte3_e32 v179, v181
	v_cvt_f32_ubyte2_e32 v178, v181
	v_cvt_f32_ubyte1_e32 v183, v181
	v_cvt_f32_ubyte0_e32 v182, v181
	v_pk_mul_f32 v[180:181], v[184:185], v[182:183]
	v_pk_mul_f32 v[178:179], v[186:187], v[178:179]
	v_pk_mul_f32 v[98:99], v[98:99], v[180:181]
	v_pk_mul_f32 v[100:101], v[100:101], v[178:179]
	v_cvt_f32_ubyte0_e32 v0, v174
	v_cvt_f32_ubyte1_e32 v178, v174
	v_cvt_f32_ubyte2_e32 v179, v174
	v_cvt_f32_ubyte3_e32 v180, v174
	v_cvt_f32_ubyte0_e32 v181, v175
	v_cvt_f32_ubyte1_e32 v182, v175
	v_cvt_f32_ubyte2_e32 v183, v175
	v_cvt_f32_ubyte3_e32 v184, v175
	v_rcp_iflag_f32_e32 v174, v0
	v_rcp_iflag_f32_e32 v175, v178
	v_rcp_iflag_f32_e32 v178, v179
	v_rcp_iflag_f32_e32 v179, v180
	v_rcp_iflag_f32_e32 v180, v181
;     __device__ __forceinline__ void mid(Acc& acc, const Unit& u, int s, int wr, int wc, int fr, int fq) const {
;     ...
;         for (int i = 0; i < 8; ++i) { const int ai = i >> 2, m = i & 3;
; #pragma unroll
;             for (int bj = 0; bj < 2; ++bj) {
;                 const u32x4 ga = G[i][0], gb = G[i][1];
;                 const u32x2 wa = bj == 0 ? (u32x2){ga.x, ga.y} : (u32x2){ga.z, ga.w}, wb = bj == 0 ? (u32x2){gb.x, gb.y} : (u32x2){gb.z, gb.w};
;                 float fa[8], fb[8]; gate_unpack8(wa, fa); gate_unpack8(wb, fb);
; #pragma unroll
;                 for (int e = 0; e < 8; ++e) fa[e] = fa[e] * __builtin_amdgcn_rcpf(fb[e]);
;                 f32x4& v0 = acc[ai][bj][m][0]; f32x4& v1 = acc[ai][bj][m][1];
;                 v0[0] *= fa[0]; v0[1] *= fa[1]; v0[2] *= fa[2]; v0[3] *= fa[3]; v1[0] *= fa[4]; v1[1] *= fa[5]; v1[2] *= fa[6]; v1[3] *= fa[7]; }
;             __builtin_amdgcn_sched_barrier(0); }
	v_rcp_iflag_f32_e32 v181, v182
	v_rcp_iflag_f32_e32 v182, v183
	v_rcp_iflag_f32_e32 v183, v184
	v_cvt_f32_ubyte3_e32 v185, v170
	v_cvt_f32_ubyte2_e32 v184, v170
	v_cvt_f32_ubyte1_e32 v187, v170
	v_cvt_f32_ubyte0_e32 v186, v170
	v_pk_mul_f32 v[174:175], v[174:175], v[186:187]
	v_pk_mul_f32 v[178:179], v[178:179], v[184:185]
	v_pk_mul_f32 v[94:95], v[94:95], v[174:175]
	v_pk_mul_f32 v[96:97], v[96:97], v[178:179]
	v_cvt_f32_ubyte3_e32 v175, v171
	v_cvt_f32_ubyte2_e32 v174, v171
	v_cvt_f32_ubyte1_e32 v179, v171
	v_cvt_f32_ubyte0_e32 v178, v171
	v_pk_mul_f32 v[170:171], v[180:181], v[178:179]
	v_pk_mul_f32 v[174:175], v[182:183], v[174:175]
	v_pk_mul_f32 v[90:91], v[90:91], v[170:171]
	v_pk_mul_f32 v[92:93], v[92:93], v[174:175]
	v_cvt_f32_ubyte0_e32 v0, v176
	v_cvt_f32_ubyte1_e32 v171, v176
	v_cvt_f32_ubyte2_e32 v174, v176
	v_cvt_f32_ubyte3_e32 v175, v176
	v_rcp_iflag_f32_e32 v170, v0
	v_rcp_iflag_f32_e32 v171, v171
	v_rcp_iflag_f32_e32 v174, v174
	v_rcp_iflag_f32_e32 v175, v175
	v_cvt_f32_ubyte0_e32 v176, v177
	v_cvt_f32_ubyte1_e32 v178, v177
	v_cvt_f32_ubyte2_e32 v179, v177
	v_cvt_f32_ubyte3_e32 v180, v177
	v_rcp_iflag_f32_e32 v176, v176
	v_rcp_iflag_f32_e32 v177, v178
	v_rcp_iflag_f32_e32 v178, v179
	v_rcp_iflag_f32_e32 v179, v180
	v_cvt_f32_ubyte3_e32 v181, v172
	v_cvt_f32_ubyte2_e32 v180, v172
	v_cvt_f32_ubyte1_e32 v183, v172
	v_cvt_f32_ubyte0_e32 v182, v172
	v_pk_mul_f32 v[170:171], v[170:171], v[182:183]
	v_pk_mul_f32 v[174:175], v[174:175], v[180:181]
	v_pk_mul_f32 v[86:87], v[86:87], v[170:171]
	v_pk_mul_f32 v[88:89], v[88:89], v[174:175]
	v_cvt_f32_ubyte3_e32 v171, v173
	v_cvt_f32_ubyte2_e32 v170, v173
	v_cvt_f32_ubyte1_e32 v175, v173
	v_cvt_f32_ubyte0_e32 v174, v173
	v_pk_mul_f32 v[172:173], v[176:177], v[174:175]
	v_pk_mul_f32 v[170:171], v[178:179], v[170:171]
	v_pk_mul_f32 v[82:83], v[82:83], v[172:173]
	v_pk_mul_f32 v[84:85], v[84:85], v[170:171]
	v_cvt_f32_ubyte0_e32 v0, v166
	v_cvt_f32_ubyte1_e32 v170, v166
	v_cvt_f32_ubyte2_e32 v171, v166
	v_cvt_f32_ubyte3_e32 v172, v166
	v_cvt_f32_ubyte0_e32 v173, v167
	v_cvt_f32_ubyte1_e32 v174, v167
	v_cvt_f32_ubyte2_e32 v175, v167
	v_cvt_f32_ubyte3_e32 v176, v167
	v_rcp_iflag_f32_e32 v166, v0
	v_rcp_iflag_f32_e32 v167, v170
	v_rcp_iflag_f32_e32 v170, v171
	v_rcp_iflag_f32_e32 v171, v172
	v_rcp_iflag_f32_e32 v172, v173
	v_rcp_iflag_f32_e32 v173, v174
	v_rcp_iflag_f32_e32 v174, v175
	v_rcp_iflag_f32_e32 v175, v176
	v_cvt_f32_ubyte3_e32 v177, v162
	v_cvt_f32_ubyte2_e32 v176, v162
	v_cvt_f32_ubyte1_e32 v179, v162
	v_cvt_f32_ubyte0_e32 v178, v162
	v_pk_mul_f32 v[166:167], v[166:167], v[178:179]
	v_pk_mul_f32 v[170:171], v[170:171], v[176:177]
	v_pk_mul_f32 v[78:79], v[78:79], v[166:167]
	v_pk_mul_f32 v[80:81], v[80:81], v[170:171]
	v_cvt_f32_ubyte3_e32 v167, v163
	v_cvt_f32_ubyte2_e32 v166, v163
	v_cvt_f32_ubyte1_e32 v171, v163
	v_cvt_f32_ubyte0_e32 v170, v163
	v_pk_mul_f32 v[162:163], v[172:173], v[170:171]
	v_pk_mul_f32 v[166:167], v[174:175], v[166:167]
	v_pk_mul_f32 v[74:75], v[74:75], v[162:163]
	v_pk_mul_f32 v[76:77], v[76:77], v[166:167]
	v_cvt_f32_ubyte0_e32 v0, v168
	v_cvt_f32_ubyte1_e32 v163, v168
	v_cvt_f32_ubyte2_e32 v166, v168
	v_cvt_f32_ubyte3_e32 v167, v168
	v_rcp_iflag_f32_e32 v162, v0
	v_rcp_iflag_f32_e32 v163, v163
	v_rcp_iflag_f32_e32 v166, v166
	v_rcp_iflag_f32_e32 v167, v167
	v_cvt_f32_ubyte0_e32 v168, v169
	v_cvt_f32_ubyte1_e32 v170, v169
	v_cvt_f32_ubyte2_e32 v171, v169
	v_cvt_f32_ubyte3_e32 v172, v169
	v_rcp_iflag_f32_e32 v168, v168
	v_rcp_iflag_f32_e32 v169, v170
	v_rcp_iflag_f32_e32 v170, v171
	v_rcp_iflag_f32_e32 v171, v172
	v_cvt_f32_ubyte3_e32 v173, v164
	v_cvt_f32_ubyte2_e32 v172, v164
	v_cvt_f32_ubyte1_e32 v175, v164
	v_cvt_f32_ubyte0_e32 v174, v164
	v_pk_mul_f32 v[162:163], v[162:163], v[174:175]
	v_pk_mul_f32 v[166:167], v[166:167], v[172:173]
	v_pk_mul_f32 v[70:71], v[70:71], v[162:163]
	v_pk_mul_f32 v[72:73], v[72:73], v[166:167]
	v_cvt_f32_ubyte3_e32 v163, v165
	v_cvt_f32_ubyte2_e32 v162, v165
	v_cvt_f32_ubyte1_e32 v167, v165
	v_cvt_f32_ubyte0_e32 v166, v165
	v_pk_mul_f32 v[164:165], v[168:169], v[166:167]
	v_pk_mul_f32 v[162:163], v[170:171], v[162:163]
	v_pk_mul_f32 v[66:67], v[66:67], v[164:165]
	v_pk_mul_f32 v[68:69], v[68:69], v[162:163]
	s_waitcnt vmcnt(6)
	v_cvt_f32_ubyte0_e32 v0, v158
	v_cvt_f32_ubyte1_e32 v162, v158
	v_cvt_f32_ubyte2_e32 v163, v158
	v_cvt_f32_ubyte3_e32 v164, v158
	v_cvt_f32_ubyte0_e32 v165, v159
	v_cvt_f32_ubyte1_e32 v166, v159
	v_cvt_f32_ubyte2_e32 v167, v159
	v_cvt_f32_ubyte3_e32 v168, v159
	v_rcp_iflag_f32_e32 v158, v0
	v_rcp_iflag_f32_e32 v159, v162
	v_rcp_iflag_f32_e32 v162, v163
	v_rcp_iflag_f32_e32 v163, v164
	v_rcp_iflag_f32_e32 v164, v165
	v_rcp_iflag_f32_e32 v165, v166
	v_rcp_iflag_f32_e32 v166, v167
	v_rcp_iflag_f32_e32 v167, v168
	v_cvt_f32_ubyte3_e32 v169, v154
	v_cvt_f32_ubyte2_e32 v168, v154
	v_cvt_f32_ubyte1_e32 v171, v154
	v_cvt_f32_ubyte0_e32 v170, v154
	v_pk_mul_f32 v[158:159], v[158:159], v[170:171]
	v_pk_mul_f32 v[162:163], v[162:163], v[168:169]
	v_pk_mul_f32 v[62:63], v[62:63], v[158:159]
	v_pk_mul_f32 v[64:65], v[64:65], v[162:163]
	v_cvt_f32_ubyte3_e32 v159, v155
	v_cvt_f32_ubyte2_e32 v158, v155
	v_cvt_f32_ubyte1_e32 v163, v155
	v_cvt_f32_ubyte0_e32 v162, v155
	v_pk_mul_f32 v[154:155], v[164:165], v[162:163]
	v_pk_mul_f32 v[158:159], v[166:167], v[158:159]
	v_pk_mul_f32 v[58:59], v[58:59], v[154:155]
	v_pk_mul_f32 v[60:61], v[60:61], v[158:159]
	v_cvt_f32_ubyte0_e32 v0, v160
	v_cvt_f32_ubyte1_e32 v155, v160
	v_cvt_f32_ubyte2_e32 v158, v160
	v_cvt_f32_ubyte3_e32 v159, v160
	v_rcp_iflag_f32_e32 v154, v0
	v_rcp_iflag_f32_e32 v155, v155
	v_rcp_iflag_f32_e32 v158, v158
	v_rcp_iflag_f32_e32 v159, v159
	v_cvt_f32_ubyte0_e32 v160, v161
	v_cvt_f32_ubyte1_e32 v162, v161
	v_cvt_f32_ubyte2_e32 v163, v161
	v_cvt_f32_ubyte3_e32 v164, v161
	v_rcp_iflag_f32_e32 v160, v160
	v_rcp_iflag_f32_e32 v161, v162
	v_rcp_iflag_f32_e32 v162, v163
	v_rcp_iflag_f32_e32 v163, v164
	v_cvt_f32_ubyte3_e32 v165, v156
	v_cvt_f32_ubyte2_e32 v164, v156
	v_cvt_f32_ubyte1_e32 v167, v156
	v_cvt_f32_ubyte0_e32 v166, v156
	v_pk_mul_f32 v[154:155], v[154:155], v[166:167]
	v_pk_mul_f32 v[158:159], v[158:159], v[164:165]
	v_pk_mul_f32 v[54:55], v[54:55], v[154:155]
	v_pk_mul_f32 v[56:57], v[56:57], v[158:159]
	v_cvt_f32_ubyte3_e32 v155, v157
	v_cvt_f32_ubyte2_e32 v154, v157
	v_cvt_f32_ubyte1_e32 v159, v157
	v_cvt_f32_ubyte0_e32 v158, v157
	v_pk_mul_f32 v[156:157], v[160:161], v[158:159]
	v_pk_mul_f32 v[154:155], v[162:163], v[154:155]
	v_pk_mul_f32 v[50:51], v[50:51], v[156:157]
	v_pk_mul_f32 v[52:53], v[52:53], v[154:155]
	s_waitcnt vmcnt(4)
;     __device__ __forceinline__ void mid(Acc& acc, const Unit& u, int s, int wr, int wc, int fr, int fq) const {
;     ...
;         for (int i = 0; i < 8; ++i) { const int ai = i >> 2, m = i & 3;
; #pragma unroll
;             for (int bj = 0; bj < 2; ++bj) {
;                 const u32x4 ga = G[i][0], gb = G[i][1];
;                 const u32x2 wa = bj == 0 ? (u32x2){ga.x, ga.y} : (u32x2){ga.z, ga.w}, wb = bj == 0 ? (u32x2){gb.x, gb.y} : (u32x2){gb.z, gb.w};
;                 float fa[8], fb[8]; gate_unpack8(wa, fa); gate_unpack8(wb, fb);
; #pragma unroll
;                 for (int e = 0; e < 8; ++e) fa[e] = fa[e] * __builtin_amdgcn_rcpf(fb[e]);
;                 f32x4& v0 = acc[ai][bj][m][0]; f32x4& v1 = acc[ai][bj][m][1];
;                 v0[0] *= fa[0]; v0[1] *= fa[1]; v0[2] *= fa[2]; v0[3] *= fa[3]; v1[0] *= fa[4]; v1[1] *= fa[5]; v1[2] *= fa[6]; v1[3] *= fa[7]; }
;             __builtin_amdgcn_sched_barrier(0); }
	v_cvt_f32_ubyte0_e32 v0, v150
	v_cvt_f32_ubyte1_e32 v154, v150
	v_cvt_f32_ubyte2_e32 v155, v150
	v_cvt_f32_ubyte3_e32 v156, v150
	v_cvt_f32_ubyte0_e32 v157, v151
	v_cvt_f32_ubyte1_e32 v158, v151
	v_cvt_f32_ubyte2_e32 v159, v151
	v_cvt_f32_ubyte3_e32 v160, v151
	v_rcp_iflag_f32_e32 v150, v0
	v_rcp_iflag_f32_e32 v151, v154
	v_rcp_iflag_f32_e32 v154, v155
	v_rcp_iflag_f32_e32 v155, v156
	v_rcp_iflag_f32_e32 v156, v157
	v_rcp_iflag_f32_e32 v157, v158
	v_rcp_iflag_f32_e32 v158, v159
	v_rcp_iflag_f32_e32 v159, v160
	v_cvt_f32_ubyte3_e32 v161, v146
	v_cvt_f32_ubyte2_e32 v160, v146
	v_cvt_f32_ubyte1_e32 v163, v146
	v_cvt_f32_ubyte0_e32 v162, v146
	v_pk_mul_f32 v[150:151], v[150:151], v[162:163]
	v_pk_mul_f32 v[154:155], v[154:155], v[160:161]
	v_pk_mul_f32 v[46:47], v[46:47], v[150:151]
	v_pk_mul_f32 v[48:49], v[48:49], v[154:155]
	v_cvt_f32_ubyte3_e32 v151, v147
	v_cvt_f32_ubyte2_e32 v150, v147
	v_cvt_f32_ubyte1_e32 v155, v147
	v_cvt_f32_ubyte0_e32 v154, v147
	v_pk_mul_f32 v[146:147], v[156:157], v[154:155]
	v_pk_mul_f32 v[150:151], v[158:159], v[150:151]
	v_pk_mul_f32 v[42:43], v[42:43], v[146:147]
	v_pk_mul_f32 v[44:45], v[44:45], v[150:151]
	v_cvt_f32_ubyte0_e32 v0, v152
	v_cvt_f32_ubyte1_e32 v147, v152
	v_cvt_f32_ubyte2_e32 v150, v152
	v_cvt_f32_ubyte3_e32 v151, v152
	v_rcp_iflag_f32_e32 v146, v0
	v_rcp_iflag_f32_e32 v147, v147
	v_rcp_iflag_f32_e32 v150, v150
	v_rcp_iflag_f32_e32 v151, v151
	v_cvt_f32_ubyte0_e32 v152, v153
	v_cvt_f32_ubyte1_e32 v154, v153
	v_cvt_f32_ubyte2_e32 v155, v153
	v_cvt_f32_ubyte3_e32 v156, v153
	v_rcp_iflag_f32_e32 v152, v152
	v_rcp_iflag_f32_e32 v153, v154
	v_rcp_iflag_f32_e32 v154, v155
	v_rcp_iflag_f32_e32 v155, v156
	v_cvt_f32_ubyte3_e32 v157, v148
	v_cvt_f32_ubyte2_e32 v156, v148
	v_cvt_f32_ubyte1_e32 v159, v148
	v_cvt_f32_ubyte0_e32 v158, v148
	v_pk_mul_f32 v[146:147], v[146:147], v[158:159]
	v_pk_mul_f32 v[150:151], v[150:151], v[156:157]
	v_pk_mul_f32 v[38:39], v[38:39], v[146:147]
	v_pk_mul_f32 v[40:41], v[40:41], v[150:151]
	v_cvt_f32_ubyte3_e32 v147, v149
	v_cvt_f32_ubyte2_e32 v146, v149
	v_cvt_f32_ubyte1_e32 v151, v149
	v_cvt_f32_ubyte0_e32 v150, v149
	v_pk_mul_f32 v[148:149], v[152:153], v[150:151]
	v_pk_mul_f32 v[146:147], v[154:155], v[146:147]
	v_pk_mul_f32 v[34:35], v[34:35], v[148:149]
	v_pk_mul_f32 v[36:37], v[36:37], v[146:147]
	s_waitcnt vmcnt(2)
	v_cvt_f32_ubyte0_e32 v0, v142
	v_cvt_f32_ubyte1_e32 v146, v142
	v_cvt_f32_ubyte2_e32 v147, v142
	v_cvt_f32_ubyte3_e32 v148, v142
	v_cvt_f32_ubyte0_e32 v149, v143
	v_cvt_f32_ubyte1_e32 v150, v143
	v_cvt_f32_ubyte2_e32 v151, v143
	v_cvt_f32_ubyte3_e32 v152, v143
	v_rcp_iflag_f32_e32 v142, v0
	v_rcp_iflag_f32_e32 v143, v146
	v_rcp_iflag_f32_e32 v146, v147
	v_rcp_iflag_f32_e32 v147, v148
	v_rcp_iflag_f32_e32 v148, v149
	v_rcp_iflag_f32_e32 v149, v150
	v_rcp_iflag_f32_e32 v150, v151
	v_rcp_iflag_f32_e32 v151, v152
	v_cvt_f32_ubyte3_e32 v153, v138
	v_cvt_f32_ubyte2_e32 v152, v138
	v_cvt_f32_ubyte1_e32 v155, v138
	v_cvt_f32_ubyte0_e32 v154, v138
	v_pk_mul_f32 v[142:143], v[142:143], v[154:155]
	v_pk_mul_f32 v[146:147], v[146:147], v[152:153]
	v_pk_mul_f32 v[30:31], v[30:31], v[142:143]
	v_pk_mul_f32 v[32:33], v[32:33], v[146:147]
	v_cvt_f32_ubyte3_e32 v143, v139
	v_cvt_f32_ubyte2_e32 v142, v139
	v_cvt_f32_ubyte1_e32 v147, v139
	v_cvt_f32_ubyte0_e32 v146, v139
	v_pk_mul_f32 v[138:139], v[148:149], v[146:147]
	v_pk_mul_f32 v[142:143], v[150:151], v[142:143]
	v_pk_mul_f32 v[22:23], v[22:23], v[138:139]
	v_pk_mul_f32 v[24:25], v[24:25], v[142:143]
	v_cvt_f32_ubyte0_e32 v0, v144
	v_cvt_f32_ubyte1_e32 v139, v144
	v_cvt_f32_ubyte2_e32 v142, v144
	v_cvt_f32_ubyte3_e32 v143, v144
	v_rcp_iflag_f32_e32 v138, v0
	v_rcp_iflag_f32_e32 v139, v139
	v_rcp_iflag_f32_e32 v142, v142
	v_rcp_iflag_f32_e32 v143, v143
	v_cvt_f32_ubyte0_e32 v144, v145
	v_cvt_f32_ubyte1_e32 v146, v145
	v_cvt_f32_ubyte2_e32 v147, v145
	v_cvt_f32_ubyte3_e32 v148, v145
	v_rcp_iflag_f32_e32 v144, v144
	v_rcp_iflag_f32_e32 v145, v146
	v_rcp_iflag_f32_e32 v146, v147
	v_rcp_iflag_f32_e32 v147, v148
	v_cvt_f32_ubyte3_e32 v149, v140
	v_cvt_f32_ubyte2_e32 v148, v140
	v_cvt_f32_ubyte1_e32 v151, v140
	v_cvt_f32_ubyte0_e32 v150, v140
	v_pk_mul_f32 v[138:139], v[138:139], v[150:151]
	v_pk_mul_f32 v[142:143], v[142:143], v[148:149]
	v_pk_mul_f32 v[26:27], v[26:27], v[138:139]
	v_pk_mul_f32 v[28:29], v[28:29], v[142:143]
	v_cvt_f32_ubyte3_e32 v139, v141
	v_cvt_f32_ubyte2_e32 v138, v141
	v_cvt_f32_ubyte1_e32 v143, v141
	v_cvt_f32_ubyte0_e32 v142, v141
	v_pk_mul_f32 v[140:141], v[144:145], v[142:143]
	v_pk_mul_f32 v[138:139], v[146:147], v[138:139]
	v_pk_mul_f32 v[18:19], v[18:19], v[140:141]
	v_pk_mul_f32 v[20:21], v[20:21], v[138:139]
	s_waitcnt vmcnt(0)
	v_cvt_f32_ubyte0_e32 v0, v134
	v_cvt_f32_ubyte1_e32 v138, v134
	v_cvt_f32_ubyte2_e32 v139, v134
	v_cvt_f32_ubyte3_e32 v140, v134
	v_cvt_f32_ubyte0_e32 v141, v135
	v_cvt_f32_ubyte1_e32 v142, v135
	v_cvt_f32_ubyte2_e32 v143, v135
	v_cvt_f32_ubyte3_e32 v144, v135
	v_rcp_iflag_f32_e32 v134, v0
	v_rcp_iflag_f32_e32 v135, v138
	v_rcp_iflag_f32_e32 v138, v139
	v_rcp_iflag_f32_e32 v139, v140
	v_rcp_iflag_f32_e32 v140, v141
	v_rcp_iflag_f32_e32 v141, v142
	v_rcp_iflag_f32_e32 v142, v143
	v_rcp_iflag_f32_e32 v143, v144
	v_cvt_f32_ubyte3_e32 v145, v130
	v_cvt_f32_ubyte2_e32 v144, v130
	v_cvt_f32_ubyte1_e32 v147, v130
	v_cvt_f32_ubyte0_e32 v146, v130
	v_pk_mul_f32 v[134:135], v[134:135], v[146:147]
	v_pk_mul_f32 v[138:139], v[138:139], v[144:145]
	v_pk_mul_f32 v[14:15], v[14:15], v[134:135]
	v_pk_mul_f32 v[16:17], v[16:17], v[138:139]
	v_cvt_f32_ubyte3_e32 v135, v131
	v_cvt_f32_ubyte2_e32 v134, v131
	v_cvt_f32_ubyte1_e32 v139, v131
	v_cvt_f32_ubyte0_e32 v138, v131
	v_pk_mul_f32 v[130:131], v[140:141], v[138:139]
	v_pk_mul_f32 v[134:135], v[142:143], v[134:135]
	v_pk_mul_f32 v[6:7], v[6:7], v[130:131]
	v_pk_mul_f32 v[8:9], v[8:9], v[134:135]
	v_cvt_f32_ubyte0_e32 v0, v136
	v_cvt_f32_ubyte1_e32 v131, v136
	v_cvt_f32_ubyte2_e32 v134, v136
	v_cvt_f32_ubyte3_e32 v135, v136
	v_rcp_iflag_f32_e32 v130, v0
	v_rcp_iflag_f32_e32 v131, v131
	v_rcp_iflag_f32_e32 v134, v134
	v_rcp_iflag_f32_e32 v135, v135
	v_cvt_f32_ubyte0_e32 v136, v137
	v_cvt_f32_ubyte1_e32 v138, v137
	v_cvt_f32_ubyte2_e32 v139, v137
	v_cvt_f32_ubyte3_e32 v140, v137
	v_rcp_iflag_f32_e32 v136, v136
	v_rcp_iflag_f32_e32 v137, v138
	v_rcp_iflag_f32_e32 v138, v139
	v_rcp_iflag_f32_e32 v139, v140
	v_cvt_f32_ubyte3_e32 v141, v132
	v_cvt_f32_ubyte2_e32 v140, v132
	v_cvt_f32_ubyte1_e32 v143, v132
	v_cvt_f32_ubyte0_e32 v142, v132
	v_pk_mul_f32 v[130:131], v[130:131], v[142:143]
	v_pk_mul_f32 v[134:135], v[134:135], v[140:141]
	v_pk_mul_f32 v[10:11], v[10:11], v[130:131]
	v_pk_mul_f32 v[12:13], v[12:13], v[134:135]
	v_cvt_f32_ubyte3_e32 v131, v133
	v_cvt_f32_ubyte2_e32 v130, v133
	v_cvt_f32_ubyte1_e32 v135, v133
	v_cvt_f32_ubyte0_e32 v134, v133
	v_pk_mul_f32 v[132:133], v[136:137], v[134:135]
	v_pk_mul_f32 v[130:131], v[138:139], v[130:131]
	v_pk_mul_f32 v[2:3], v[2:3], v[132:133]
	v_pk_mul_f32 v[4:5], v[4:5], v[130:131]

; #define PG8_STAGE(bufoff, gbase, voff) do { _Pragma("unroll") for (int _i = 0; _i < 2; ++_i) \
;         __builtin_amdgcn_global_load_lds((const unsigned*)((const char*)(gbase) + (voff)[_i]), (LAS unsigned*)(lds + (bufoff) + ldsw + _i * 8192), 16, 0, 0); } while (0)
; #define PG8_LDA(dst, b, h) do { _Pragma("unroll") for (int m = 0; m < 4; ++m) _Pragma("unroll") for (int k = 0; k < 2; ++k) dst[m][k] = *(const LAS bf16x8*)(lds + PG8_SA(b, h) + aoffk[k] + m * 2048); } while (0)
; #define PG8_LDB(dst, b, h) do { _Pragma("unroll") for (int n = 0; n < 2; ++n) _Pragma("unroll") for (int k = 0; k < 2; ++k) dst[n][k] = *(const LAS bf16x8*)(lds + PG8_SB(b, h) + boffk[k] + n * 2048); } while (0)
; #define PG8_WAIT_V(n) asm volatile("s_waitcnt vmcnt(" #n ")" ::: "memory")
; #define PG8_WAIT_L(n) asm volatile("s_waitcnt lgkmcnt(" #n ")" ::: "memory")
; #define PG8_BAR __builtin_amdgcn_s_barrier()
; #define PG8_SCHED __builtin_amdgcn_sched_barrier(0)
; template <class Epi, class Sched, class GemmT>
; __device__ __forceinline__ void gemm_phase(LAS unsigned char* lds, const GemmT& g, const Sched& S, const Epi& E, const int wid) {
;     ...
;                 const char* a1 = cA + (size_t)(t + 1) * kstep;
;                 const char* a2 = last ? ns.A : cA + (size_t)(t + 2) * kstep; const char* b2 = last ? ns.B : cB + (size_t)(t + 2) * kstep;
;                 const char* a3 = a2 + kstep; const char* b3 = b2 + kstep;
;                 unsigned vA2[2], vB2[2];
; #pragma unroll
;                 for (int i = 0; i < 2; ++i) { vA2[i] = last ? nvA[i] : voffA[i]; vB2[i] = last ? nvB[i] : voffB[i]; }
;                 const size_t hA2 = last ? nhA : hstepA, hB2 = last ? nhB : hstepB;
;                 PG8_LDB(B0, 0, 0); PG8_LDB(B1, 0, 1); PG8_SCHED; PG8_LDA(At, 0, 0); PG8_STAGE(PG8_SA(1, 1), a1 + hstepA, voffA);
;                 PG8_WAIT_V(8); PG8_WAIT_L(0); PG8_BAR; PG8_MMA(0, 0, At, B0); PG8_MMA(0, 1, At, B1); PG8_BAR; PG8_SCHED;
;                 PG8_LDA(At, 0, 1); PG8_STAGE(PG8_SB(0, 0), b2, vB2); PG8_STAGE(PG8_SB(0, 1), b2 + hB2, vB2); PG8_STAGE(PG8_SA(0, 0), a2, vA2);
.LBB0_846:
	ds_read_b128 v[128:131], v194
	ds_read_b128 v[132:135], v195
	ds_read_b128 v[136:139], v196
	ds_read_b128 v[140:143], v197
	ds_read_b128 v[144:147], v198
	ds_read_b128 v[148:151], v199
	ds_read_b128 v[152:155], v200
	ds_read_b128 v[168:171], v201
	s_add_u32 s44, s42, 0xfff00080
	s_addc_u32 s45, s43, -1
	s_cmp_eq_u32 s62, 60
	s_cselect_b32 s51, s37, s45
	s_cselect_b32 s50, s36, s44
	s_cselect_b32 s45, s59, s61
	s_cselect_b32 s44, s41, s60
	v_lshl_add_u64 v[188:189], s[42:43], 0, v[156:157]
	s_add_i32 m0, s14, 0xc000
	ds_read_b128 v[172:175], v202
	ds_read_b128 v[176:179], v202 offset:2048
	ds_read_b128 v[180:183], v203
	ds_read_b128 v[184:187], v203 offset:2048
	ds_read_b128 v[208:211], v202 offset:4096
	ds_read_b128 v[212:215], v202 offset:6144
	ds_read_b128 v[216:219], v203 offset:4096
	ds_read_b128 v[220:223], v203 offset:6144
	global_load_lds_dwordx4 v[188:189], off sc1
	v_lshl_add_u64 v[188:189], s[42:43], 0, v[160:161]
	s_add_i32 m0, s14, 0xe000
	s_nop 0
	global_load_lds_dwordx4 v[188:189], off sc1
	s_waitcnt vmcnt(8)
	s_waitcnt lgkmcnt(0)
	s_barrier
	s_setprio 3
	s_waitcnt lgkmcnt(0)
	v_mfma_f32_16x16x32_bf16 v[124:127], v[128:131], v[172:175], v[124:127]
	v_mfma_f32_16x16x32_bf16 v[124:127], v[132:135], v[180:183], v[124:127]
	v_mfma_f32_16x16x32_bf16 v[120:123], v[140:143], v[180:183], v[120:123]
	v_mfma_f32_16x16x32_bf16 v[120:123], v[136:139], v[172:175], v[120:123]
	v_mfma_f32_16x16x32_bf16 v[104:107], v[136:139], v[176:179], v[104:107]
	v_mfma_f32_16x16x32_bf16 v[104:107], v[140:143], v[184:187], v[104:107]
	v_mfma_f32_16x16x32_bf16 v[108:111], v[132:135], v[184:187], v[108:111]
	v_mfma_f32_16x16x32_bf16 v[108:111], v[128:131], v[176:179], v[108:111]
	v_mfma_f32_16x16x32_bf16 v[92:95], v[128:131], v[208:211], v[92:95]
	v_mfma_f32_16x16x32_bf16 v[92:95], v[132:135], v[216:219], v[92:95]
	v_mfma_f32_16x16x32_bf16 v[88:91], v[140:143], v[216:219], v[88:91]
	v_mfma_f32_16x16x32_bf16 v[88:91], v[136:139], v[208:211], v[88:91]
	v_mfma_f32_16x16x32_bf16 v[72:75], v[136:139], v[212:215], v[72:75]
	v_mfma_f32_16x16x32_bf16 v[72:75], v[140:143], v[220:223], v[72:75]
	v_mfma_f32_16x16x32_bf16 v[76:79], v[132:135], v[220:223], v[76:79]
	v_mfma_f32_16x16x32_bf16 v[76:79], v[128:131], v[212:215], v[76:79]
	s_setprio 0
	s_setprio 3
	v_mfma_f32_16x16x32_bf16 v[116:119], v[144:147], v[172:175], v[116:119]
	v_mfma_f32_16x16x32_bf16 v[116:119], v[148:151], v[180:183], v[116:119]
	v_mfma_f32_16x16x32_bf16 v[112:115], v[168:171], v[180:183], v[112:115]
	v_mfma_f32_16x16x32_bf16 v[112:115], v[152:155], v[172:175], v[112:115]
	v_mfma_f32_16x16x32_bf16 v[96:99], v[152:155], v[176:179], v[96:99]
	v_mfma_f32_16x16x32_bf16 v[96:99], v[168:171], v[184:187], v[96:99]
	v_mfma_f32_16x16x32_bf16 v[100:103], v[148:151], v[184:187], v[100:103]
	v_mfma_f32_16x16x32_bf16 v[100:103], v[144:147], v[176:179], v[100:103]
	v_mfma_f32_16x16x32_bf16 v[84:87], v[144:147], v[208:211], v[84:87]
	v_mfma_f32_16x16x32_bf16 v[84:87], v[148:151], v[216:219], v[84:87]
	v_mfma_f32_16x16x32_bf16 v[80:83], v[168:171], v[216:219], v[80:83]
	v_mfma_f32_16x16x32_bf16 v[80:83], v[152:155], v[208:211], v[80:83]
	v_mfma_f32_16x16x32_bf16 v[64:67], v[152:155], v[212:215], v[64:67]
	v_mfma_f32_16x16x32_bf16 v[64:67], v[168:171], v[220:223], v[64:67]
	v_mfma_f32_16x16x32_bf16 v[68:71], v[148:151], v[220:223], v[68:71]
	v_mfma_f32_16x16x32_bf16 v[68:71], v[144:147], v[212:215], v[68:71]
	s_setprio 0
	s_barrier
	s_add_i32 s48, s54, s68
	v_lshl_add_u64 v[188:189], s[44:45], 0, v[158:159]
	s_mov_b32 m0, s48
	ds_read_b128 v[172:175], v202 offset:16384
	ds_read_b128 v[176:179], v202 offset:18432
	ds_read_b128 v[180:183], v203 offset:16384
	ds_read_b128 v[184:187], v203 offset:18432
	ds_read_b128 v[208:211], v202 offset:20480
	ds_read_b128 v[212:215], v202 offset:22528
	ds_read_b128 v[216:219], v203 offset:20480
	ds_read_b128 v[220:223], v203 offset:22528
	global_load_lds_dwordx4 v[188:189], off sc1
	s_add_i32 m0, s48, 0x2000
	s_add_u32 s48, s44, 0x100000
	v_lshl_add_u64 v[224:225], s[44:45], 0, v[162:163]
	s_addc_u32 s49, s45, 0
	s_add_i32 s63, s55, s68
	global_load_lds_dwordx4 v[224:225], off sc1
	v_lshl_add_u64 v[226:227], s[48:49], 0, v[158:159]
	s_mov_b32 m0, s63
	v_lshl_add_u64 v[230:231], s[50:51], 0, v[160:161]
	global_load_lds_dwordx4 v[226:227], off sc1
	v_lshl_add_u64 v[226:227], s[48:49], 0, v[162:163]
	s_add_i32 m0, s63, 0x2000
	s_nop 0
	global_load_lds_dwordx4 v[226:227], off sc1
	v_lshl_add_u64 v[226:227], s[50:51], 0, v[156:157]
	s_mov_b32 m0, s14
	s_nop 0
	global_load_lds_dwordx4 v[226:227], off sc1
	s_mov_b32 m0, s15
	s_nop 0
	global_load_lds_dwordx4 v[230:231], off sc1
	s_waitcnt vmcnt(8)
	s_waitcnt lgkmcnt(0)
	s_barrier
; #define PG8_STAGE(bufoff, gbase, voff) do { _Pragma("unroll") for (int _i = 0; _i < 2; ++_i) \
;         __builtin_amdgcn_global_load_lds((const unsigned*)((const char*)(gbase) + (voff)[_i]), (LAS unsigned*)(lds + (bufoff) + ldsw + _i * 8192), 16, 0, 0); } while (0)
; #define PG8_LDA(dst, b, h) do { _Pragma("unroll") for (int m = 0; m < 4; ++m) _Pragma("unroll") for (int k = 0; k < 2; ++k) dst[m][k] = *(const LAS bf16x8*)(lds + PG8_SA(b, h) + aoffk[k] + m * 2048); } while (0)
; #define PG8_LDB(dst, b, h) do { _Pragma("unroll") for (int n = 0; n < 2; ++n) _Pragma("unroll") for (int k = 0; k < 2; ++k) dst[n][k] = *(const LAS bf16x8*)(lds + PG8_SB(b, h) + boffk[k] + n * 2048); } while (0)
; #define PG8_WAIT_V(n) asm volatile("s_waitcnt vmcnt(" #n ")" ::: "memory")
; #define PG8_WAIT_L(n) asm volatile("s_waitcnt lgkmcnt(" #n ")" ::: "memory")
; #define PG8_BAR __builtin_amdgcn_s_barrier()
; #define PG8_SCHED __builtin_amdgcn_sched_barrier(0)
; template <class Epi, class Sched, class GemmT>
; __device__ __forceinline__ void gemm_phase(LAS unsigned char* lds, const GemmT& g, const Sched& S, const Epi& E, const int wid) {
;     ...
;                 PG8_WAIT_V(8); PG8_WAIT_L(0); PG8_BAR; PG8_MMA(0, 0, At, B0); PG8_MMA(0, 1, At, B1); PG8_BAR; PG8_SCHED;
;                 PG8_LDA(At, 0, 1); PG8_STAGE(PG8_SB(0, 0), b2, vB2); PG8_STAGE(PG8_SB(0, 1), b2 + hB2, vB2); PG8_STAGE(PG8_SA(0, 0), a2, vA2);
;                 PG8_WAIT_V(8); PG8_WAIT_L(0); PG8_BAR; PG8_MMA(1, 0, At, B0); PG8_MMA(1, 1, At, B1); PG8_BAR; PG8_SCHED;
;                 PG8_LDB(B0, 1, 0); PG8_LDB(B1, 1, 1); PG8_SCHED; PG8_LDA(At, 1, 0); PG8_STAGE(PG8_SA(0, 1), a2 + hA2, vA2);
;                 PG8_WAIT_V(8); PG8_WAIT_L(0); PG8_BAR; PG8_MMA(0, 0, At, B0); PG8_MMA(0, 1, At, B1); PG8_BAR; PG8_SCHED;
	s_setprio 3
	s_waitcnt lgkmcnt(0)
	v_mfma_f32_16x16x32_bf16 v[52:55], v[128:131], v[172:175], v[52:55]
	v_mfma_f32_16x16x32_bf16 v[52:55], v[132:135], v[180:183], v[52:55]
	v_mfma_f32_16x16x32_bf16 v[48:51], v[140:143], v[180:183], v[48:51]
	v_mfma_f32_16x16x32_bf16 v[48:51], v[136:139], v[172:175], v[48:51]
	v_mfma_f32_16x16x32_bf16 v[32:35], v[136:139], v[176:179], v[32:35]
	v_mfma_f32_16x16x32_bf16 v[32:35], v[140:143], v[184:187], v[32:35]
	v_mfma_f32_16x16x32_bf16 v[36:39], v[132:135], v[184:187], v[36:39]
	v_mfma_f32_16x16x32_bf16 v[36:39], v[128:131], v[176:179], v[36:39]
	v_mfma_f32_16x16x32_bf16 v[20:23], v[128:131], v[208:211], v[20:23]
	v_mfma_f32_16x16x32_bf16 v[20:23], v[132:135], v[216:219], v[20:23]
	v_mfma_f32_16x16x32_bf16 v[16:19], v[140:143], v[216:219], v[16:19]
	v_mfma_f32_16x16x32_bf16 v[16:19], v[136:139], v[208:211], v[16:19]
	v_mfma_f32_16x16x32_bf16 v[0:3], v[136:139], v[212:215], v[0:3]
	v_mfma_f32_16x16x32_bf16 v[0:3], v[140:143], v[220:223], v[0:3]
	v_mfma_f32_16x16x32_bf16 v[4:7], v[132:135], v[220:223], v[4:7]
	v_mfma_f32_16x16x32_bf16 v[4:7], v[128:131], v[212:215], v[4:7]
	s_setprio 0
	s_setprio 3
	v_mfma_f32_16x16x32_bf16 v[60:63], v[144:147], v[172:175], v[60:63]
	v_mfma_f32_16x16x32_bf16 v[60:63], v[148:151], v[180:183], v[60:63]
	v_mfma_f32_16x16x32_bf16 v[56:59], v[168:171], v[180:183], v[56:59]
	v_mfma_f32_16x16x32_bf16 v[56:59], v[152:155], v[172:175], v[56:59]
	v_mfma_f32_16x16x32_bf16 v[40:43], v[152:155], v[176:179], v[40:43]
	v_mfma_f32_16x16x32_bf16 v[40:43], v[168:171], v[184:187], v[40:43]
	v_mfma_f32_16x16x32_bf16 v[44:47], v[148:151], v[184:187], v[44:47]
	v_mfma_f32_16x16x32_bf16 v[44:47], v[144:147], v[176:179], v[44:47]
	v_mfma_f32_16x16x32_bf16 v[28:31], v[144:147], v[208:211], v[28:31]
	v_mfma_f32_16x16x32_bf16 v[28:31], v[148:151], v[216:219], v[28:31]
	v_mfma_f32_16x16x32_bf16 v[24:27], v[168:171], v[216:219], v[24:27]
	v_mfma_f32_16x16x32_bf16 v[24:27], v[152:155], v[208:211], v[24:27]
	v_mfma_f32_16x16x32_bf16 v[8:11], v[152:155], v[212:215], v[8:11]
	v_mfma_f32_16x16x32_bf16 v[8:11], v[168:171], v[220:223], v[8:11]
	v_mfma_f32_16x16x32_bf16 v[12:15], v[148:151], v[220:223], v[12:15]
	v_mfma_f32_16x16x32_bf16 v[12:15], v[144:147], v[212:215], v[12:15]
	s_setprio 0
	s_barrier
	s_add_i32 s63, 0, 0x18000
	s_add_i32 s64, 0, 0x1c000
	v_add_u32_e32 v128, s63, v191
	v_add_u32_e32 v132, s63, v192
	v_add_u32_e32 v144, s64, v191
	v_add_u32_e32 v148, s64, v192
	ds_read_b128 v[128:131], v128
	ds_read_b128 v[132:135], v132
	ds_read_b128 v[136:139], v204
	ds_read_b128 v[140:143], v205
	ds_read_b128 v[144:147], v144
	ds_read_b128 v[148:151], v148
	ds_read_b128 v[152:155], v206
	ds_read_b128 v[168:171], v207
	s_add_u32 s48, s50, 0x100000
	s_addc_u32 s49, s51, 0
	s_mov_b32 m0, s22
	v_lshl_add_u64 v[232:233], s[48:49], 0, v[156:157]
	ds_read_b128 v[172:175], v202 offset:32768
	ds_read_b128 v[176:179], v202 offset:34816
	ds_read_b128 v[180:183], v203 offset:32768
	ds_read_b128 v[184:187], v203 offset:34816
	ds_read_b128 v[208:211], v202 offset:36864
	ds_read_b128 v[212:215], v202 offset:38912
	ds_read_b128 v[216:219], v203 offset:36864
	ds_read_b128 v[220:223], v203 offset:38912
	global_load_lds_dwordx4 v[232:233], off sc1
	v_lshl_add_u64 v[232:233], s[48:49], 0, v[160:161]
	s_mov_b32 m0, s23
	s_nop 0
	global_load_lds_dwordx4 v[232:233], off sc1
	s_waitcnt vmcnt(8)
	s_waitcnt lgkmcnt(0)
	s_barrier
	s_setprio 3
	s_waitcnt lgkmcnt(0)
	v_mfma_f32_16x16x32_bf16 v[124:127], v[128:131], v[172:175], v[124:127]
	v_mfma_f32_16x16x32_bf16 v[124:127], v[132:135], v[180:183], v[124:127]
	v_mfma_f32_16x16x32_bf16 v[120:123], v[140:143], v[180:183], v[120:123]
	v_mfma_f32_16x16x32_bf16 v[120:123], v[136:139], v[172:175], v[120:123]
	v_mfma_f32_16x16x32_bf16 v[104:107], v[136:139], v[176:179], v[104:107]
	v_mfma_f32_16x16x32_bf16 v[104:107], v[140:143], v[184:187], v[104:107]
	v_mfma_f32_16x16x32_bf16 v[108:111], v[132:135], v[184:187], v[108:111]
	v_mfma_f32_16x16x32_bf16 v[108:111], v[128:131], v[176:179], v[108:111]
	v_mfma_f32_16x16x32_bf16 v[92:95], v[128:131], v[208:211], v[92:95]
	v_mfma_f32_16x16x32_bf16 v[92:95], v[132:135], v[216:219], v[92:95]
	v_mfma_f32_16x16x32_bf16 v[88:91], v[140:143], v[216:219], v[88:91]
	v_mfma_f32_16x16x32_bf16 v[88:91], v[136:139], v[208:211], v[88:91]
	v_mfma_f32_16x16x32_bf16 v[72:75], v[136:139], v[212:215], v[72:75]
	v_mfma_f32_16x16x32_bf16 v[72:75], v[140:143], v[220:223], v[72:75]
	v_mfma_f32_16x16x32_bf16 v[76:79], v[132:135], v[220:223], v[76:79]
	v_mfma_f32_16x16x32_bf16 v[76:79], v[128:131], v[212:215], v[76:79]
	s_setprio 0
	s_setprio 3
	v_mfma_f32_16x16x32_bf16 v[116:119], v[144:147], v[172:175], v[116:119]
	v_mfma_f32_16x16x32_bf16 v[116:119], v[148:151], v[180:183], v[116:119]
	v_mfma_f32_16x16x32_bf16 v[112:115], v[168:171], v[180:183], v[112:115]
	v_mfma_f32_16x16x32_bf16 v[112:115], v[152:155], v[172:175], v[112:115]
	v_mfma_f32_16x16x32_bf16 v[96:99], v[152:155], v[176:179], v[96:99]
	v_mfma_f32_16x16x32_bf16 v[96:99], v[168:171], v[184:187], v[96:99]
	v_mfma_f32_16x16x32_bf16 v[100:103], v[148:151], v[184:187], v[100:103]
	v_mfma_f32_16x16x32_bf16 v[100:103], v[144:147], v[176:179], v[100:103]
	v_mfma_f32_16x16x32_bf16 v[84:87], v[144:147], v[208:211], v[84:87]
	v_mfma_f32_16x16x32_bf16 v[84:87], v[148:151], v[216:219], v[84:87]
	v_mfma_f32_16x16x32_bf16 v[80:83], v[168:171], v[216:219], v[80:83]
	v_mfma_f32_16x16x32_bf16 v[80:83], v[152:155], v[208:211], v[80:83]
	v_mfma_f32_16x16x32_bf16 v[64:67], v[152:155], v[212:215], v[64:67]
	v_mfma_f32_16x16x32_bf16 v[64:67], v[168:171], v[220:223], v[64:67]
	v_mfma_f32_16x16x32_bf16 v[68:71], v[148:151], v[220:223], v[68:71]
	v_mfma_f32_16x16x32_bf16 v[68:71], v[144:147], v[212:215], v[68:71]
	s_setprio 0
	s_barrier
; #define PG8_STAGE(bufoff, gbase, voff) do { _Pragma("unroll") for (int _i = 0; _i < 2; ++_i) \
;         __builtin_amdgcn_global_load_lds((const unsigned*)((const char*)(gbase) + (voff)[_i]), (LAS unsigned*)(lds + (bufoff) + ldsw + _i * 8192), 16, 0, 0); } while (0)
; #define PG8_LDA(dst, b, h) do { _Pragma("unroll") for (int m = 0; m < 4; ++m) _Pragma("unroll") for (int k = 0; k < 2; ++k) dst[m][k] = *(const LAS bf16x8*)(lds + PG8_SA(b, h) + aoffk[k] + m * 2048); } while (0)
; #define PG8_WAIT_V(n) asm volatile("s_waitcnt vmcnt(" #n ")" ::: "memory")
; #define PG8_WAIT_L(n) asm volatile("s_waitcnt lgkmcnt(" #n ")" ::: "memory")
; #define PG8_BAR __builtin_amdgcn_s_barrier()
; #define PG8_SCHED __builtin_amdgcn_sched_barrier(0)
; template <class Epi, class Sched, class GemmT>
; __device__ __forceinline__ void gemm_phase(LAS unsigned char* lds, const GemmT& g, const Sched& S, const Epi& E, const int wid) {
;     ...
;                 PG8_LDA(At, 1, 1); PG8_STAGE(PG8_SB(1, 0), b3, vB2); PG8_STAGE(PG8_SB(1, 1), b3 + hB2, vB2); PG8_STAGE(PG8_SA(1, 0), a3, vA2);
;                 PG8_WAIT_V(8); PG8_WAIT_L(0); PG8_BAR; PG8_MMA(1, 0, At, B0); PG8_MMA(1, 1, At, B1); PG8_BAR; PG8_SCHED;
;             }
;             if constexpr (NSEG > 1) { if (sgi + 1 < NSEG) E.mid(acc, cur, sgi, wr, wc, fr, fq); }
;             cs = ns; cA = ns.A; cB = ns.B; hstepA = nhA; hstepB = nhB;
; #pragma unroll
;             for (int i = 0; i < 2; ++i) { voffA[i] = nvA[i]; voffB[i] = nvB[i]; }
;         }
;         if (wr == 0) PG8_BAR;
	s_add_i32 s48, s63, s68
	v_lshl_add_u64 v[188:189], v[188:189], 0, s[18:19]
	s_mov_b32 m0, s48
	ds_read_b128 v[172:175], v202 offset:49152
	ds_read_b128 v[176:179], v202 offset:51200
	ds_read_b128 v[180:183], v203 offset:49152
	ds_read_b128 v[184:187], v203 offset:51200
	ds_read_b128 v[208:211], v202 offset:53248
	ds_read_b128 v[212:215], v202 offset:55296
	ds_read_b128 v[216:219], v203 offset:53248
	ds_read_b128 v[220:223], v203 offset:55296
	global_load_lds_dwordx4 v[188:189], off sc1
	s_add_i32 m0, s48, 0x2000
	s_add_u32 s44, s44, 0x100080
	v_lshl_add_u64 v[188:189], v[224:225], 0, s[18:19]
	s_addc_u32 s45, s45, 0
	s_add_i32 s48, s64, s68
	global_load_lds_dwordx4 v[188:189], off sc1
	v_lshl_add_u64 v[188:189], s[44:45], 0, v[158:159]
	s_mov_b32 m0, s48
	s_nop 0
	global_load_lds_dwordx4 v[188:189], off sc1
	v_lshl_add_u64 v[188:189], s[44:45], 0, v[162:163]
	s_add_i32 m0, s48, 0x2000
	s_nop 0
	global_load_lds_dwordx4 v[188:189], off sc1
	v_lshl_add_u64 v[188:189], v[226:227], 0, s[18:19]
	s_mov_b32 m0, s34
	s_nop 0
	global_load_lds_dwordx4 v[188:189], off sc1
	v_lshl_add_u64 v[188:189], v[230:231], 0, s[18:19]
	s_mov_b32 m0, s35
	s_nop 0
	global_load_lds_dwordx4 v[188:189], off sc1
	s_waitcnt vmcnt(8)
	s_waitcnt lgkmcnt(0)
	s_barrier
	s_setprio 3
	s_waitcnt lgkmcnt(0)
	v_mfma_f32_16x16x32_bf16 v[52:55], v[128:131], v[172:175], v[52:55]
	v_mfma_f32_16x16x32_bf16 v[52:55], v[132:135], v[180:183], v[52:55]
	v_mfma_f32_16x16x32_bf16 v[48:51], v[140:143], v[180:183], v[48:51]
	v_mfma_f32_16x16x32_bf16 v[48:51], v[136:139], v[172:175], v[48:51]
	v_mfma_f32_16x16x32_bf16 v[32:35], v[136:139], v[176:179], v[32:35]
	v_mfma_f32_16x16x32_bf16 v[32:35], v[140:143], v[184:187], v[32:35]
	v_mfma_f32_16x16x32_bf16 v[36:39], v[132:135], v[184:187], v[36:39]
	v_mfma_f32_16x16x32_bf16 v[36:39], v[128:131], v[176:179], v[36:39]
	v_mfma_f32_16x16x32_bf16 v[20:23], v[128:131], v[208:211], v[20:23]
	v_mfma_f32_16x16x32_bf16 v[20:23], v[132:135], v[216:219], v[20:23]
	v_mfma_f32_16x16x32_bf16 v[16:19], v[140:143], v[216:219], v[16:19]
	v_mfma_f32_16x16x32_bf16 v[16:19], v[136:139], v[208:211], v[16:19]
	v_mfma_f32_16x16x32_bf16 v[0:3], v[136:139], v[212:215], v[0:3]
	v_mfma_f32_16x16x32_bf16 v[0:3], v[140:143], v[220:223], v[0:3]
	v_mfma_f32_16x16x32_bf16 v[4:7], v[132:135], v[220:223], v[4:7]
	v_mfma_f32_16x16x32_bf16 v[4:7], v[128:131], v[212:215], v[4:7]
	s_setprio 0
	s_setprio 3
	v_mfma_f32_16x16x32_bf16 v[60:63], v[144:147], v[172:175], v[60:63]
	v_mfma_f32_16x16x32_bf16 v[60:63], v[148:151], v[180:183], v[60:63]
	v_mfma_f32_16x16x32_bf16 v[56:59], v[168:171], v[180:183], v[56:59]
	v_mfma_f32_16x16x32_bf16 v[56:59], v[152:155], v[172:175], v[56:59]
	v_mfma_f32_16x16x32_bf16 v[40:43], v[152:155], v[176:179], v[40:43]
	v_mfma_f32_16x16x32_bf16 v[40:43], v[168:171], v[184:187], v[40:43]
	v_mfma_f32_16x16x32_bf16 v[44:47], v[148:151], v[184:187], v[44:47]
	v_mfma_f32_16x16x32_bf16 v[44:47], v[144:147], v[176:179], v[44:47]
	v_mfma_f32_16x16x32_bf16 v[28:31], v[144:147], v[208:211], v[28:31]
	v_mfma_f32_16x16x32_bf16 v[28:31], v[148:151], v[216:219], v[28:31]
	v_mfma_f32_16x16x32_bf16 v[24:27], v[168:171], v[216:219], v[24:27]
	v_mfma_f32_16x16x32_bf16 v[24:27], v[152:155], v[208:211], v[24:27]
	v_mfma_f32_16x16x32_bf16 v[8:11], v[152:155], v[212:215], v[8:11]
	v_mfma_f32_16x16x32_bf16 v[8:11], v[168:171], v[220:223], v[8:11]
	v_mfma_f32_16x16x32_bf16 v[12:15], v[148:151], v[220:223], v[12:15]
	v_mfma_f32_16x16x32_bf16 v[12:15], v[144:147], v[212:215], v[12:15]
	s_setprio 0
	s_barrier
	s_add_i32 s62, s62, 2
	s_add_u32 s42, s42, 0x100
	s_addc_u32 s43, s43, 0
	s_add_u32 s60, s60, 0x100
	s_addc_u32 s61, s61, 0
	s_cmp_gt_u32 s62, 61
	s_cbranch_scc0 .LBB0_846
	s_and_b64 vcc, exec, s[20:21]
	s_cbranch_vccz .LBB0_849
	s_barrier

; #define PG8_STAGE(bufoff, gbase, voff) do { _Pragma("unroll") for (int _i = 0; _i < 2; ++_i) \
;         __builtin_amdgcn_global_load_lds((const unsigned*)((const char*)(gbase) + (voff)[_i]), (LAS unsigned*)(lds + (bufoff) + ldsw + _i * 8192), 16, 0, 0); } while (0)
; #define PG8_LDA(dst, b, h) do { _Pragma("unroll") for (int m = 0; m < 4; ++m) _Pragma("unroll") for (int k = 0; k < 2; ++k) dst[m][k] = *(const LAS bf16x8*)(lds + PG8_SA(b, h) + aoffk[k] + m * 2048); } while (0)
; #define PG8_LDB(dst, b, h) do { _Pragma("unroll") for (int n = 0; n < 2; ++n) _Pragma("unroll") for (int k = 0; k < 2; ++k) dst[n][k] = *(const LAS bf16x8*)(lds + PG8_SB(b, h) + boffk[k] + n * 2048); } while (0)
; #define PG8_WAIT_V(n) asm volatile("s_waitcnt vmcnt(" #n ")" ::: "memory")
; #define PG8_WAIT_L(n) asm volatile("s_waitcnt lgkmcnt(" #n ")" ::: "memory")
; #define PG8_BAR __builtin_amdgcn_s_barrier()
; #define PG8_SCHED __builtin_amdgcn_sched_barrier(0)
; template <class Epi, class Sched, class GemmT>
; __device__ __forceinline__ void gemm_phase(LAS unsigned char* lds, const GemmT& g, const Sched& S, const Epi& E, const int wid) {
;     ...
;                 const char* a1 = cA + (size_t)(t + 1) * kstep;
;                 const char* a2 = last ? ns.A : cA + (size_t)(t + 2) * kstep; const char* b2 = last ? ns.B : cB + (size_t)(t + 2) * kstep;
;                 const char* a3 = a2 + kstep; const char* b3 = b2 + kstep;
;                 unsigned vA2[2], vB2[2];
; #pragma unroll
;                 for (int i = 0; i < 2; ++i) { vA2[i] = last ? nvA[i] : voffA[i]; vB2[i] = last ? nvB[i] : voffB[i]; }
;                 const size_t hA2 = last ? nhA : hstepA, hB2 = last ? nhB : hstepB;
;                 PG8_LDB(B0, 0, 0); PG8_LDB(B1, 0, 1); PG8_SCHED; PG8_LDA(At, 0, 0); PG8_STAGE(PG8_SA(1, 1), a1 + hstepA, voffA);
;                 PG8_WAIT_V(8); PG8_WAIT_L(0); PG8_BAR; PG8_MMA(0, 0, At, B0); PG8_MMA(0, 1, At, B1); PG8_BAR; PG8_SCHED;
;                 PG8_LDA(At, 0, 1); PG8_STAGE(PG8_SB(0, 0), b2, vB2); PG8_STAGE(PG8_SB(0, 1), b2 + hB2, vB2); PG8_STAGE(PG8_SA(0, 0), a2, vA2);
.LBB0_936:
	ds_read_b128 v[12:15], v223
	ds_read_b128 v[132:135], v224
	ds_read_b128 v[136:139], v225
	ds_read_b128 v[140:143], v226
	ds_read_b128 v[144:147], v227
	ds_read_b128 v[148:151], v229
	ds_read_b128 v[152:155], v230
	ds_read_b128 v[156:159], v231
	s_add_u32 s66, s64, 0xfff00080
	s_addc_u32 s67, s65, -1
	s_cmp_eq_u32 s81, 60
	s_cselect_b32 s71, s57, s67
	s_cselect_b32 s70, s56, s66
	s_cselect_b32 s67, s77, s79
	s_cselect_b32 s66, s63, s78
	v_lshl_add_u64 v[204:205], s[64:65], 0, v[176:177]
	s_add_i32 m0, s14, 0xc000
	ds_read_b128 v[160:163], v232
	ds_read_b128 v[164:167], v232 offset:2048
	ds_read_b128 v[168:171], v233
	ds_read_b128 v[172:175], v233 offset:2048
	ds_read_b128 v[188:191], v232 offset:4096
	ds_read_b128 v[192:195], v232 offset:6144
	ds_read_b128 v[196:199], v233 offset:4096
	ds_read_b128 v[200:203], v233 offset:6144
	global_load_lds_dwordx4 v[204:205], off sc1
	v_lshl_add_u64 v[204:205], s[64:65], 0, v[180:181]
	s_add_i32 m0, s14, 0xe000
	s_nop 0
	global_load_lds_dwordx4 v[204:205], off sc1
	s_waitcnt vmcnt(8)
	s_waitcnt lgkmcnt(0)
	s_barrier
	s_setprio 3
	s_waitcnt lgkmcnt(0)
	v_mfma_f32_16x16x32_bf16 v[124:127], v[12:15], v[160:163], v[124:127]
	v_mfma_f32_16x16x32_bf16 v[124:127], v[132:135], v[168:171], v[124:127]
	v_mfma_f32_16x16x32_bf16 v[120:123], v[140:143], v[168:171], v[120:123]
	v_mfma_f32_16x16x32_bf16 v[120:123], v[136:139], v[160:163], v[120:123]
	v_mfma_f32_16x16x32_bf16 v[104:107], v[136:139], v[164:167], v[104:107]
	v_mfma_f32_16x16x32_bf16 v[104:107], v[140:143], v[172:175], v[104:107]
	v_mfma_f32_16x16x32_bf16 v[40:43], v[132:135], v[172:175], v[40:43]
	v_mfma_f32_16x16x32_bf16 v[40:43], v[12:15], v[164:167], v[40:43]
	v_mfma_f32_16x16x32_bf16 v[32:35], v[12:15], v[188:191], v[32:35]
	v_mfma_f32_16x16x32_bf16 v[32:35], v[132:135], v[196:199], v[32:35]
	v_mfma_f32_16x16x32_bf16 v[96:99], v[140:143], v[196:199], v[96:99]
	v_mfma_f32_16x16x32_bf16 v[96:99], v[136:139], v[188:191], v[96:99]
	v_mfma_f32_16x16x32_bf16 v[92:95], v[136:139], v[192:195], v[92:95]
	v_mfma_f32_16x16x32_bf16 v[92:95], v[140:143], v[200:203], v[92:95]
	v_mfma_f32_16x16x32_bf16 v[112:115], v[132:135], v[200:203], v[112:115]
	v_mfma_f32_16x16x32_bf16 v[112:115], v[12:15], v[192:195], v[112:115]
	s_setprio 0
	s_setprio 3
	v_mfma_f32_16x16x32_bf16 v[68:71], v[144:147], v[160:163], v[68:71]
	v_mfma_f32_16x16x32_bf16 v[68:71], v[148:151], v[168:171], v[68:71]
	v_mfma_f32_16x16x32_bf16 v[60:63], v[156:159], v[168:171], v[60:63]
	v_mfma_f32_16x16x32_bf16 v[60:63], v[152:155], v[160:163], v[60:63]
	v_mfma_f32_16x16x32_bf16 v[20:23], v[152:155], v[164:167], v[20:23]
	v_mfma_f32_16x16x32_bf16 v[20:23], v[156:159], v[172:175], v[20:23]
	v_mfma_f32_16x16x32_bf16 v[76:79], v[148:151], v[172:175], v[76:79]
	v_mfma_f32_16x16x32_bf16 v[76:79], v[144:147], v[164:167], v[76:79]
	v_mfma_f32_16x16x32_bf16 v[72:75], v[144:147], v[188:191], v[72:75]
	v_mfma_f32_16x16x32_bf16 v[72:75], v[148:151], v[196:199], v[72:75]
	v_mfma_f32_16x16x32_bf16 v[16:19], v[156:159], v[196:199], v[16:19]
	v_mfma_f32_16x16x32_bf16 v[16:19], v[152:155], v[188:191], v[16:19]
	v_mfma_f32_16x16x32_bf16 v[80:83], v[152:155], v[192:195], v[80:83]
	v_mfma_f32_16x16x32_bf16 v[80:83], v[156:159], v[200:203], v[80:83]
	v_mfma_f32_16x16x32_bf16 v[84:87], v[148:151], v[200:203], v[84:87]
	v_mfma_f32_16x16x32_bf16 v[84:87], v[144:147], v[192:195], v[84:87]
	s_setprio 0
	s_barrier
	s_add_i32 s80, s69, s68
	v_lshl_add_u64 v[204:205], s[66:67], 0, v[178:179]
	s_mov_b32 m0, s80
	ds_read_b128 v[160:163], v232 offset:16384
	ds_read_b128 v[164:167], v232 offset:18432
	ds_read_b128 v[168:171], v233 offset:16384
	ds_read_b128 v[172:175], v233 offset:18432
	ds_read_b128 v[188:191], v232 offset:20480
	ds_read_b128 v[192:195], v232 offset:22528
	ds_read_b128 v[196:199], v233 offset:20480
	ds_read_b128 v[200:203], v233 offset:22528
	global_load_lds_dwordx4 v[204:205], off sc1
	s_add_i32 m0, s80, 0x2000
	s_add_u32 s82, s66, 0x100000
	v_lshl_add_u64 v[206:207], s[66:67], 0, v[182:183]
	s_addc_u32 s83, s67, 0
	s_add_i32 s80, s72, s68
	global_load_lds_dwordx4 v[206:207], off sc1
	v_lshl_add_u64 v[240:241], s[82:83], 0, v[178:179]
	s_mov_b32 m0, s80
	v_lshl_add_u64 v[242:243], s[70:71], 0, v[180:181]
	global_load_lds_dwordx4 v[240:241], off sc1
	v_lshl_add_u64 v[240:241], s[82:83], 0, v[182:183]
	s_add_i32 m0, s80, 0x2000
	s_nop 0
	global_load_lds_dwordx4 v[240:241], off sc1
	v_lshl_add_u64 v[240:241], s[70:71], 0, v[176:177]
	s_mov_b32 m0, s14
	s_nop 0
	global_load_lds_dwordx4 v[240:241], off sc1
	s_mov_b32 m0, s15
	s_nop 0
	global_load_lds_dwordx4 v[242:243], off sc1
	s_waitcnt vmcnt(8)
	s_waitcnt lgkmcnt(0)
	s_barrier
; #define PG8_STAGE(bufoff, gbase, voff) do { _Pragma("unroll") for (int _i = 0; _i < 2; ++_i) \
;         __builtin_amdgcn_global_load_lds((const unsigned*)((const char*)(gbase) + (voff)[_i]), (LAS unsigned*)(lds + (bufoff) + ldsw + _i * 8192), 16, 0, 0); } while (0)
; #define PG8_LDA(dst, b, h) do { _Pragma("unroll") for (int m = 0; m < 4; ++m) _Pragma("unroll") for (int k = 0; k < 2; ++k) dst[m][k] = *(const LAS bf16x8*)(lds + PG8_SA(b, h) + aoffk[k] + m * 2048); } while (0)
; #define PG8_LDB(dst, b, h) do { _Pragma("unroll") for (int n = 0; n < 2; ++n) _Pragma("unroll") for (int k = 0; k < 2; ++k) dst[n][k] = *(const LAS bf16x8*)(lds + PG8_SB(b, h) + boffk[k] + n * 2048); } while (0)
; #define PG8_WAIT_V(n) asm volatile("s_waitcnt vmcnt(" #n ")" ::: "memory")
; #define PG8_WAIT_L(n) asm volatile("s_waitcnt lgkmcnt(" #n ")" ::: "memory")
; #define PG8_BAR __builtin_amdgcn_s_barrier()
; #define PG8_SCHED __builtin_amdgcn_sched_barrier(0)
; template <class Epi, class Sched, class GemmT>
; __device__ __forceinline__ void gemm_phase(LAS unsigned char* lds, const GemmT& g, const Sched& S, const Epi& E, const int wid) {
;     ...
;                 PG8_WAIT_V(8); PG8_WAIT_L(0); PG8_BAR; PG8_MMA(0, 0, At, B0); PG8_MMA(0, 1, At, B1); PG8_BAR; PG8_SCHED;
;                 PG8_LDA(At, 0, 1); PG8_STAGE(PG8_SB(0, 0), b2, vB2); PG8_STAGE(PG8_SB(0, 1), b2 + hB2, vB2); PG8_STAGE(PG8_SA(0, 0), a2, vA2);
;                 PG8_WAIT_V(8); PG8_WAIT_L(0); PG8_BAR; PG8_MMA(1, 0, At, B0); PG8_MMA(1, 1, At, B1); PG8_BAR; PG8_SCHED;
;                 PG8_LDB(B0, 1, 0); PG8_LDB(B1, 1, 1); PG8_SCHED; PG8_LDA(At, 1, 0); PG8_STAGE(PG8_SA(0, 1), a2 + hA2, vA2);
;                 PG8_WAIT_V(8); PG8_WAIT_L(0); PG8_BAR; PG8_MMA(0, 0, At, B0); PG8_MMA(0, 1, At, B1); PG8_BAR; PG8_SCHED;
	s_setprio 3
	s_waitcnt lgkmcnt(0)
	v_mfma_f32_16x16x32_bf16 v[56:59], v[12:15], v[160:163], v[56:59]
	v_mfma_f32_16x16x32_bf16 v[56:59], v[132:135], v[168:171], v[56:59]
	v_mfma_f32_16x16x32_bf16 v[108:111], v[136:139], v[160:163], v[108:111]
	v_mfma_f32_16x16x32_bf16 v[108:111], v[140:143], v[168:171], v[108:111]
	v_mfma_f32_16x16x32_bf16 v[36:39], v[12:15], v[164:167], v[36:39]
	v_mfma_f32_16x16x32_bf16 v[36:39], v[132:135], v[172:175], v[36:39]
	v_mfma_f32_16x16x32_bf16 v[100:103], v[136:139], v[164:167], v[100:103]
	v_mfma_f32_16x16x32_bf16 v[100:103], v[140:143], v[172:175], v[100:103]
	v_mfma_f32_16x16x32_bf16 v[28:31], v[12:15], v[188:191], v[28:31]
	v_mfma_f32_16x16x32_bf16 v[28:31], v[132:135], v[196:199], v[28:31]
	v_mfma_f32_16x16x32_bf16 v[88:91], v[136:139], v[188:191], v[88:91]
	v_mfma_f32_16x16x32_bf16 v[88:91], v[140:143], v[196:199], v[88:91]
	v_mfma_f32_16x16x32_bf16 v[24:27], v[136:139], v[192:195], v[24:27]
	v_mfma_f32_16x16x32_bf16 v[24:27], v[140:143], v[200:203], v[24:27]
	v_mfma_f32_16x16x32_bf16 v[12:15], v[12:15], v[192:195], v[64:67]
	v_mfma_f32_16x16x32_bf16 v[12:15], v[132:135], v[200:203], v[12:15]
	s_setprio 0
	s_setprio 3
	v_mfma_f32_16x16x32_bf16 v[64:67], v[144:147], v[192:195], v[116:119]
	v_mfma_f32_16x16x32_bf16 v[116:119], v[148:151], v[200:203], v[64:67]
	v_mfma_f32_16x16x32_bf16 v[44:47], v[144:147], v[160:163], v[44:47]
	v_mfma_f32_16x16x32_bf16 v[44:47], v[148:151], v[168:171], v[44:47]
	v_mfma_f32_16x16x32_bf16 v[0:3], v[152:155], v[160:163], v[0:3]
	v_mfma_f32_16x16x32_bf16 v[0:3], v[156:159], v[168:171], v[0:3]
	v_mfma_f32_16x16x32_bf16 v[48:51], v[144:147], v[164:167], v[48:51]
	v_mfma_f32_16x16x32_bf16 v[48:51], v[148:151], v[172:175], v[48:51]
	v_mfma_f32_16x16x32_bf16 v[4:7], v[152:155], v[164:167], v[4:7]
	v_mfma_f32_16x16x32_bf16 v[4:7], v[156:159], v[172:175], v[4:7]
	v_mfma_f32_16x16x32_bf16 v[64:67], v[152:155], v[192:195], v[128:131]
	v_mfma_f32_16x16x32_bf16 v[128:131], v[156:159], v[200:203], v[64:67]
	v_mfma_f32_16x16x32_bf16 v[52:55], v[144:147], v[188:191], v[52:55]
	v_mfma_f32_16x16x32_bf16 v[52:55], v[148:151], v[196:199], v[52:55]
	v_mfma_f32_16x16x32_bf16 v[8:11], v[152:155], v[188:191], v[8:11]
	v_mfma_f32_16x16x32_bf16 v[8:11], v[156:159], v[196:199], v[8:11]
	s_setprio 0
	s_barrier
	s_add_i32 s80, 0, 0x18000
	s_add_i32 s82, 0, 0x1c000
	v_add_u32_e32 v64, s80, v210
	v_add_u32_e32 v132, s80, v211
	v_add_u32_e32 v144, s82, v210
	v_add_u32_e32 v148, s82, v211
	ds_read_b128 v[64:67], v64
	ds_read_b128 v[132:135], v132
	ds_read_b128 v[136:139], v234
	ds_read_b128 v[140:143], v235
	ds_read_b128 v[144:147], v144
	ds_read_b128 v[148:151], v148
	ds_read_b128 v[152:155], v236
	ds_read_b128 v[156:159], v237
	s_add_u32 s70, s70, 0x100000
	s_addc_u32 s71, s71, 0
	s_mov_b32 m0, s23
	v_lshl_add_u64 v[244:245], s[70:71], 0, v[176:177]
	ds_read_b128 v[160:163], v232 offset:32768
	ds_read_b128 v[164:167], v232 offset:34816
	ds_read_b128 v[168:171], v233 offset:32768
	ds_read_b128 v[172:175], v233 offset:34816
	ds_read_b128 v[188:191], v232 offset:36864
	ds_read_b128 v[192:195], v232 offset:38912
	ds_read_b128 v[196:199], v233 offset:36864
	ds_read_b128 v[200:203], v233 offset:38912
	global_load_lds_dwordx4 v[244:245], off sc1
	v_lshl_add_u64 v[244:245], s[70:71], 0, v[180:181]
	s_mov_b32 m0, s34
	s_nop 0
	global_load_lds_dwordx4 v[244:245], off sc1
	s_waitcnt vmcnt(8)
	s_waitcnt lgkmcnt(0)
	s_barrier
	s_setprio 3
	s_waitcnt lgkmcnt(0)
	v_mfma_f32_16x16x32_bf16 v[124:127], v[64:67], v[160:163], v[124:127]
	v_mfma_f32_16x16x32_bf16 v[124:127], v[132:135], v[168:171], v[124:127]
	v_mfma_f32_16x16x32_bf16 v[120:123], v[140:143], v[168:171], v[120:123]
	v_mfma_f32_16x16x32_bf16 v[120:123], v[136:139], v[160:163], v[120:123]
	v_mfma_f32_16x16x32_bf16 v[104:107], v[136:139], v[164:167], v[104:107]
	v_mfma_f32_16x16x32_bf16 v[104:107], v[140:143], v[172:175], v[104:107]
	v_mfma_f32_16x16x32_bf16 v[40:43], v[132:135], v[172:175], v[40:43]
	v_mfma_f32_16x16x32_bf16 v[40:43], v[64:67], v[164:167], v[40:43]
	v_mfma_f32_16x16x32_bf16 v[32:35], v[64:67], v[188:191], v[32:35]
	v_mfma_f32_16x16x32_bf16 v[32:35], v[132:135], v[196:199], v[32:35]
	v_mfma_f32_16x16x32_bf16 v[96:99], v[140:143], v[196:199], v[96:99]
	v_mfma_f32_16x16x32_bf16 v[96:99], v[136:139], v[188:191], v[96:99]
	v_mfma_f32_16x16x32_bf16 v[92:95], v[136:139], v[192:195], v[92:95]
	v_mfma_f32_16x16x32_bf16 v[92:95], v[140:143], v[200:203], v[92:95]
	v_mfma_f32_16x16x32_bf16 v[112:115], v[132:135], v[200:203], v[112:115]
	v_mfma_f32_16x16x32_bf16 v[112:115], v[64:67], v[192:195], v[112:115]
	s_setprio 0
	s_setprio 3
	v_mfma_f32_16x16x32_bf16 v[68:71], v[144:147], v[160:163], v[68:71]
	v_mfma_f32_16x16x32_bf16 v[68:71], v[148:151], v[168:171], v[68:71]
	v_mfma_f32_16x16x32_bf16 v[60:63], v[156:159], v[168:171], v[60:63]
	v_mfma_f32_16x16x32_bf16 v[60:63], v[152:155], v[160:163], v[60:63]
	v_mfma_f32_16x16x32_bf16 v[20:23], v[152:155], v[164:167], v[20:23]
	v_mfma_f32_16x16x32_bf16 v[20:23], v[156:159], v[172:175], v[20:23]
	v_mfma_f32_16x16x32_bf16 v[76:79], v[148:151], v[172:175], v[76:79]
	v_mfma_f32_16x16x32_bf16 v[76:79], v[144:147], v[164:167], v[76:79]
	v_mfma_f32_16x16x32_bf16 v[72:75], v[144:147], v[188:191], v[72:75]
	v_mfma_f32_16x16x32_bf16 v[72:75], v[148:151], v[196:199], v[72:75]
	v_mfma_f32_16x16x32_bf16 v[16:19], v[156:159], v[196:199], v[16:19]
	v_mfma_f32_16x16x32_bf16 v[16:19], v[152:155], v[188:191], v[16:19]
	v_mfma_f32_16x16x32_bf16 v[80:83], v[152:155], v[192:195], v[80:83]
	v_mfma_f32_16x16x32_bf16 v[80:83], v[156:159], v[200:203], v[80:83]
	v_mfma_f32_16x16x32_bf16 v[84:87], v[148:151], v[200:203], v[84:87]
	v_mfma_f32_16x16x32_bf16 v[84:87], v[144:147], v[192:195], v[84:87]
	s_setprio 0
	s_barrier
; #define PG8_STAGE(bufoff, gbase, voff) do { _Pragma("unroll") for (int _i = 0; _i < 2; ++_i) \
;         __builtin_amdgcn_global_load_lds((const unsigned*)((const char*)(gbase) + (voff)[_i]), (LAS unsigned*)(lds + (bufoff) + ldsw + _i * 8192), 16, 0, 0); } while (0)
; #define PG8_LDA(dst, b, h) do { _Pragma("unroll") for (int m = 0; m < 4; ++m) _Pragma("unroll") for (int k = 0; k < 2; ++k) dst[m][k] = *(const LAS bf16x8*)(lds + PG8_SA(b, h) + aoffk[k] + m * 2048); } while (0)
; #define PG8_WAIT_V(n) asm volatile("s_waitcnt vmcnt(" #n ")" ::: "memory")
; #define PG8_WAIT_L(n) asm volatile("s_waitcnt lgkmcnt(" #n ")" ::: "memory")
; #define PG8_BAR __builtin_amdgcn_s_barrier()
; #define PG8_SCHED __builtin_amdgcn_sched_barrier(0)
; template <class Epi, class Sched, class GemmT>
; __device__ __forceinline__ void gemm_phase(LAS unsigned char* lds, const GemmT& g, const Sched& S, const Epi& E, const int wid) {
;     ...
;                 PG8_LDA(At, 1, 1); PG8_STAGE(PG8_SB(1, 0), b3, vB2); PG8_STAGE(PG8_SB(1, 1), b3 + hB2, vB2); PG8_STAGE(PG8_SA(1, 0), a3, vA2);
;                 PG8_WAIT_V(8); PG8_WAIT_L(0); PG8_BAR; PG8_MMA(1, 0, At, B0); PG8_MMA(1, 1, At, B1); PG8_BAR; PG8_SCHED;
;             }
	s_add_i32 s70, s80, s68
	v_lshl_add_u64 v[204:205], v[204:205], 0, s[38:39]
	s_mov_b32 m0, s70
	ds_read_b128 v[160:163], v232 offset:49152
	ds_read_b128 v[164:167], v232 offset:51200
	ds_read_b128 v[168:171], v233 offset:49152
	ds_read_b128 v[172:175], v233 offset:51200
	ds_read_b128 v[188:191], v232 offset:53248
	ds_read_b128 v[192:195], v232 offset:55296
	ds_read_b128 v[196:199], v233 offset:53248
	ds_read_b128 v[200:203], v233 offset:55296
	global_load_lds_dwordx4 v[204:205], off sc1
	s_add_i32 m0, s70, 0x2000
	s_add_u32 s66, s66, 0x100080
	v_lshl_add_u64 v[204:205], v[206:207], 0, s[38:39]
	s_addc_u32 s67, s67, 0
	s_add_i32 s70, s82, s68
	global_load_lds_dwordx4 v[204:205], off sc1
	v_lshl_add_u64 v[204:205], s[66:67], 0, v[178:179]
	s_mov_b32 m0, s70
	s_nop 0
	global_load_lds_dwordx4 v[204:205], off sc1
	v_lshl_add_u64 v[204:205], s[66:67], 0, v[182:183]
	s_add_i32 m0, s70, 0x2000
	s_nop 0
	global_load_lds_dwordx4 v[204:205], off sc1
	v_lshl_add_u64 v[204:205], v[240:241], 0, s[38:39]
	s_mov_b32 m0, s54
	s_nop 0
	global_load_lds_dwordx4 v[204:205], off sc1
	v_lshl_add_u64 v[204:205], v[242:243], 0, s[38:39]
	s_mov_b32 m0, s55
	s_nop 0
	global_load_lds_dwordx4 v[204:205], off sc1
	s_waitcnt vmcnt(8)
	s_waitcnt lgkmcnt(0)
	s_barrier
	s_setprio 3
	s_waitcnt lgkmcnt(0)
	v_mfma_f32_16x16x32_bf16 v[12:15], v[64:67], v[192:195], v[12:15]
	v_mfma_f32_16x16x32_bf16 v[56:59], v[64:67], v[160:163], v[56:59]
	v_mfma_f32_16x16x32_bf16 v[56:59], v[132:135], v[168:171], v[56:59]
	v_mfma_f32_16x16x32_bf16 v[108:111], v[136:139], v[160:163], v[108:111]
	v_mfma_f32_16x16x32_bf16 v[108:111], v[140:143], v[168:171], v[108:111]
	v_mfma_f32_16x16x32_bf16 v[36:39], v[64:67], v[164:167], v[36:39]
	v_mfma_f32_16x16x32_bf16 v[36:39], v[132:135], v[172:175], v[36:39]
	v_mfma_f32_16x16x32_bf16 v[100:103], v[136:139], v[164:167], v[100:103]
	v_mfma_f32_16x16x32_bf16 v[100:103], v[140:143], v[172:175], v[100:103]
	v_mfma_f32_16x16x32_bf16 v[28:31], v[64:67], v[188:191], v[28:31]
	v_mfma_f32_16x16x32_bf16 v[28:31], v[132:135], v[196:199], v[28:31]
	v_mfma_f32_16x16x32_bf16 v[88:91], v[136:139], v[188:191], v[88:91]
	v_mfma_f32_16x16x32_bf16 v[88:91], v[140:143], v[196:199], v[88:91]
	v_mfma_f32_16x16x32_bf16 v[64:67], v[132:135], v[200:203], v[12:15]
	v_mfma_f32_16x16x32_bf16 v[12:15], v[136:139], v[192:195], v[24:27]
	v_mfma_f32_16x16x32_bf16 v[24:27], v[140:143], v[200:203], v[12:15]
	s_setprio 0
	s_setprio 3
	v_mfma_f32_16x16x32_bf16 v[12:15], v[144:147], v[160:163], v[44:47]
	v_mfma_f32_16x16x32_bf16 v[44:47], v[148:151], v[168:171], v[12:15]
	v_mfma_f32_16x16x32_bf16 v[0:3], v[152:155], v[160:163], v[0:3]
	v_mfma_f32_16x16x32_bf16 v[0:3], v[156:159], v[168:171], v[0:3]
	v_mfma_f32_16x16x32_bf16 v[4:7], v[152:155], v[164:167], v[4:7]
	v_mfma_f32_16x16x32_bf16 v[4:7], v[156:159], v[172:175], v[4:7]
	v_mfma_f32_16x16x32_bf16 v[12:15], v[144:147], v[164:167], v[48:51]
	v_mfma_f32_16x16x32_bf16 v[48:51], v[148:151], v[172:175], v[12:15]
	v_mfma_f32_16x16x32_bf16 v[8:11], v[152:155], v[188:191], v[8:11]
	v_mfma_f32_16x16x32_bf16 v[8:11], v[156:159], v[196:199], v[8:11]
	v_mfma_f32_16x16x32_bf16 v[12:15], v[144:147], v[188:191], v[52:55]
	v_mfma_f32_16x16x32_bf16 v[52:55], v[148:151], v[196:199], v[12:15]
	v_mfma_f32_16x16x32_bf16 v[12:15], v[144:147], v[192:195], v[116:119]
	v_mfma_f32_16x16x32_bf16 v[116:119], v[148:151], v[200:203], v[12:15]
	v_mfma_f32_16x16x32_bf16 v[12:15], v[152:155], v[192:195], v[128:131]
	v_mfma_f32_16x16x32_bf16 v[128:131], v[156:159], v[200:203], v[12:15]
	s_setprio 0
	s_barrier
	s_add_i32 s81, s81, 2
	s_add_u32 s64, s64, 0x100
	s_addc_u32 s65, s65, 0
	s_add_u32 s78, s78, 0x100
	s_addc_u32 s79, s79, 0
	s_cmp_gt_u32 s81, 61
	s_cbranch_scc0 .LBB0_936
	s_and_b64 vcc, exec, s[40:41]
	s_cbranch_vccz .LBB0_939
	s_barrier

; #define PG8_STAGE(bufoff, gbase, voff) do { _Pragma("unroll") for (int _i = 0; _i < 2; ++_i) \
;         __builtin_amdgcn_global_load_lds((const unsigned*)((const char*)(gbase) + (voff)[_i]), (LAS unsigned*)(lds + (bufoff) + ldsw + _i * 8192), 16, 0, 0); } while (0)
; #define PG8_LDA(dst, b, h) do { _Pragma("unroll") for (int m = 0; m < 4; ++m) _Pragma("unroll") for (int k = 0; k < 2; ++k) dst[m][k] = *(const LAS bf16x8*)(lds + PG8_SA(b, h) + aoffk[k] + m * 2048); } while (0)
; #define PG8_LDB(dst, b, h) do { _Pragma("unroll") for (int n = 0; n < 2; ++n) _Pragma("unroll") for (int k = 0; k < 2; ++k) dst[n][k] = *(const LAS bf16x8*)(lds + PG8_SB(b, h) + boffk[k] + n * 2048); } while (0)
; #define PG8_WAIT_V(n) asm volatile("s_waitcnt vmcnt(" #n ")" ::: "memory")
; #define PG8_WAIT_L(n) asm volatile("s_waitcnt lgkmcnt(" #n ")" ::: "memory")
; #define PG8_BAR __builtin_amdgcn_s_barrier()
; #define PG8_SCHED __builtin_amdgcn_sched_barrier(0)
; template <class Epi, class Sched, class GemmT>
; __device__ __forceinline__ void gemm_phase(LAS unsigned char* lds, const GemmT& g, const Sched& S, const Epi& E, const int wid) {
;     ...
;                 const char* a1 = cA + (size_t)(t + 1) * kstep;
;                 const char* a2 = last ? ns.A : cA + (size_t)(t + 2) * kstep; const char* b2 = last ? ns.B : cB + (size_t)(t + 2) * kstep;
;                 const char* a3 = a2 + kstep; const char* b3 = b2 + kstep;
;                 unsigned vA2[2], vB2[2];
; #pragma unroll
;                 for (int i = 0; i < 2; ++i) { vA2[i] = last ? nvA[i] : voffA[i]; vB2[i] = last ? nvB[i] : voffB[i]; }
;                 const size_t hA2 = last ? nhA : hstepA, hB2 = last ? nhB : hstepB;
;                 PG8_LDB(B0, 0, 0); PG8_LDB(B1, 0, 1); PG8_SCHED; PG8_LDA(At, 0, 0); PG8_STAGE(PG8_SA(1, 1), a1 + hstepA, voffA);
;                 PG8_WAIT_V(8); PG8_WAIT_L(0); PG8_BAR; PG8_MMA(0, 0, At, B0); PG8_MMA(0, 1, At, B1); PG8_BAR; PG8_SCHED;
;                 PG8_LDA(At, 0, 1); PG8_STAGE(PG8_SB(0, 0), b2, vB2); PG8_STAGE(PG8_SB(0, 1), b2 + hB2, vB2); PG8_STAGE(PG8_SA(0, 0), a2, vA2);
.LBB0_1096:
	ds_read_b128 v[128:131], v188
	ds_read_b128 v[132:135], v189
	ds_read_b128 v[136:139], v190
	ds_read_b128 v[140:143], v191
	ds_read_b128 v[144:147], v192
	ds_read_b128 v[148:151], v193
	ds_read_b128 v[152:155], v194
	ds_read_b128 v[156:159], v195
	s_add_u32 s24, s22, 0xffd50080
	s_addc_u32 s25, s23, -1
	s_cmpk_eq_i32 s56, 0xa8
	s_cselect_b32 s27, s19, s25
	s_cselect_b32 s26, s18, s24
	s_cselect_b32 s25, s53, s55
	s_cselect_b32 s24, s52, s54
	v_lshl_add_u64 v[222:223], s[22:23], 0, v[168:169]
	s_add_i32 m0, s34, 0xc000
	ds_read_b128 v[160:163], v196
	ds_read_b128 v[164:167], v196 offset:2048
	ds_read_b128 v[180:183], v197
	ds_read_b128 v[202:205], v197 offset:2048
	ds_read_b128 v[206:209], v196 offset:4096
	ds_read_b128 v[210:213], v196 offset:6144
	ds_read_b128 v[214:217], v197 offset:4096
	ds_read_b128 v[218:221], v197 offset:6144
	global_load_lds_dwordx4 v[222:223], off sc1
	v_lshl_add_u64 v[222:223], s[22:23], 0, v[172:173]
	s_add_i32 m0, s34, 0xe000
	s_nop 0
	global_load_lds_dwordx4 v[222:223], off sc1
	s_waitcnt vmcnt(8)
	s_waitcnt lgkmcnt(0)
	s_barrier
	s_setprio 3
	s_waitcnt lgkmcnt(0)
	v_mfma_f32_16x16x32_bf16 v[124:127], v[128:131], v[160:163], v[124:127]
	v_mfma_f32_16x16x32_bf16 v[124:127], v[132:135], v[180:183], v[124:127]
	v_mfma_f32_16x16x32_bf16 v[120:123], v[140:143], v[180:183], v[120:123]
	v_mfma_f32_16x16x32_bf16 v[120:123], v[136:139], v[160:163], v[120:123]
	v_mfma_f32_16x16x32_bf16 v[104:107], v[136:139], v[164:167], v[104:107]
	v_mfma_f32_16x16x32_bf16 v[104:107], v[140:143], v[202:205], v[104:107]
	v_mfma_f32_16x16x32_bf16 v[112:115], v[132:135], v[202:205], v[112:115]
	v_mfma_f32_16x16x32_bf16 v[112:115], v[128:131], v[164:167], v[112:115]
	v_mfma_f32_16x16x32_bf16 v[96:99], v[128:131], v[206:209], v[96:99]
	v_mfma_f32_16x16x32_bf16 v[96:99], v[132:135], v[214:217], v[96:99]
	v_mfma_f32_16x16x32_bf16 v[88:91], v[140:143], v[214:217], v[88:91]
	v_mfma_f32_16x16x32_bf16 v[88:91], v[136:139], v[206:209], v[88:91]
	v_mfma_f32_16x16x32_bf16 v[72:75], v[136:139], v[210:213], v[72:75]
	v_mfma_f32_16x16x32_bf16 v[72:75], v[140:143], v[218:221], v[72:75]
	v_mfma_f32_16x16x32_bf16 v[80:83], v[132:135], v[218:221], v[80:83]
	v_mfma_f32_16x16x32_bf16 v[80:83], v[128:131], v[210:213], v[80:83]
	s_setprio 0
	s_setprio 3
	v_mfma_f32_16x16x32_bf16 v[116:119], v[144:147], v[160:163], v[116:119]
	v_mfma_f32_16x16x32_bf16 v[116:119], v[148:151], v[180:183], v[116:119]
	v_mfma_f32_16x16x32_bf16 v[108:111], v[156:159], v[180:183], v[108:111]
	v_mfma_f32_16x16x32_bf16 v[108:111], v[152:155], v[160:163], v[108:111]
	v_mfma_f32_16x16x32_bf16 v[92:95], v[152:155], v[164:167], v[92:95]
	v_mfma_f32_16x16x32_bf16 v[92:95], v[156:159], v[202:205], v[92:95]
	v_mfma_f32_16x16x32_bf16 v[100:103], v[148:151], v[202:205], v[100:103]
	v_mfma_f32_16x16x32_bf16 v[100:103], v[144:147], v[164:167], v[100:103]
	v_mfma_f32_16x16x32_bf16 v[84:87], v[144:147], v[206:209], v[84:87]
	v_mfma_f32_16x16x32_bf16 v[84:87], v[148:151], v[214:217], v[84:87]
	v_mfma_f32_16x16x32_bf16 v[76:79], v[156:159], v[214:217], v[76:79]
	v_mfma_f32_16x16x32_bf16 v[76:79], v[152:155], v[206:209], v[76:79]
	v_mfma_f32_16x16x32_bf16 v[60:63], v[152:155], v[210:213], v[60:63]
	v_mfma_f32_16x16x32_bf16 v[60:63], v[156:159], v[218:221], v[60:63]
	v_mfma_f32_16x16x32_bf16 v[68:71], v[148:151], v[218:221], v[68:71]
	v_mfma_f32_16x16x32_bf16 v[68:71], v[144:147], v[210:213], v[68:71]
	s_setprio 0
	s_barrier
	s_add_i32 s57, s41, s68
	v_lshl_add_u64 v[222:223], s[24:25], 0, v[170:171]
	s_mov_b32 m0, s57
	ds_read_b128 v[160:163], v196 offset:16384
	ds_read_b128 v[164:167], v196 offset:18432
	ds_read_b128 v[180:183], v197 offset:16384
	ds_read_b128 v[202:205], v197 offset:18432
	ds_read_b128 v[206:209], v196 offset:20480
	ds_read_b128 v[210:213], v196 offset:22528
	ds_read_b128 v[214:217], v197 offset:20480
	ds_read_b128 v[218:221], v197 offset:22528
	global_load_lds_dwordx4 v[222:223], off sc1
	s_add_i32 m0, s57, 0x2000
	s_add_u32 s58, s24, 0x2b0000
	v_lshl_add_u64 v[224:225], s[24:25], 0, v[174:175]
	s_addc_u32 s59, s25, 0
	s_add_i32 s57, s42, s68
	global_load_lds_dwordx4 v[224:225], off sc1
	v_lshl_add_u64 v[226:227], s[58:59], 0, v[170:171]
	s_mov_b32 m0, s57
	v_lshl_add_u64 v[228:229], s[26:27], 0, v[172:173]
	global_load_lds_dwordx4 v[226:227], off sc1
	v_lshl_add_u64 v[226:227], s[58:59], 0, v[174:175]
	s_add_i32 m0, s57, 0x2000
	s_nop 0
	global_load_lds_dwordx4 v[226:227], off sc1
	v_lshl_add_u64 v[226:227], s[26:27], 0, v[168:169]
	s_mov_b32 m0, s34
	s_nop 0
	global_load_lds_dwordx4 v[226:227], off sc1
	s_mov_b32 m0, s35
	s_nop 0
	global_load_lds_dwordx4 v[228:229], off sc1
	s_waitcnt vmcnt(8)
	s_waitcnt lgkmcnt(0)
	s_barrier
; #define PG8_STAGE(bufoff, gbase, voff) do { _Pragma("unroll") for (int _i = 0; _i < 2; ++_i) \
;         __builtin_amdgcn_global_load_lds((const unsigned*)((const char*)(gbase) + (voff)[_i]), (LAS unsigned*)(lds + (bufoff) + ldsw + _i * 8192), 16, 0, 0); } while (0)
; #define PG8_LDA(dst, b, h) do { _Pragma("unroll") for (int m = 0; m < 4; ++m) _Pragma("unroll") for (int k = 0; k < 2; ++k) dst[m][k] = *(const LAS bf16x8*)(lds + PG8_SA(b, h) + aoffk[k] + m * 2048); } while (0)
; #define PG8_LDB(dst, b, h) do { _Pragma("unroll") for (int n = 0; n < 2; ++n) _Pragma("unroll") for (int k = 0; k < 2; ++k) dst[n][k] = *(const LAS bf16x8*)(lds + PG8_SB(b, h) + boffk[k] + n * 2048); } while (0)
; #define PG8_WAIT_V(n) asm volatile("s_waitcnt vmcnt(" #n ")" ::: "memory")
; #define PG8_WAIT_L(n) asm volatile("s_waitcnt lgkmcnt(" #n ")" ::: "memory")
; #define PG8_BAR __builtin_amdgcn_s_barrier()
; #define PG8_SCHED __builtin_amdgcn_sched_barrier(0)
; template <class Epi, class Sched, class GemmT>
; __device__ __forceinline__ void gemm_phase(LAS unsigned char* lds, const GemmT& g, const Sched& S, const Epi& E, const int wid) {
;     ...
;                 PG8_WAIT_V(8); PG8_WAIT_L(0); PG8_BAR; PG8_MMA(0, 0, At, B0); PG8_MMA(0, 1, At, B1); PG8_BAR; PG8_SCHED;
;                 PG8_LDA(At, 0, 1); PG8_STAGE(PG8_SB(0, 0), b2, vB2); PG8_STAGE(PG8_SB(0, 1), b2 + hB2, vB2); PG8_STAGE(PG8_SA(0, 0), a2, vA2);
;                 PG8_WAIT_V(8); PG8_WAIT_L(0); PG8_BAR; PG8_MMA(1, 0, At, B0); PG8_MMA(1, 1, At, B1); PG8_BAR; PG8_SCHED;
;                 PG8_LDB(B0, 1, 0); PG8_LDB(B1, 1, 1); PG8_SCHED; PG8_LDA(At, 1, 0); PG8_STAGE(PG8_SA(0, 1), a2 + hA2, vA2);
;                 PG8_WAIT_V(8); PG8_WAIT_L(0); PG8_BAR; PG8_MMA(0, 0, At, B0); PG8_MMA(0, 1, At, B1); PG8_BAR; PG8_SCHED;
	s_setprio 3
	s_waitcnt lgkmcnt(0)
	v_mfma_f32_16x16x32_bf16 v[52:55], v[128:131], v[160:163], v[52:55]
	v_mfma_f32_16x16x32_bf16 v[52:55], v[132:135], v[180:183], v[52:55]
	v_mfma_f32_16x16x32_bf16 v[48:51], v[140:143], v[180:183], v[48:51]
	v_mfma_f32_16x16x32_bf16 v[48:51], v[136:139], v[160:163], v[48:51]
	v_mfma_f32_16x16x32_bf16 v[32:35], v[136:139], v[164:167], v[32:35]
	v_mfma_f32_16x16x32_bf16 v[32:35], v[140:143], v[202:205], v[32:35]
	v_mfma_f32_16x16x32_bf16 v[36:39], v[132:135], v[202:205], v[36:39]
	v_mfma_f32_16x16x32_bf16 v[36:39], v[128:131], v[164:167], v[36:39]
	v_mfma_f32_16x16x32_bf16 v[20:23], v[128:131], v[206:209], v[20:23]
	v_mfma_f32_16x16x32_bf16 v[20:23], v[132:135], v[214:217], v[20:23]
	v_mfma_f32_16x16x32_bf16 v[8:11], v[140:143], v[214:217], v[8:11]
	v_mfma_f32_16x16x32_bf16 v[8:11], v[136:139], v[206:209], v[8:11]
	v_mfma_f32_16x16x32_bf16 v[0:3], v[136:139], v[210:213], v[0:3]
	v_mfma_f32_16x16x32_bf16 v[0:3], v[140:143], v[218:221], v[0:3]
	v_mfma_f32_16x16x32_bf16 v[4:7], v[132:135], v[218:221], v[4:7]
	v_mfma_f32_16x16x32_bf16 v[4:7], v[128:131], v[210:213], v[4:7]
	s_setprio 0
	s_setprio 3
	v_mfma_f32_16x16x32_bf16 v[64:67], v[144:147], v[160:163], v[64:67]
	v_mfma_f32_16x16x32_bf16 v[64:67], v[148:151], v[180:183], v[64:67]
	v_mfma_f32_16x16x32_bf16 v[56:59], v[156:159], v[180:183], v[56:59]
	v_mfma_f32_16x16x32_bf16 v[56:59], v[152:155], v[160:163], v[56:59]
	v_mfma_f32_16x16x32_bf16 v[40:43], v[152:155], v[164:167], v[40:43]
	v_mfma_f32_16x16x32_bf16 v[40:43], v[156:159], v[202:205], v[40:43]
	v_mfma_f32_16x16x32_bf16 v[44:47], v[148:151], v[202:205], v[44:47]
	v_mfma_f32_16x16x32_bf16 v[44:47], v[144:147], v[164:167], v[44:47]
	v_mfma_f32_16x16x32_bf16 v[28:31], v[144:147], v[206:209], v[28:31]
	v_mfma_f32_16x16x32_bf16 v[28:31], v[148:151], v[214:217], v[28:31]
	v_mfma_f32_16x16x32_bf16 v[24:27], v[156:159], v[214:217], v[24:27]
	v_mfma_f32_16x16x32_bf16 v[24:27], v[152:155], v[206:209], v[24:27]
	v_mfma_f32_16x16x32_bf16 v[12:15], v[152:155], v[210:213], v[12:15]
	v_mfma_f32_16x16x32_bf16 v[12:15], v[156:159], v[218:221], v[12:15]
	v_mfma_f32_16x16x32_bf16 v[16:19], v[148:151], v[218:221], v[16:19]
	v_mfma_f32_16x16x32_bf16 v[16:19], v[144:147], v[210:213], v[16:19]
	s_setprio 0
	s_barrier
	s_add_i32 s57, 0, 0x18000
	s_add_i32 s58, 0, 0x1c000
	v_add_u32_e32 v128, s57, v185
	v_add_u32_e32 v132, s57, v186
	v_add_u32_e32 v144, s58, v185
	v_add_u32_e32 v148, s58, v186
	ds_read_b128 v[128:131], v128
	ds_read_b128 v[132:135], v132
	ds_read_b128 v[136:139], v198
	ds_read_b128 v[140:143], v199
	ds_read_b128 v[144:147], v144
	ds_read_b128 v[148:151], v148
	ds_read_b128 v[152:155], v200
	ds_read_b128 v[156:159], v201
	s_add_u32 s26, s26, 0x2b0000
	s_addc_u32 s27, s27, 0
	s_mov_b32 m0, s36
	v_lshl_add_u64 v[230:231], s[26:27], 0, v[168:169]
	ds_read_b128 v[160:163], v196 offset:32768
	ds_read_b128 v[164:167], v196 offset:34816
	ds_read_b128 v[180:183], v197 offset:32768
	ds_read_b128 v[202:205], v197 offset:34816
	ds_read_b128 v[206:209], v196 offset:36864
	ds_read_b128 v[210:213], v196 offset:38912
	ds_read_b128 v[214:217], v197 offset:36864
	ds_read_b128 v[218:221], v197 offset:38912
	global_load_lds_dwordx4 v[230:231], off sc1
	v_lshl_add_u64 v[230:231], s[26:27], 0, v[172:173]
	s_mov_b32 m0, s37
	s_nop 0
	global_load_lds_dwordx4 v[230:231], off sc1
	s_waitcnt vmcnt(8)
	s_waitcnt lgkmcnt(0)
	s_barrier
	s_setprio 3
	s_waitcnt lgkmcnt(0)
	v_mfma_f32_16x16x32_bf16 v[124:127], v[128:131], v[160:163], v[124:127]
	v_mfma_f32_16x16x32_bf16 v[124:127], v[132:135], v[180:183], v[124:127]
	v_mfma_f32_16x16x32_bf16 v[120:123], v[140:143], v[180:183], v[120:123]
	v_mfma_f32_16x16x32_bf16 v[120:123], v[136:139], v[160:163], v[120:123]
	v_mfma_f32_16x16x32_bf16 v[104:107], v[136:139], v[164:167], v[104:107]
	v_mfma_f32_16x16x32_bf16 v[104:107], v[140:143], v[202:205], v[104:107]
	v_mfma_f32_16x16x32_bf16 v[112:115], v[132:135], v[202:205], v[112:115]
	v_mfma_f32_16x16x32_bf16 v[112:115], v[128:131], v[164:167], v[112:115]
	v_mfma_f32_16x16x32_bf16 v[96:99], v[128:131], v[206:209], v[96:99]
	v_mfma_f32_16x16x32_bf16 v[96:99], v[132:135], v[214:217], v[96:99]
	v_mfma_f32_16x16x32_bf16 v[88:91], v[140:143], v[214:217], v[88:91]
	v_mfma_f32_16x16x32_bf16 v[88:91], v[136:139], v[206:209], v[88:91]
	v_mfma_f32_16x16x32_bf16 v[72:75], v[136:139], v[210:213], v[72:75]
	v_mfma_f32_16x16x32_bf16 v[72:75], v[140:143], v[218:221], v[72:75]
	v_mfma_f32_16x16x32_bf16 v[80:83], v[132:135], v[218:221], v[80:83]
	v_mfma_f32_16x16x32_bf16 v[80:83], v[128:131], v[210:213], v[80:83]
	s_setprio 0
	s_setprio 3
	v_mfma_f32_16x16x32_bf16 v[116:119], v[144:147], v[160:163], v[116:119]
	v_mfma_f32_16x16x32_bf16 v[116:119], v[148:151], v[180:183], v[116:119]
	v_mfma_f32_16x16x32_bf16 v[108:111], v[156:159], v[180:183], v[108:111]
	v_mfma_f32_16x16x32_bf16 v[108:111], v[152:155], v[160:163], v[108:111]
	v_mfma_f32_16x16x32_bf16 v[92:95], v[152:155], v[164:167], v[92:95]
	v_mfma_f32_16x16x32_bf16 v[92:95], v[156:159], v[202:205], v[92:95]
	v_mfma_f32_16x16x32_bf16 v[100:103], v[148:151], v[202:205], v[100:103]
	v_mfma_f32_16x16x32_bf16 v[100:103], v[144:147], v[164:167], v[100:103]
	v_mfma_f32_16x16x32_bf16 v[84:87], v[144:147], v[206:209], v[84:87]
	v_mfma_f32_16x16x32_bf16 v[84:87], v[148:151], v[214:217], v[84:87]
	v_mfma_f32_16x16x32_bf16 v[76:79], v[156:159], v[214:217], v[76:79]
	v_mfma_f32_16x16x32_bf16 v[76:79], v[152:155], v[206:209], v[76:79]
	v_mfma_f32_16x16x32_bf16 v[60:63], v[152:155], v[210:213], v[60:63]
	v_mfma_f32_16x16x32_bf16 v[60:63], v[156:159], v[218:221], v[60:63]
	v_mfma_f32_16x16x32_bf16 v[68:71], v[148:151], v[218:221], v[68:71]
	v_mfma_f32_16x16x32_bf16 v[68:71], v[144:147], v[210:213], v[68:71]
	s_setprio 0
	s_barrier
; #define PG8_STAGE(bufoff, gbase, voff) do { _Pragma("unroll") for (int _i = 0; _i < 2; ++_i) \
;         __builtin_amdgcn_global_load_lds((const unsigned*)((const char*)(gbase) + (voff)[_i]), (LAS unsigned*)(lds + (bufoff) + ldsw + _i * 8192), 16, 0, 0); } while (0)
; #define PG8_LDA(dst, b, h) do { _Pragma("unroll") for (int m = 0; m < 4; ++m) _Pragma("unroll") for (int k = 0; k < 2; ++k) dst[m][k] = *(const LAS bf16x8*)(lds + PG8_SA(b, h) + aoffk[k] + m * 2048); } while (0)
; #define PG8_WAIT_V(n) asm volatile("s_waitcnt vmcnt(" #n ")" ::: "memory")
; #define PG8_WAIT_L(n) asm volatile("s_waitcnt lgkmcnt(" #n ")" ::: "memory")
; #define PG8_BAR __builtin_amdgcn_s_barrier()
; #define PG8_SCHED __builtin_amdgcn_sched_barrier(0)
; template <class Epi, class Sched, class GemmT>
; __device__ __forceinline__ void gemm_phase(LAS unsigned char* lds, const GemmT& g, const Sched& S, const Epi& E, const int wid) {
;     ...
;                 PG8_LDA(At, 1, 1); PG8_STAGE(PG8_SB(1, 0), b3, vB2); PG8_STAGE(PG8_SB(1, 1), b3 + hB2, vB2); PG8_STAGE(PG8_SA(1, 0), a3, vA2);
;                 PG8_WAIT_V(8); PG8_WAIT_L(0); PG8_BAR; PG8_MMA(1, 0, At, B0); PG8_MMA(1, 1, At, B1); PG8_BAR; PG8_SCHED;
;             }
;             if constexpr (NSEG > 1) { if (sgi + 1 < NSEG) E.mid(acc, cur, sgi, wr, wc, fr, fq); }
;             cs = ns; cA = ns.A; cB = ns.B; hstepA = nhA; hstepB = nhB;
; #pragma unroll
;             for (int i = 0; i < 2; ++i) { voffA[i] = nvA[i]; voffB[i] = nvB[i]; }
;         }
;         if (wr == 0) PG8_BAR;
	s_add_i32 s26, s57, s68
	v_lshl_add_u64 v[222:223], v[222:223], 0, s[6:7]
	s_mov_b32 m0, s26
	ds_read_b128 v[160:163], v196 offset:49152
	ds_read_b128 v[164:167], v196 offset:51200
	ds_read_b128 v[180:183], v197 offset:49152
	ds_read_b128 v[202:205], v197 offset:51200
	ds_read_b128 v[206:209], v196 offset:53248
	ds_read_b128 v[210:213], v196 offset:55296
	ds_read_b128 v[214:217], v197 offset:53248
	ds_read_b128 v[218:221], v197 offset:55296
	global_load_lds_dwordx4 v[222:223], off sc1
	s_add_i32 m0, s26, 0x2000
	s_add_u32 s24, s24, 0x2b0080
	v_lshl_add_u64 v[222:223], v[224:225], 0, s[6:7]
	s_addc_u32 s25, s25, 0
	s_add_i32 s26, s58, s68
	global_load_lds_dwordx4 v[222:223], off sc1
	v_lshl_add_u64 v[222:223], s[24:25], 0, v[170:171]
	s_mov_b32 m0, s26
	s_nop 0
	global_load_lds_dwordx4 v[222:223], off sc1
	v_lshl_add_u64 v[222:223], s[24:25], 0, v[174:175]
	s_add_i32 m0, s26, 0x2000
	s_nop 0
	global_load_lds_dwordx4 v[222:223], off sc1
	v_lshl_add_u64 v[222:223], v[226:227], 0, s[6:7]
	s_mov_b32 m0, s39
	s_nop 0
	global_load_lds_dwordx4 v[222:223], off sc1
	v_lshl_add_u64 v[222:223], v[228:229], 0, s[6:7]
	s_mov_b32 m0, s40
	s_nop 0
	global_load_lds_dwordx4 v[222:223], off sc1
	s_waitcnt vmcnt(8)
	s_waitcnt lgkmcnt(0)
	s_barrier
	s_setprio 3
	s_waitcnt lgkmcnt(0)
	v_mfma_f32_16x16x32_bf16 v[52:55], v[128:131], v[160:163], v[52:55]
	v_mfma_f32_16x16x32_bf16 v[52:55], v[132:135], v[180:183], v[52:55]
	v_mfma_f32_16x16x32_bf16 v[48:51], v[140:143], v[180:183], v[48:51]
	v_mfma_f32_16x16x32_bf16 v[48:51], v[136:139], v[160:163], v[48:51]
	v_mfma_f32_16x16x32_bf16 v[32:35], v[136:139], v[164:167], v[32:35]
	v_mfma_f32_16x16x32_bf16 v[32:35], v[140:143], v[202:205], v[32:35]
	v_mfma_f32_16x16x32_bf16 v[36:39], v[132:135], v[202:205], v[36:39]
	v_mfma_f32_16x16x32_bf16 v[36:39], v[128:131], v[164:167], v[36:39]
	v_mfma_f32_16x16x32_bf16 v[20:23], v[128:131], v[206:209], v[20:23]
	v_mfma_f32_16x16x32_bf16 v[20:23], v[132:135], v[214:217], v[20:23]
	v_mfma_f32_16x16x32_bf16 v[8:11], v[140:143], v[214:217], v[8:11]
	v_mfma_f32_16x16x32_bf16 v[8:11], v[136:139], v[206:209], v[8:11]
	v_mfma_f32_16x16x32_bf16 v[0:3], v[136:139], v[210:213], v[0:3]
	v_mfma_f32_16x16x32_bf16 v[0:3], v[140:143], v[218:221], v[0:3]
	v_mfma_f32_16x16x32_bf16 v[4:7], v[132:135], v[218:221], v[4:7]
	v_mfma_f32_16x16x32_bf16 v[4:7], v[128:131], v[210:213], v[4:7]
	s_setprio 0
	s_setprio 3
	v_mfma_f32_16x16x32_bf16 v[64:67], v[144:147], v[160:163], v[64:67]
	v_mfma_f32_16x16x32_bf16 v[64:67], v[148:151], v[180:183], v[64:67]
	v_mfma_f32_16x16x32_bf16 v[56:59], v[156:159], v[180:183], v[56:59]
	v_mfma_f32_16x16x32_bf16 v[56:59], v[152:155], v[160:163], v[56:59]
	v_mfma_f32_16x16x32_bf16 v[40:43], v[152:155], v[164:167], v[40:43]
	v_mfma_f32_16x16x32_bf16 v[40:43], v[156:159], v[202:205], v[40:43]
	v_mfma_f32_16x16x32_bf16 v[44:47], v[148:151], v[202:205], v[44:47]
	v_mfma_f32_16x16x32_bf16 v[44:47], v[144:147], v[164:167], v[44:47]
	v_mfma_f32_16x16x32_bf16 v[28:31], v[144:147], v[206:209], v[28:31]
	v_mfma_f32_16x16x32_bf16 v[28:31], v[148:151], v[214:217], v[28:31]
	v_mfma_f32_16x16x32_bf16 v[24:27], v[156:159], v[214:217], v[24:27]
	v_mfma_f32_16x16x32_bf16 v[24:27], v[152:155], v[206:209], v[24:27]
	v_mfma_f32_16x16x32_bf16 v[12:15], v[152:155], v[210:213], v[12:15]
	v_mfma_f32_16x16x32_bf16 v[12:15], v[156:159], v[218:221], v[12:15]
	v_mfma_f32_16x16x32_bf16 v[16:19], v[148:151], v[218:221], v[16:19]
	v_mfma_f32_16x16x32_bf16 v[16:19], v[144:147], v[210:213], v[16:19]
	s_setprio 0
	s_barrier
	s_add_i32 s56, s56, 2
	s_add_u32 s22, s22, 0x100
	s_addc_u32 s23, s23, 0
	s_add_u32 s54, s54, 0x100
	s_addc_u32 s55, s55, 0
	s_cmpk_gt_u32 s56, 0xa9
	s_cbranch_scc0 .LBB0_1096
	s_and_b64 vcc, exec, s[8:9]
	s_cbranch_vccz .LBB0_1099
	s_barrier
